# v77 + GEMM read sections: LDS-DMA loads (with M0/address setup) issued before the section's ds_reads
# baseline (speedup 1.0000x reference)
; #define PG8_STAGE(bufoff, gbase, voff) do { _Pragma("unroll") for (int _i = 0; _i < 2; ++_i) \
;         __builtin_amdgcn_global_load_lds((const unsigned*)((const char*)(gbase) + (voff)[_i]), (LAS unsigned*)(lds + (bufoff) + ldsw + _i * 8192), 16, 0, 0); } while (0)
; #define PG8_LDA(dst, b, h) do { _Pragma("unroll") for (int m = 0; m < 4; ++m) _Pragma("unroll") for (int k = 0; k < 2; ++k) dst[m][k] = *(const LAS bf16x8*)(lds + PG8_SA(b, h) + aoff + m * 2048 + k * 1024); } while (0)
; #define PG8_MMA(ai, bj, At, Bt) do { __builtin_amdgcn_s_setprio(1); _Pragma("unroll") for (int m = 0; m < 4; ++m) _Pragma("unroll") for (int n = 0; n < 2; ++n) _Pragma("unroll") for (int k = 0; k < 2; ++k) \
;         acc[ai][bj][m][n] = __builtin_amdgcn_mfma_f32_16x16x32_bf16(Bt[n][k], At[m][k], acc[ai][bj][m][n], 0, 0, 0); __builtin_amdgcn_s_setprio(0); } while (0)
; #define PG8_WAIT_V(n) asm volatile("s_waitcnt vmcnt(" #n ")" ::: "memory")
; #define PG8_WAIT_L(n) asm volatile("s_waitcnt lgkmcnt(" #n ")" ::: "memory")
; #define PG8_BAR __builtin_amdgcn_s_barrier()
; #define PG8_SCHED __builtin_amdgcn_sched_barrier(0)
; template <class Epi, bool ALIGN_EPI = PG8_ALIGN, bool SP2 = PG8_SP2>
; __device__ __forceinline__ void gemm_phase(LAS uchar* lds, const Gemm g, const StaticOrder& S, const Epi& E) {
;     ...
;             PG8_WAIT_V(8); PG8_WAIT_L(0); PG8_BAR; PG8_MMA(0, 0, At, B0); PG8_MMA(0, 1, At, B1); PG8_BAR; PG8_SCHED;
;             PG8_LDA(At, 0, 1); PG8_STAGE(PG8_SB(0, 0), b2, voffB); PG8_STAGE(PG8_SB(0, 1), b2 + hstepB, voffB); PG8_STAGE(PG8_SA(0, 0), a2, voffA);
;             PG8_WAIT_V(8); PG8_WAIT_L(0); PG8_BAR; PG8_MMA(1, 0, At, B0); PG8_MMA(1, 1, At, B1); PG8_BAR; PG8_SCHED;
.Lrw_done_345_0_pl:
	s_waitcnt lgkmcnt(0)
	s_setprio 1
	s_barrier
	v_mfma_f32_16x16x32_bf16 v[126:129], v[164:167], v[204:207], 0
	v_mfma_f32_16x16x32_bf16 v[122:125], v[176:179], v[204:207], 0
	v_mfma_f32_16x16x32_bf16 v[118:121], v[164:167], v[212:215], 0
	v_mfma_f32_16x16x32_bf16 v[110:113], v[176:179], v[212:215], 0
	v_mfma_f32_16x16x32_bf16 v[102:105], v[164:167], v[220:223], 0
	v_mfma_f32_16x16x32_bf16 v[94:97], v[176:179], v[220:223], 0
	v_mfma_f32_16x16x32_bf16 v[86:89], v[164:167], v[228:231], 0
	v_mfma_f32_16x16x32_bf16 v[78:81], v[176:179], v[228:231], 0
	v_mfma_f32_16x16x32_bf16 v[126:129], v[172:175], v[208:211], v[126:129]
	v_mfma_f32_16x16x32_bf16 v[122:125], v[184:187], v[208:211], v[122:125]
	v_mfma_f32_16x16x32_bf16 v[118:121], v[172:175], v[216:219], v[118:121]
	v_mfma_f32_16x16x32_bf16 v[110:113], v[184:187], v[216:219], v[110:113]
	v_mfma_f32_16x16x32_bf16 v[102:105], v[172:175], v[224:227], v[102:105]
	v_mfma_f32_16x16x32_bf16 v[94:97], v[184:187], v[224:227], v[94:97]
	v_mfma_f32_16x16x32_bf16 v[86:89], v[172:175], v[232:235], v[86:89]
	v_mfma_f32_16x16x32_bf16 v[78:81], v[184:187], v[232:235], v[78:81]
	v_mfma_f32_16x16x32_bf16 v[114:117], v[188:191], v[204:207], 0
	v_mfma_f32_16x16x32_bf16 v[106:109], v[196:199], v[204:207], 0
	v_mfma_f32_16x16x32_bf16 v[98:101], v[188:191], v[212:215], 0
	v_mfma_f32_16x16x32_bf16 v[90:93], v[196:199], v[212:215], 0
	v_mfma_f32_16x16x32_bf16 v[82:85], v[188:191], v[220:223], 0
	v_mfma_f32_16x16x32_bf16 v[74:77], v[196:199], v[220:223], 0
	v_mfma_f32_16x16x32_bf16 v[70:73], v[188:191], v[228:231], 0
	v_mfma_f32_16x16x32_bf16 v[66:69], v[196:199], v[228:231], 0
	v_mfma_f32_16x16x32_bf16 v[114:117], v[192:195], v[208:211], v[114:117]
	v_mfma_f32_16x16x32_bf16 v[106:109], v[200:203], v[208:211], v[106:109]
	v_mfma_f32_16x16x32_bf16 v[98:101], v[192:195], v[216:219], v[98:101]
	v_mfma_f32_16x16x32_bf16 v[90:93], v[200:203], v[216:219], v[90:93]
	v_mfma_f32_16x16x32_bf16 v[82:85], v[192:195], v[224:227], v[82:85]
	v_mfma_f32_16x16x32_bf16 v[74:77], v[200:203], v[224:227], v[74:77]
	v_mfma_f32_16x16x32_bf16 v[70:73], v[192:195], v[232:235], v[70:73]
	v_mfma_f32_16x16x32_bf16 v[66:69], v[200:203], v[232:235], v[66:69]
	s_barrier
	s_setprio 0
	s_add_i32 s16, s41, s23
	v_lshl_add_u64 v[168:169], s[4:5], 0, v[134:135]
	s_mov_b32 m0, s16
	ds_read_b128 v[204:207], v171 offset:16384
	ds_read_b128 v[208:211], v171 offset:17408
	ds_read_b128 v[212:215], v171 offset:18432
	ds_read_b128 v[216:219], v171 offset:19456
	ds_read_b128 v[220:223], v171 offset:20480
	ds_read_b128 v[224:227], v171 offset:21504
	ds_read_b128 v[228:231], v171 offset:22528
	ds_read_b128 v[232:235], v171 offset:23552
	global_load_lds_dwordx4 v[168:169], off
	s_add_i32 m0, s16, 0x2000
	s_add_u32 s16, s4, 0x44000
	v_lshl_add_u64 v[180:181], s[4:5], 0, v[130:131]
	s_addc_u32 s17, s5, 0
	s_add_i32 s41, s42, s23
	global_load_lds_dwordx4 v[180:181], off
	s_mov_b32 m0, s41
	v_lshl_add_u64 v[236:237], s[16:17], 0, v[134:135]
	global_load_lds_dwordx4 v[236:237], off
	s_add_i32 m0, s41, 0x2000
	v_lshl_add_u64 v[236:237], s[16:17], 0, v[130:131]
	global_load_lds_dwordx4 v[236:237], off
	s_mov_b32 m0, s25
	v_lshl_add_u64 v[236:237], s[20:21], 0, v[156:157]
	global_load_lds_dwordx4 v[236:237], off
	s_mov_b32 m0, s26
	v_lshl_add_u64 v[238:239], s[20:21], 0, v[132:133]
	global_load_lds_dwordx4 v[238:239], off
	s_cmp_eq_u32 s97, 1
	s_cbranch_scc0 .Lrw_std_345_1_pl
	s_waitcnt vmcnt(24)
	s_branch .Lrw_done_345_1_pl

; #define PG8_STAGE(bufoff, gbase, voff) do { _Pragma("unroll") for (int _i = 0; _i < 2; ++_i) \
;         __builtin_amdgcn_global_load_lds((const unsigned*)((const char*)(gbase) + (voff)[_i]), (LAS unsigned*)(lds + (bufoff) + ldsw + _i * 8192), 16, 0, 0); } while (0)
; #define PG8_LDA(dst, b, h) do { _Pragma("unroll") for (int m = 0; m < 4; ++m) _Pragma("unroll") for (int k = 0; k < 2; ++k) dst[m][k] = *(const LAS bf16x8*)(lds + PG8_SA(b, h) + aoff + m * 2048 + k * 1024); } while (0)
; #define PG8_LDB(dst, b, h) do { _Pragma("unroll") for (int n = 0; n < 2; ++n) _Pragma("unroll") for (int k = 0; k < 2; ++k) dst[n][k] = *(const LAS bf16x8*)(lds + PG8_SB(b, h) + boff + n * 2048 + k * 1024); } while (0)
; #define PG8_MMA(ai, bj, At, Bt) do { __builtin_amdgcn_s_setprio(1); _Pragma("unroll") for (int m = 0; m < 4; ++m) _Pragma("unroll") for (int n = 0; n < 2; ++n) _Pragma("unroll") for (int k = 0; k < 2; ++k) \
;         acc[ai][bj][m][n] = __builtin_amdgcn_mfma_f32_16x16x32_bf16(Bt[n][k], At[m][k], acc[ai][bj][m][n], 0, 0, 0); __builtin_amdgcn_s_setprio(0); } while (0)
; #define PG8_WAIT_V(n) asm volatile("s_waitcnt vmcnt(" #n ")" ::: "memory")
; #define PG8_WAIT_L(n) asm volatile("s_waitcnt lgkmcnt(" #n ")" ::: "memory")
; #define PG8_BAR __builtin_amdgcn_s_barrier()
; #define PG8_SCHED __builtin_amdgcn_sched_barrier(0)
; template <class Epi, bool ALIGN_EPI = PG8_ALIGN, bool SP2 = PG8_SP2>
; __device__ __forceinline__ void gemm_phase(LAS uchar* lds, const Gemm g, const StaticOrder& S, const Epi& E) {
;     ...
;             PG8_WAIT_V(8); PG8_WAIT_L(0); PG8_BAR; PG8_MMA(1, 0, At, B0); PG8_MMA(1, 1, At, B1); PG8_BAR; PG8_SCHED;
;             PG8_LDB(B0, 1, 0); PG8_LDB(B1, 1, 1); PG8_SCHED; PG8_LDA(At, 1, 0); PG8_STAGE(PG8_SA(0, 1), a2 + hstepA, voffA);
;             PG8_WAIT_V(8); PG8_WAIT_L(0); PG8_BAR; PG8_MMA(0, 0, At, B0); PG8_MMA(0, 1, At, B1); PG8_BAR; PG8_SCHED;
.Lrw_done_345_1_pl:
	s_waitcnt lgkmcnt(0)
	s_setprio 1
	s_barrier
	v_mfma_f32_16x16x32_bf16 v[62:65], v[164:167], v[204:207], 0
	v_mfma_f32_16x16x32_bf16 v[58:61], v[176:179], v[204:207], 0
	v_mfma_f32_16x16x32_bf16 v[54:57], v[164:167], v[212:215], 0
	v_mfma_f32_16x16x32_bf16 v[46:49], v[176:179], v[212:215], 0
	v_mfma_f32_16x16x32_bf16 v[38:41], v[164:167], v[220:223], 0
	v_mfma_f32_16x16x32_bf16 v[30:33], v[176:179], v[220:223], 0
	v_mfma_f32_16x16x32_bf16 v[22:25], v[164:167], v[228:231], 0
	v_mfma_f32_16x16x32_bf16 v[14:17], v[176:179], v[228:231], 0
	v_mfma_f32_16x16x32_bf16 v[62:65], v[172:175], v[208:211], v[62:65]
	v_mfma_f32_16x16x32_bf16 v[58:61], v[184:187], v[208:211], v[58:61]
	v_mfma_f32_16x16x32_bf16 v[54:57], v[172:175], v[216:219], v[54:57]
	v_mfma_f32_16x16x32_bf16 v[46:49], v[184:187], v[216:219], v[46:49]
	v_mfma_f32_16x16x32_bf16 v[38:41], v[172:175], v[224:227], v[38:41]
	v_mfma_f32_16x16x32_bf16 v[30:33], v[184:187], v[224:227], v[30:33]
	v_mfma_f32_16x16x32_bf16 v[22:25], v[172:175], v[232:235], v[22:25]
	v_mfma_f32_16x16x32_bf16 v[14:17], v[184:187], v[232:235], v[14:17]
	v_mfma_f32_16x16x32_bf16 v[50:53], v[188:191], v[204:207], 0
	v_mfma_f32_16x16x32_bf16 v[42:45], v[196:199], v[204:207], 0
	v_mfma_f32_16x16x32_bf16 v[34:37], v[188:191], v[212:215], 0
	v_mfma_f32_16x16x32_bf16 v[26:29], v[196:199], v[212:215], 0
	v_mfma_f32_16x16x32_bf16 v[18:21], v[188:191], v[220:223], 0
	v_mfma_f32_16x16x32_bf16 v[10:13], v[196:199], v[220:223], 0
	v_mfma_f32_16x16x32_bf16 v[6:9], v[188:191], v[228:231], 0
	v_mfma_f32_16x16x32_bf16 v[2:5], v[196:199], v[228:231], 0
	v_mfma_f32_16x16x32_bf16 v[50:53], v[192:195], v[208:211], v[50:53]
	v_mfma_f32_16x16x32_bf16 v[42:45], v[200:203], v[208:211], v[42:45]
	v_mfma_f32_16x16x32_bf16 v[34:37], v[192:195], v[216:219], v[34:37]
	v_mfma_f32_16x16x32_bf16 v[26:29], v[200:203], v[216:219], v[26:29]
	v_mfma_f32_16x16x32_bf16 v[18:21], v[192:195], v[224:227], v[18:21]
	v_mfma_f32_16x16x32_bf16 v[10:13], v[200:203], v[224:227], v[10:13]
	v_mfma_f32_16x16x32_bf16 v[6:9], v[192:195], v[232:235], v[6:9]
	v_mfma_f32_16x16x32_bf16 v[2:5], v[200:203], v[232:235], v[2:5]
	s_barrier
	s_setprio 0
	s_add_i32 s41, 0, 0x18000
	s_add_i32 s42, 0, 0x1c000
	v_add_u32_e32 v184, s41, v139
	v_add_u32_e32 v200, s42, v139
	s_add_u32 s16, s20, 0x44000
	s_addc_u32 s17, s21, 0
	s_mov_b32 m0, s27
	v_lshl_add_u64 v[240:241], s[16:17], 0, v[156:157]
	global_load_lds_dwordx4 v[240:241], off
	s_mov_b32 m0, s28
	v_lshl_add_u64 v[240:241], s[16:17], 0, v[132:133]
	global_load_lds_dwordx4 v[240:241], off
	ds_read_b128 v[164:167], v184
	ds_read_b128 v[172:175], v184 offset:1024
	ds_read_b128 v[176:179], v184 offset:2048
	ds_read_b128 v[184:187], v184 offset:3072
	ds_read_b128 v[188:191], v200
	ds_read_b128 v[192:195], v200 offset:1024
	ds_read_b128 v[196:199], v200 offset:2048
	ds_read_b128 v[200:203], v200 offset:3072
	ds_read_b128 v[204:207], v171 offset:32768
	ds_read_b128 v[208:211], v171 offset:33792
	ds_read_b128 v[212:215], v171 offset:34816
	ds_read_b128 v[216:219], v171 offset:35840
	ds_read_b128 v[220:223], v171 offset:36864
	ds_read_b128 v[224:227], v171 offset:37888
	ds_read_b128 v[228:231], v171 offset:38912
	ds_read_b128 v[232:235], v171 offset:39936
	s_setprio 1
	s_waitcnt vmcnt(8) lgkmcnt(0)
	s_barrier
	v_mfma_f32_16x16x32_bf16 v[126:129], v[164:167], v[204:207], v[126:129]
	v_mfma_f32_16x16x32_bf16 v[122:125], v[176:179], v[204:207], v[122:125]
	v_mfma_f32_16x16x32_bf16 v[118:121], v[164:167], v[212:215], v[118:121]
	v_mfma_f32_16x16x32_bf16 v[110:113], v[176:179], v[212:215], v[110:113]
	v_mfma_f32_16x16x32_bf16 v[102:105], v[164:167], v[220:223], v[102:105]
	v_mfma_f32_16x16x32_bf16 v[94:97], v[176:179], v[220:223], v[94:97]
	v_mfma_f32_16x16x32_bf16 v[86:89], v[164:167], v[228:231], v[86:89]
	v_mfma_f32_16x16x32_bf16 v[78:81], v[176:179], v[228:231], v[78:81]
	v_mfma_f32_16x16x32_bf16 v[126:129], v[172:175], v[208:211], v[126:129]
	v_mfma_f32_16x16x32_bf16 v[122:125], v[184:187], v[208:211], v[122:125]
	v_mfma_f32_16x16x32_bf16 v[118:121], v[172:175], v[216:219], v[118:121]
	v_mfma_f32_16x16x32_bf16 v[110:113], v[184:187], v[216:219], v[110:113]
	v_mfma_f32_16x16x32_bf16 v[102:105], v[172:175], v[224:227], v[102:105]
	v_mfma_f32_16x16x32_bf16 v[94:97], v[184:187], v[224:227], v[94:97]
	v_mfma_f32_16x16x32_bf16 v[86:89], v[172:175], v[232:235], v[86:89]
	v_mfma_f32_16x16x32_bf16 v[78:81], v[184:187], v[232:235], v[78:81]
	v_mfma_f32_16x16x32_bf16 v[114:117], v[188:191], v[204:207], v[114:117]
	v_mfma_f32_16x16x32_bf16 v[106:109], v[196:199], v[204:207], v[106:109]
	v_mfma_f32_16x16x32_bf16 v[98:101], v[188:191], v[212:215], v[98:101]
	v_mfma_f32_16x16x32_bf16 v[90:93], v[196:199], v[212:215], v[90:93]
	v_mfma_f32_16x16x32_bf16 v[82:85], v[188:191], v[220:223], v[82:85]
	v_mfma_f32_16x16x32_bf16 v[74:77], v[196:199], v[220:223], v[74:77]
	v_mfma_f32_16x16x32_bf16 v[70:73], v[188:191], v[228:231], v[70:73]
	v_mfma_f32_16x16x32_bf16 v[66:69], v[196:199], v[228:231], v[66:69]
	v_mfma_f32_16x16x32_bf16 v[114:117], v[192:195], v[208:211], v[114:117]
	v_mfma_f32_16x16x32_bf16 v[106:109], v[200:203], v[208:211], v[106:109]
	v_mfma_f32_16x16x32_bf16 v[98:101], v[192:195], v[216:219], v[98:101]
	v_mfma_f32_16x16x32_bf16 v[90:93], v[200:203], v[216:219], v[90:93]
	v_mfma_f32_16x16x32_bf16 v[82:85], v[192:195], v[224:227], v[82:85]
	v_mfma_f32_16x16x32_bf16 v[74:77], v[200:203], v[224:227], v[74:77]
	v_mfma_f32_16x16x32_bf16 v[70:73], v[192:195], v[232:235], v[70:73]
	v_mfma_f32_16x16x32_bf16 v[66:69], v[200:203], v[232:235], v[66:69]
	s_barrier
; #define PG8_STAGE(bufoff, gbase, voff) do { _Pragma("unroll") for (int _i = 0; _i < 2; ++_i) \
;         __builtin_amdgcn_global_load_lds((const unsigned*)((const char*)(gbase) + (voff)[_i]), (LAS unsigned*)(lds + (bufoff) + ldsw + _i * 8192), 16, 0, 0); } while (0)
; #define PG8_LDA(dst, b, h) do { _Pragma("unroll") for (int m = 0; m < 4; ++m) _Pragma("unroll") for (int k = 0; k < 2; ++k) dst[m][k] = *(const LAS bf16x8*)(lds + PG8_SA(b, h) + aoff + m * 2048 + k * 1024); } while (0)
; #define PG8_LDB(dst, b, h) do { _Pragma("unroll") for (int n = 0; n < 2; ++n) _Pragma("unroll") for (int k = 0; k < 2; ++k) dst[n][k] = *(const LAS bf16x8*)(lds + PG8_SB(b, h) + boff + n * 2048 + k * 1024); } while (0)
; #define PG8_BAR __builtin_amdgcn_s_barrier()
; template <class Epi, bool ALIGN_EPI = PG8_ALIGN, bool SP2 = PG8_SP2>
; __device__ __forceinline__ void gemm_phase(LAS uchar* lds, const Gemm g, const StaticOrder& S, const Epi& E) {
;     ...
;         for (int t = tb; t < tb + tblk; t += 2) {
;             const bool last = (t == nt - 2);
;             const char* a1 = cA + (size_t)(t + 1) * kstep;
;             const char* a2 = last ? nA : cA + (size_t)(t + 2) * kstep; const char* b2 = last ? nB : cB + (size_t)(t + 2) * kstep;
;             const char* a3 = a2 + kstep; const char* b3 = b2 + kstep;
;             if constexpr (SP2) {
;             PG8_LDB(B0, 0, 0); PG8_LDB(B1, 0, 1); PG8_SCHED; PG8_LDA(At, 0, 0); PG8_STAGE(PG8_SA(1, 1), a1 + hstepA, voffA);
;             PG8_WAIT_V(8); PG8_WAIT_L(0); PG8_BAR; PG8_MMA(0, 0, At, B0); PG8_MMA(0, 1, At, B1); PG8_BAR; PG8_SCHED;
;             PG8_LDA(At, 0, 1); PG8_STAGE(PG8_SB(0, 0), b2, voffB); PG8_STAGE(PG8_SB(0, 1), b2 + hstepB, voffB); PG8_STAGE(PG8_SA(0, 0), a2, voffA);
;             PG8_WAIT_V(8); PG8_WAIT_L(0); PG8_BAR; PG8_MMA(1, 0, At, B0); PG8_MMA(1, 1, At, B1); PG8_BAR; PG8_SCHED;
;             PG8_LDB(B0, 1, 0); PG8_LDB(B1, 1, 1); PG8_SCHED; PG8_LDA(At, 1, 0); PG8_STAGE(PG8_SA(0, 1), a2 + hstepA, voffA);
;             PG8_WAIT_V(8); PG8_WAIT_L(0); PG8_BAR; PG8_MMA(0, 0, At, B0); PG8_MMA(0, 1, At, B1); PG8_BAR; PG8_SCHED;
;             PG8_LDA(At, 1, 1); PG8_STAGE(PG8_SB(1, 0), b3, voffB); PG8_STAGE(PG8_SB(1, 1), b3 + hstepB, voffB); PG8_STAGE(PG8_SA(1, 0), a3, voffA);
;             PG8_WAIT_V(8); PG8_WAIT_L(0); PG8_BAR; PG8_MMA(1, 0, At, B0); PG8_MMA(1, 1, At, B1); PG8_BAR; PG8_SCHED;
	s_setprio 0
	s_add_i32 s16, s41, s23
	s_mov_b32 m0, s16
	v_lshl_add_u64 v[168:169], v[168:169], 0, s[84:85]
	global_load_lds_dwordx4 v[168:169], off
	s_add_i32 m0, s16, 0x2000
	s_add_u32 s4, s4, 0x44080
	v_lshl_add_u64 v[168:169], v[180:181], 0, s[84:85]
	s_addc_u32 s5, s5, 0
	s_add_i32 s16, s42, s23
	global_load_lds_dwordx4 v[168:169], off
	s_mov_b32 m0, s16
	v_lshl_add_u64 v[168:169], s[4:5], 0, v[134:135]
	global_load_lds_dwordx4 v[168:169], off
	s_add_i32 m0, s16, 0x2000
	v_lshl_add_u64 v[168:169], s[4:5], 0, v[130:131]
	global_load_lds_dwordx4 v[168:169], off
	s_mov_b32 m0, s29
	v_lshl_add_u64 v[168:169], v[236:237], 0, s[84:85]
	global_load_lds_dwordx4 v[168:169], off
	s_mov_b32 m0, s30
	v_lshl_add_u64 v[168:169], v[238:239], 0, s[84:85]
	global_load_lds_dwordx4 v[168:169], off
	ds_read_b128 v[204:207], v171 offset:49152
	ds_read_b128 v[208:211], v171 offset:50176
	ds_read_b128 v[212:215], v171 offset:51200
	ds_read_b128 v[216:219], v171 offset:52224
	ds_read_b128 v[220:223], v171 offset:53248
	ds_read_b128 v[224:227], v171 offset:54272
	ds_read_b128 v[228:231], v171 offset:55296
	ds_read_b128 v[232:235], v171 offset:56320
	s_setprio 1
	s_waitcnt vmcnt(8) lgkmcnt(0)
	s_barrier
	v_mfma_f32_16x16x32_bf16 v[62:65], v[164:167], v[204:207], v[62:65]
	v_mfma_f32_16x16x32_bf16 v[58:61], v[176:179], v[204:207], v[58:61]
	v_mfma_f32_16x16x32_bf16 v[54:57], v[164:167], v[212:215], v[54:57]
	v_mfma_f32_16x16x32_bf16 v[46:49], v[176:179], v[212:215], v[46:49]
	v_mfma_f32_16x16x32_bf16 v[38:41], v[164:167], v[220:223], v[38:41]
	v_mfma_f32_16x16x32_bf16 v[30:33], v[176:179], v[220:223], v[30:33]
	v_mfma_f32_16x16x32_bf16 v[22:25], v[164:167], v[228:231], v[22:25]
	v_mfma_f32_16x16x32_bf16 v[14:17], v[176:179], v[228:231], v[14:17]
	v_mfma_f32_16x16x32_bf16 v[62:65], v[172:175], v[208:211], v[62:65]
	v_mfma_f32_16x16x32_bf16 v[58:61], v[184:187], v[208:211], v[58:61]
	v_mfma_f32_16x16x32_bf16 v[54:57], v[172:175], v[216:219], v[54:57]
	v_mfma_f32_16x16x32_bf16 v[46:49], v[184:187], v[216:219], v[46:49]
	v_mfma_f32_16x16x32_bf16 v[38:41], v[172:175], v[224:227], v[38:41]
	v_mfma_f32_16x16x32_bf16 v[30:33], v[184:187], v[224:227], v[30:33]
	v_mfma_f32_16x16x32_bf16 v[22:25], v[172:175], v[232:235], v[22:25]
	v_mfma_f32_16x16x32_bf16 v[14:17], v[184:187], v[232:235], v[14:17]
	v_mfma_f32_16x16x32_bf16 v[50:53], v[188:191], v[204:207], v[50:53]
	v_mfma_f32_16x16x32_bf16 v[42:45], v[196:199], v[204:207], v[42:45]
	v_mfma_f32_16x16x32_bf16 v[34:37], v[188:191], v[212:215], v[34:37]
	v_mfma_f32_16x16x32_bf16 v[26:29], v[196:199], v[212:215], v[26:29]
	v_mfma_f32_16x16x32_bf16 v[18:21], v[188:191], v[220:223], v[18:21]
	v_mfma_f32_16x16x32_bf16 v[10:13], v[196:199], v[220:223], v[10:13]
	v_mfma_f32_16x16x32_bf16 v[6:9], v[188:191], v[228:231], v[6:9]
	v_mfma_f32_16x16x32_bf16 v[2:5], v[196:199], v[228:231], v[2:5]
	v_mfma_f32_16x16x32_bf16 v[50:53], v[192:195], v[208:211], v[50:53]
	v_mfma_f32_16x16x32_bf16 v[42:45], v[200:203], v[208:211], v[42:45]
	v_mfma_f32_16x16x32_bf16 v[34:37], v[192:195], v[216:219], v[34:37]
	v_mfma_f32_16x16x32_bf16 v[26:29], v[200:203], v[216:219], v[26:29]
	v_mfma_f32_16x16x32_bf16 v[18:21], v[192:195], v[224:227], v[18:21]
	v_mfma_f32_16x16x32_bf16 v[10:13], v[200:203], v[224:227], v[10:13]
	v_mfma_f32_16x16x32_bf16 v[6:9], v[192:195], v[232:235], v[6:9]
	v_mfma_f32_16x16x32_bf16 v[2:5], v[200:203], v[232:235], v[2:5]
	s_barrier
	s_setprio 0
	s_add_i32 s40, s40, 2
	s_add_u32 s38, s38, 0x100
	s_addc_u32 s39, s39, 0
	s_cmp_gt_u32 s40, 13
	s_mov_b64 s[16:17], s[18:19]
.LBB0_345:
	s_add_u32 s18, s16, 0x100
	s_addc_u32 s19, s17, 0
	s_add_i32 s41, 0, 0x10000
	s_cmp_eq_u32 s40, 12
	s_cselect_b32 s21, s7, s19
	s_cselect_b32 s20, s6, s18
	v_add_u32_e32 v168, s41, v139
	s_cselect_b32 s5, s15, s39
	s_cselect_b32 s4, s14, s38
	s_add_i32 s42, 0, 0x14000
	ds_read_b128 v[164:167], v168
	ds_read_b128 v[172:175], v168 offset:1024
	ds_read_b128 v[176:179], v168 offset:2048
	ds_read_b128 v[184:187], v168 offset:3072
	v_add_u32_e32 v168, s42, v139
	ds_read_b128 v[188:191], v168
	ds_read_b128 v[192:195], v168 offset:1024
	ds_read_b128 v[196:199], v168 offset:2048
	ds_read_b128 v[200:203], v168 offset:3072
	s_add_i32 m0, s25, 0xc000
	v_lshl_add_u64 v[168:169], s[16:17], 0, v[160:161]
	global_load_lds_dwordx4 v[168:169], off
	s_add_i32 m0, s25, 0xe000
	v_lshl_add_u64 v[168:169], s[16:17], 0, v[162:163]
	global_load_lds_dwordx4 v[168:169], off
	ds_read_b128 v[204:207], v171
	ds_read_b128 v[208:211], v171 offset:1024
	ds_read_b128 v[212:215], v171 offset:2048
	ds_read_b128 v[216:219], v171 offset:3072
	ds_read_b128 v[220:223], v171 offset:4096
	ds_read_b128 v[224:227], v171 offset:5120
	ds_read_b128 v[228:231], v171 offset:6144
	ds_read_b128 v[232:235], v171 offset:7168
	s_setprio 1
	s_waitcnt vmcnt(8) lgkmcnt(0)
	s_barrier
; #define PG8_STAGE(bufoff, gbase, voff) do { _Pragma("unroll") for (int _i = 0; _i < 2; ++_i) \
;         __builtin_amdgcn_global_load_lds((const unsigned*)((const char*)(gbase) + (voff)[_i]), (LAS unsigned*)(lds + (bufoff) + ldsw + _i * 8192), 16, 0, 0); } while (0)
; #define PG8_LDA(dst, b, h) do { _Pragma("unroll") for (int m = 0; m < 4; ++m) _Pragma("unroll") for (int k = 0; k < 2; ++k) dst[m][k] = *(const LAS bf16x8*)(lds + PG8_SA(b, h) + aoff + m * 2048 + k * 1024); } while (0)
; #define PG8_MMA(ai, bj, At, Bt) do { __builtin_amdgcn_s_setprio(1); _Pragma("unroll") for (int m = 0; m < 4; ++m) _Pragma("unroll") for (int n = 0; n < 2; ++n) _Pragma("unroll") for (int k = 0; k < 2; ++k) \
;         acc[ai][bj][m][n] = __builtin_amdgcn_mfma_f32_16x16x32_bf16(Bt[n][k], At[m][k], acc[ai][bj][m][n], 0, 0, 0); __builtin_amdgcn_s_setprio(0); } while (0)
; #define PG8_WAIT_V(n) asm volatile("s_waitcnt vmcnt(" #n ")" ::: "memory")
; #define PG8_WAIT_L(n) asm volatile("s_waitcnt lgkmcnt(" #n ")" ::: "memory")
; #define PG8_BAR __builtin_amdgcn_s_barrier()
; #define PG8_SCHED __builtin_amdgcn_sched_barrier(0)
; template <class Epi, bool ALIGN_EPI = PG8_ALIGN, bool SP2 = PG8_SP2>
; __device__ __forceinline__ void gemm_phase(LAS uchar* lds, const Gemm g, const StaticOrder& S, const Epi& E) {
;     ...
;             PG8_WAIT_V(8); PG8_WAIT_L(0); PG8_BAR; PG8_MMA(0, 0, At, B0); PG8_MMA(0, 1, At, B1); PG8_BAR; PG8_SCHED;
;             PG8_LDA(At, 0, 1); PG8_STAGE(PG8_SB(0, 0), b2, voffB); PG8_STAGE(PG8_SB(0, 1), b2 + hstepB, voffB); PG8_STAGE(PG8_SA(0, 0), a2, voffA);
;             PG8_WAIT_V(8); PG8_WAIT_L(0); PG8_BAR; PG8_MMA(1, 0, At, B0); PG8_MMA(1, 1, At, B1); PG8_BAR; PG8_SCHED;
	v_mfma_f32_16x16x32_bf16 v[126:129], v[164:167], v[204:207], v[126:129]
	v_mfma_f32_16x16x32_bf16 v[122:125], v[176:179], v[204:207], v[122:125]
	v_mfma_f32_16x16x32_bf16 v[118:121], v[164:167], v[212:215], v[118:121]
	v_mfma_f32_16x16x32_bf16 v[110:113], v[176:179], v[212:215], v[110:113]
	v_mfma_f32_16x16x32_bf16 v[102:105], v[164:167], v[220:223], v[102:105]
	v_mfma_f32_16x16x32_bf16 v[94:97], v[176:179], v[220:223], v[94:97]
	v_mfma_f32_16x16x32_bf16 v[86:89], v[164:167], v[228:231], v[86:89]
	v_mfma_f32_16x16x32_bf16 v[78:81], v[176:179], v[228:231], v[78:81]
	v_mfma_f32_16x16x32_bf16 v[126:129], v[172:175], v[208:211], v[126:129]
	v_mfma_f32_16x16x32_bf16 v[122:125], v[184:187], v[208:211], v[122:125]
	v_mfma_f32_16x16x32_bf16 v[118:121], v[172:175], v[216:219], v[118:121]
	v_mfma_f32_16x16x32_bf16 v[110:113], v[184:187], v[216:219], v[110:113]
	v_mfma_f32_16x16x32_bf16 v[102:105], v[172:175], v[224:227], v[102:105]
	v_mfma_f32_16x16x32_bf16 v[94:97], v[184:187], v[224:227], v[94:97]
	v_mfma_f32_16x16x32_bf16 v[86:89], v[172:175], v[232:235], v[86:89]
	v_mfma_f32_16x16x32_bf16 v[78:81], v[184:187], v[232:235], v[78:81]
	v_mfma_f32_16x16x32_bf16 v[114:117], v[188:191], v[204:207], v[114:117]
	v_mfma_f32_16x16x32_bf16 v[106:109], v[196:199], v[204:207], v[106:109]
	v_mfma_f32_16x16x32_bf16 v[98:101], v[188:191], v[212:215], v[98:101]
	v_mfma_f32_16x16x32_bf16 v[90:93], v[196:199], v[212:215], v[90:93]
	v_mfma_f32_16x16x32_bf16 v[82:85], v[188:191], v[220:223], v[82:85]
	v_mfma_f32_16x16x32_bf16 v[74:77], v[196:199], v[220:223], v[74:77]
	v_mfma_f32_16x16x32_bf16 v[70:73], v[188:191], v[228:231], v[70:73]
	v_mfma_f32_16x16x32_bf16 v[66:69], v[196:199], v[228:231], v[66:69]
	v_mfma_f32_16x16x32_bf16 v[114:117], v[192:195], v[208:211], v[114:117]
	v_mfma_f32_16x16x32_bf16 v[106:109], v[200:203], v[208:211], v[106:109]
	v_mfma_f32_16x16x32_bf16 v[98:101], v[192:195], v[216:219], v[98:101]
	v_mfma_f32_16x16x32_bf16 v[90:93], v[200:203], v[216:219], v[90:93]
	v_mfma_f32_16x16x32_bf16 v[82:85], v[192:195], v[224:227], v[82:85]
	v_mfma_f32_16x16x32_bf16 v[74:77], v[200:203], v[224:227], v[74:77]
	v_mfma_f32_16x16x32_bf16 v[70:73], v[192:195], v[232:235], v[70:73]
	v_mfma_f32_16x16x32_bf16 v[66:69], v[200:203], v[232:235], v[66:69]
	s_barrier
	s_setprio 0
	s_add_i32 s16, s41, s23
	s_mov_b32 m0, s16
	v_lshl_add_u64 v[168:169], s[4:5], 0, v[134:135]
	global_load_lds_dwordx4 v[168:169], off
	s_add_i32 m0, s16, 0x2000
	s_add_u32 s16, s4, 0x44000
	v_lshl_add_u64 v[180:181], s[4:5], 0, v[130:131]
	s_addc_u32 s17, s5, 0
	s_add_i32 s41, s42, s23
	global_load_lds_dwordx4 v[180:181], off
	s_mov_b32 m0, s41
	v_lshl_add_u64 v[236:237], s[16:17], 0, v[134:135]
	global_load_lds_dwordx4 v[236:237], off
	s_add_i32 m0, s41, 0x2000
	v_lshl_add_u64 v[236:237], s[16:17], 0, v[130:131]
	global_load_lds_dwordx4 v[236:237], off
	s_mov_b32 m0, s25
	v_lshl_add_u64 v[236:237], s[20:21], 0, v[156:157]
	global_load_lds_dwordx4 v[236:237], off
	s_mov_b32 m0, s26
	v_lshl_add_u64 v[238:239], s[20:21], 0, v[132:133]
	global_load_lds_dwordx4 v[238:239], off
	ds_read_b128 v[204:207], v171 offset:16384
	ds_read_b128 v[208:211], v171 offset:17408
	ds_read_b128 v[212:215], v171 offset:18432
	ds_read_b128 v[216:219], v171 offset:19456
	ds_read_b128 v[220:223], v171 offset:20480
	ds_read_b128 v[224:227], v171 offset:21504
	ds_read_b128 v[228:231], v171 offset:22528
	ds_read_b128 v[232:235], v171 offset:23552
	s_setprio 1
	s_waitcnt vmcnt(8) lgkmcnt(0)
	s_barrier
	v_mfma_f32_16x16x32_bf16 v[62:65], v[164:167], v[204:207], v[62:65]
	v_mfma_f32_16x16x32_bf16 v[58:61], v[176:179], v[204:207], v[58:61]
	v_mfma_f32_16x16x32_bf16 v[54:57], v[164:167], v[212:215], v[54:57]
	v_mfma_f32_16x16x32_bf16 v[46:49], v[176:179], v[212:215], v[46:49]
	v_mfma_f32_16x16x32_bf16 v[38:41], v[164:167], v[220:223], v[38:41]
	v_mfma_f32_16x16x32_bf16 v[30:33], v[176:179], v[220:223], v[30:33]
	v_mfma_f32_16x16x32_bf16 v[22:25], v[164:167], v[228:231], v[22:25]
	v_mfma_f32_16x16x32_bf16 v[14:17], v[176:179], v[228:231], v[14:17]
	v_mfma_f32_16x16x32_bf16 v[62:65], v[172:175], v[208:211], v[62:65]
	v_mfma_f32_16x16x32_bf16 v[58:61], v[184:187], v[208:211], v[58:61]
	v_mfma_f32_16x16x32_bf16 v[54:57], v[172:175], v[216:219], v[54:57]
	v_mfma_f32_16x16x32_bf16 v[46:49], v[184:187], v[216:219], v[46:49]
	v_mfma_f32_16x16x32_bf16 v[38:41], v[172:175], v[224:227], v[38:41]
	v_mfma_f32_16x16x32_bf16 v[30:33], v[184:187], v[224:227], v[30:33]
	v_mfma_f32_16x16x32_bf16 v[22:25], v[172:175], v[232:235], v[22:25]
	v_mfma_f32_16x16x32_bf16 v[14:17], v[184:187], v[232:235], v[14:17]
	v_mfma_f32_16x16x32_bf16 v[50:53], v[188:191], v[204:207], v[50:53]
	v_mfma_f32_16x16x32_bf16 v[42:45], v[196:199], v[204:207], v[42:45]
	v_mfma_f32_16x16x32_bf16 v[34:37], v[188:191], v[212:215], v[34:37]
	v_mfma_f32_16x16x32_bf16 v[26:29], v[196:199], v[212:215], v[26:29]
	v_mfma_f32_16x16x32_bf16 v[18:21], v[188:191], v[220:223], v[18:21]
	v_mfma_f32_16x16x32_bf16 v[10:13], v[196:199], v[220:223], v[10:13]
	v_mfma_f32_16x16x32_bf16 v[6:9], v[188:191], v[228:231], v[6:9]
	v_mfma_f32_16x16x32_bf16 v[2:5], v[196:199], v[228:231], v[2:5]
	v_mfma_f32_16x16x32_bf16 v[50:53], v[192:195], v[208:211], v[50:53]
	v_mfma_f32_16x16x32_bf16 v[42:45], v[200:203], v[208:211], v[42:45]
	v_mfma_f32_16x16x32_bf16 v[34:37], v[192:195], v[216:219], v[34:37]
	v_mfma_f32_16x16x32_bf16 v[26:29], v[200:203], v[216:219], v[26:29]
	v_mfma_f32_16x16x32_bf16 v[18:21], v[192:195], v[224:227], v[18:21]
	v_mfma_f32_16x16x32_bf16 v[10:13], v[200:203], v[224:227], v[10:13]
	v_mfma_f32_16x16x32_bf16 v[6:9], v[192:195], v[232:235], v[6:9]
	v_mfma_f32_16x16x32_bf16 v[2:5], v[200:203], v[232:235], v[2:5]
	s_barrier
; #define PG8_STAGE(bufoff, gbase, voff) do { _Pragma("unroll") for (int _i = 0; _i < 2; ++_i) \
;         __builtin_amdgcn_global_load_lds((const unsigned*)((const char*)(gbase) + (voff)[_i]), (LAS unsigned*)(lds + (bufoff) + ldsw + _i * 8192), 16, 0, 0); } while (0)
; #define PG8_LDA(dst, b, h) do { _Pragma("unroll") for (int m = 0; m < 4; ++m) _Pragma("unroll") for (int k = 0; k < 2; ++k) dst[m][k] = *(const LAS bf16x8*)(lds + PG8_SA(b, h) + aoff + m * 2048 + k * 1024); } while (0)
; #define PG8_LDB(dst, b, h) do { _Pragma("unroll") for (int n = 0; n < 2; ++n) _Pragma("unroll") for (int k = 0; k < 2; ++k) dst[n][k] = *(const LAS bf16x8*)(lds + PG8_SB(b, h) + boff + n * 2048 + k * 1024); } while (0)
; #define PG8_MMA(ai, bj, At, Bt) do { __builtin_amdgcn_s_setprio(1); _Pragma("unroll") for (int m = 0; m < 4; ++m) _Pragma("unroll") for (int n = 0; n < 2; ++n) _Pragma("unroll") for (int k = 0; k < 2; ++k) \
;         acc[ai][bj][m][n] = __builtin_amdgcn_mfma_f32_16x16x32_bf16(Bt[n][k], At[m][k], acc[ai][bj][m][n], 0, 0, 0); __builtin_amdgcn_s_setprio(0); } while (0)
; #define PG8_WAIT_V(n) asm volatile("s_waitcnt vmcnt(" #n ")" ::: "memory")
; #define PG8_WAIT_L(n) asm volatile("s_waitcnt lgkmcnt(" #n ")" ::: "memory")
; #define PG8_BAR __builtin_amdgcn_s_barrier()
; #define PG8_SCHED __builtin_amdgcn_sched_barrier(0)
; template <class Epi, bool ALIGN_EPI = PG8_ALIGN, bool SP2 = PG8_SP2>
; __device__ __forceinline__ void gemm_phase(LAS uchar* lds, const Gemm g, const StaticOrder& S, const Epi& E) {
;     ...
;             PG8_WAIT_V(8); PG8_WAIT_L(0); PG8_BAR; PG8_MMA(1, 0, At, B0); PG8_MMA(1, 1, At, B1); PG8_BAR; PG8_SCHED;
;             PG8_LDB(B0, 1, 0); PG8_LDB(B1, 1, 1); PG8_SCHED; PG8_LDA(At, 1, 0); PG8_STAGE(PG8_SA(0, 1), a2 + hstepA, voffA);
;             PG8_WAIT_V(8); PG8_WAIT_L(0); PG8_BAR; PG8_MMA(0, 0, At, B0); PG8_MMA(0, 1, At, B1); PG8_BAR; PG8_SCHED;
	s_setprio 0
	s_add_i32 s41, 0, 0x18000
	s_add_i32 s42, 0, 0x1c000
	v_add_u32_e32 v184, s41, v139
	v_add_u32_e32 v200, s42, v139
	s_add_u32 s16, s20, 0x44000
	s_addc_u32 s17, s21, 0
	s_mov_b32 m0, s27
	v_lshl_add_u64 v[240:241], s[16:17], 0, v[156:157]
	global_load_lds_dwordx4 v[240:241], off
	s_mov_b32 m0, s28
	v_lshl_add_u64 v[240:241], s[16:17], 0, v[132:133]
	global_load_lds_dwordx4 v[240:241], off
	ds_read_b128 v[164:167], v184
	ds_read_b128 v[172:175], v184 offset:1024
	ds_read_b128 v[176:179], v184 offset:2048
	ds_read_b128 v[184:187], v184 offset:3072
	ds_read_b128 v[188:191], v200
	ds_read_b128 v[192:195], v200 offset:1024
	ds_read_b128 v[196:199], v200 offset:2048
	ds_read_b128 v[200:203], v200 offset:3072
	ds_read_b128 v[204:207], v171 offset:32768
	ds_read_b128 v[208:211], v171 offset:33792
	ds_read_b128 v[212:215], v171 offset:34816
	ds_read_b128 v[216:219], v171 offset:35840
	ds_read_b128 v[220:223], v171 offset:36864
	ds_read_b128 v[224:227], v171 offset:37888
	ds_read_b128 v[228:231], v171 offset:38912
	ds_read_b128 v[232:235], v171 offset:39936
	s_setprio 1
	s_waitcnt vmcnt(8) lgkmcnt(0)
	s_barrier
	v_mfma_f32_16x16x32_bf16 v[126:129], v[164:167], v[204:207], v[126:129]
	v_mfma_f32_16x16x32_bf16 v[122:125], v[176:179], v[204:207], v[122:125]
	v_mfma_f32_16x16x32_bf16 v[118:121], v[164:167], v[212:215], v[118:121]
	v_mfma_f32_16x16x32_bf16 v[110:113], v[176:179], v[212:215], v[110:113]
	v_mfma_f32_16x16x32_bf16 v[102:105], v[164:167], v[220:223], v[102:105]
	v_mfma_f32_16x16x32_bf16 v[94:97], v[176:179], v[220:223], v[94:97]
	v_mfma_f32_16x16x32_bf16 v[86:89], v[164:167], v[228:231], v[86:89]
	v_mfma_f32_16x16x32_bf16 v[78:81], v[176:179], v[228:231], v[78:81]
	v_mfma_f32_16x16x32_bf16 v[126:129], v[172:175], v[208:211], v[126:129]
	v_mfma_f32_16x16x32_bf16 v[122:125], v[184:187], v[208:211], v[122:125]
	v_mfma_f32_16x16x32_bf16 v[118:121], v[172:175], v[216:219], v[118:121]
	v_mfma_f32_16x16x32_bf16 v[110:113], v[184:187], v[216:219], v[110:113]
	v_mfma_f32_16x16x32_bf16 v[102:105], v[172:175], v[224:227], v[102:105]
	v_mfma_f32_16x16x32_bf16 v[94:97], v[184:187], v[224:227], v[94:97]
	v_mfma_f32_16x16x32_bf16 v[86:89], v[172:175], v[232:235], v[86:89]
	v_mfma_f32_16x16x32_bf16 v[78:81], v[184:187], v[232:235], v[78:81]
	v_mfma_f32_16x16x32_bf16 v[114:117], v[188:191], v[204:207], v[114:117]
	v_mfma_f32_16x16x32_bf16 v[106:109], v[196:199], v[204:207], v[106:109]
	v_mfma_f32_16x16x32_bf16 v[98:101], v[188:191], v[212:215], v[98:101]
	v_mfma_f32_16x16x32_bf16 v[90:93], v[196:199], v[212:215], v[90:93]
	v_mfma_f32_16x16x32_bf16 v[82:85], v[188:191], v[220:223], v[82:85]
	v_mfma_f32_16x16x32_bf16 v[74:77], v[196:199], v[220:223], v[74:77]
	v_mfma_f32_16x16x32_bf16 v[70:73], v[188:191], v[228:231], v[70:73]
	v_mfma_f32_16x16x32_bf16 v[66:69], v[196:199], v[228:231], v[66:69]
	v_mfma_f32_16x16x32_bf16 v[114:117], v[192:195], v[208:211], v[114:117]
	v_mfma_f32_16x16x32_bf16 v[106:109], v[200:203], v[208:211], v[106:109]
	v_mfma_f32_16x16x32_bf16 v[98:101], v[192:195], v[216:219], v[98:101]
	v_mfma_f32_16x16x32_bf16 v[90:93], v[200:203], v[216:219], v[90:93]
	v_mfma_f32_16x16x32_bf16 v[82:85], v[192:195], v[224:227], v[82:85]
	v_mfma_f32_16x16x32_bf16 v[74:77], v[200:203], v[224:227], v[74:77]
	v_mfma_f32_16x16x32_bf16 v[70:73], v[192:195], v[232:235], v[70:73]
	v_mfma_f32_16x16x32_bf16 v[66:69], v[200:203], v[232:235], v[66:69]
	s_barrier
; #define PG8_STAGE(bufoff, gbase, voff) do { _Pragma("unroll") for (int _i = 0; _i < 2; ++_i) \
;         __builtin_amdgcn_global_load_lds((const unsigned*)((const char*)(gbase) + (voff)[_i]), (LAS unsigned*)(lds + (bufoff) + ldsw + _i * 8192), 16, 0, 0); } while (0)
; #define PG8_LDA(dst, b, h) do { _Pragma("unroll") for (int m = 0; m < 4; ++m) _Pragma("unroll") for (int k = 0; k < 2; ++k) dst[m][k] = *(const LAS bf16x8*)(lds + PG8_SA(b, h) + aoff + m * 2048 + k * 1024); } while (0)
; #define PG8_MMA(ai, bj, At, Bt) do { __builtin_amdgcn_s_setprio(1); _Pragma("unroll") for (int m = 0; m < 4; ++m) _Pragma("unroll") for (int n = 0; n < 2; ++n) _Pragma("unroll") for (int k = 0; k < 2; ++k) \
;         acc[ai][bj][m][n] = __builtin_amdgcn_mfma_f32_16x16x32_bf16(Bt[n][k], At[m][k], acc[ai][bj][m][n], 0, 0, 0); __builtin_amdgcn_s_setprio(0); } while (0)
; #define PG8_WAIT_V(n) asm volatile("s_waitcnt vmcnt(" #n ")" ::: "memory")
; #define PG8_WAIT_L(n) asm volatile("s_waitcnt lgkmcnt(" #n ")" ::: "memory")
; #define PG8_BAR __builtin_amdgcn_s_barrier()
; #define PG8_SCHED __builtin_amdgcn_sched_barrier(0)
; template <class Epi, bool ALIGN_EPI = PG8_ALIGN, bool SP2 = PG8_SP2>
; __device__ __forceinline__ void gemm_phase(LAS uchar* lds, const Gemm g, const StaticOrder& S, const Epi& E) {
;     ...
;             PG8_WAIT_V(8); PG8_WAIT_L(0); PG8_BAR; PG8_MMA(0, 0, At, B0); PG8_MMA(0, 1, At, B1); PG8_BAR; PG8_SCHED;
;             PG8_LDA(At, 1, 1); PG8_STAGE(PG8_SB(1, 0), b3, voffB); PG8_STAGE(PG8_SB(1, 1), b3 + hstepB, voffB); PG8_STAGE(PG8_SA(1, 0), a3, voffA);
;             PG8_WAIT_V(8); PG8_WAIT_L(0); PG8_BAR; PG8_MMA(1, 0, At, B0); PG8_MMA(1, 1, At, B1); PG8_BAR; PG8_SCHED;
;     __device__ __forceinline__ void operator()(const f32x4 (&acc)[2][2][4][2], const pg8::Unit& u, int wr, int wc, int fr, int fq, int) const {
;         const int row0 = u.pm * 256 + wr * 64 + fr;
;         if (u.pn < 24) {
;             const int col0 = u.pn * 256 + wc * 32 + 8 * fq;
	s_setprio 0
	s_add_i32 s16, s41, s23
	s_mov_b32 m0, s16
	v_lshl_add_u64 v[168:169], v[168:169], 0, s[84:85]
	global_load_lds_dwordx4 v[168:169], off
	s_add_i32 m0, s16, 0x2000
	s_add_u32 s4, s4, 0x44080
	v_lshl_add_u64 v[168:169], v[180:181], 0, s[84:85]
	s_addc_u32 s5, s5, 0
	s_add_i32 s16, s42, s23
	global_load_lds_dwordx4 v[168:169], off
	s_mov_b32 m0, s16
	v_lshl_add_u64 v[168:169], s[4:5], 0, v[134:135]
	global_load_lds_dwordx4 v[168:169], off
	s_add_i32 m0, s16, 0x2000
	v_lshl_add_u64 v[168:169], s[4:5], 0, v[130:131]
	global_load_lds_dwordx4 v[168:169], off
	s_mov_b32 m0, s29
	v_lshl_add_u64 v[168:169], v[236:237], 0, s[84:85]
	global_load_lds_dwordx4 v[168:169], off
	s_mov_b32 m0, s30
	v_lshl_add_u64 v[168:169], v[238:239], 0, s[84:85]
	global_load_lds_dwordx4 v[168:169], off
	ds_read_b128 v[204:207], v171 offset:49152
	ds_read_b128 v[208:211], v171 offset:50176
	ds_read_b128 v[212:215], v171 offset:51200
	ds_read_b128 v[216:219], v171 offset:52224
	ds_read_b128 v[220:223], v171 offset:53248
	ds_read_b128 v[224:227], v171 offset:54272
	ds_read_b128 v[228:231], v171 offset:55296
	ds_read_b128 v[232:235], v171 offset:56320
	s_setprio 1
	s_waitcnt vmcnt(8) lgkmcnt(0)
	s_barrier
	v_mfma_f32_16x16x32_bf16 v[62:65], v[164:167], v[204:207], v[62:65]
	v_mfma_f32_16x16x32_bf16 v[58:61], v[176:179], v[204:207], v[58:61]
	v_mfma_f32_16x16x32_bf16 v[54:57], v[164:167], v[212:215], v[54:57]
	v_mfma_f32_16x16x32_bf16 v[46:49], v[176:179], v[212:215], v[46:49]
	v_mfma_f32_16x16x32_bf16 v[38:41], v[164:167], v[220:223], v[38:41]
	v_mfma_f32_16x16x32_bf16 v[30:33], v[176:179], v[220:223], v[30:33]
	v_mfma_f32_16x16x32_bf16 v[22:25], v[164:167], v[228:231], v[22:25]
	v_mfma_f32_16x16x32_bf16 v[14:17], v[176:179], v[228:231], v[14:17]
	v_mfma_f32_16x16x32_bf16 v[62:65], v[172:175], v[208:211], v[62:65]
	v_mfma_f32_16x16x32_bf16 v[58:61], v[184:187], v[208:211], v[58:61]
	v_mfma_f32_16x16x32_bf16 v[54:57], v[172:175], v[216:219], v[54:57]
	v_mfma_f32_16x16x32_bf16 v[46:49], v[184:187], v[216:219], v[46:49]
	v_mfma_f32_16x16x32_bf16 v[38:41], v[172:175], v[224:227], v[38:41]
	v_mfma_f32_16x16x32_bf16 v[30:33], v[184:187], v[224:227], v[30:33]
	v_mfma_f32_16x16x32_bf16 v[22:25], v[172:175], v[232:235], v[22:25]
	v_mfma_f32_16x16x32_bf16 v[14:17], v[184:187], v[232:235], v[14:17]
	v_mfma_f32_16x16x32_bf16 v[50:53], v[188:191], v[204:207], v[50:53]
	v_mfma_f32_16x16x32_bf16 v[42:45], v[196:199], v[204:207], v[42:45]
	v_mfma_f32_16x16x32_bf16 v[34:37], v[188:191], v[212:215], v[34:37]
	v_mfma_f32_16x16x32_bf16 v[26:29], v[196:199], v[212:215], v[26:29]
	v_mfma_f32_16x16x32_bf16 v[18:21], v[188:191], v[220:223], v[18:21]
	v_mfma_f32_16x16x32_bf16 v[10:13], v[196:199], v[220:223], v[10:13]
	v_mfma_f32_16x16x32_bf16 v[6:9], v[188:191], v[228:231], v[6:9]
	v_mfma_f32_16x16x32_bf16 v[2:5], v[196:199], v[228:231], v[2:5]
	v_mfma_f32_16x16x32_bf16 v[50:53], v[192:195], v[208:211], v[50:53]
	v_mfma_f32_16x16x32_bf16 v[42:45], v[200:203], v[208:211], v[42:45]
	v_mfma_f32_16x16x32_bf16 v[34:37], v[192:195], v[216:219], v[34:37]
	v_mfma_f32_16x16x32_bf16 v[26:29], v[200:203], v[216:219], v[26:29]
	v_mfma_f32_16x16x32_bf16 v[18:21], v[192:195], v[224:227], v[18:21]
	v_mfma_f32_16x16x32_bf16 v[10:13], v[200:203], v[224:227], v[10:13]
	v_mfma_f32_16x16x32_bf16 v[6:9], v[192:195], v[232:235], v[6:9]
	v_mfma_f32_16x16x32_bf16 v[2:5], v[200:203], v[232:235], v[2:5]
	s_barrier
	s_setprio 0
	s_add_i32 s40, s40, 2
	s_add_u32 s38, s38, 0x100
	s_addc_u32 s39, s39, 0
	s_cmp_gt_u32 s40, 13
	s_mov_b64 s[16:17], s[18:19]
	s_cbranch_scc0 .LBB0_345
	s_mov_b32 s97, 0
	s_and_b64 vcc, exec, s[10:11]
	s_cbranch_vccnz .LBB0_350
	v_lshl_add_u32 v164, s37, 8, v1
	s_cmp_gt_i32 s36, 23
	s_mov_b64 s[4:5], -1
	s_cbranch_scc1 .LBB0_351

; #define PG8_STAGE(bufoff, gbase, voff) do { _Pragma("unroll") for (int _i = 0; _i < 2; ++_i) \
;         __builtin_amdgcn_global_load_lds((const unsigned*)((const char*)(gbase) + (voff)[_i]), (LAS unsigned*)(lds + (bufoff) + ldsw + _i * 8192), 16, 0, 0); } while (0)
; #define PG8_LDA(dst, b, h) do { _Pragma("unroll") for (int m = 0; m < 4; ++m) _Pragma("unroll") for (int k = 0; k < 2; ++k) dst[m][k] = *(const LAS bf16x8*)(lds + PG8_SA(b, h) + aoff + m * 2048 + k * 1024); } while (0)
; #define PG8_LDB(dst, b, h) do { _Pragma("unroll") for (int n = 0; n < 2; ++n) _Pragma("unroll") for (int k = 0; k < 2; ++k) dst[n][k] = *(const LAS bf16x8*)(lds + PG8_SB(b, h) + boff + n * 2048 + k * 1024); } while (0)
; #define PG8_MMA(ai, bj, At, Bt) do { __builtin_amdgcn_s_setprio(1); _Pragma("unroll") for (int m = 0; m < 4; ++m) _Pragma("unroll") for (int n = 0; n < 2; ++n) _Pragma("unroll") for (int k = 0; k < 2; ++k) \
;         acc[ai][bj][m][n] = __builtin_amdgcn_mfma_f32_16x16x32_bf16(Bt[n][k], At[m][k], acc[ai][bj][m][n], 0, 0, 0); __builtin_amdgcn_s_setprio(0); } while (0)
; #define PG8_WAIT_V(n) asm volatile("s_waitcnt vmcnt(" #n ")" ::: "memory")
; #define PG8_WAIT_L(n) asm volatile("s_waitcnt lgkmcnt(" #n ")" ::: "memory")
; #define PG8_BAR __builtin_amdgcn_s_barrier()
; template <class Epi, bool ALIGN_EPI = PG8_ALIGN, bool SP2 = PG8_SP2>
; __device__ __forceinline__ void gemm_phase(LAS uchar* lds, const Gemm g, const StaticOrder& S, const Epi& E) {
;     ...
;         for (int t = tb; t < tb + tblk; t += 2) {
;             const bool last = (t == nt - 2);
;             const char* a1 = cA + (size_t)(t + 1) * kstep;
;             const char* a2 = last ? nA : cA + (size_t)(t + 2) * kstep; const char* b2 = last ? nB : cB + (size_t)(t + 2) * kstep;
;             const char* a3 = a2 + kstep; const char* b3 = b2 + kstep;
;             if constexpr (SP2) {
;             PG8_LDB(B0, 0, 0); PG8_LDB(B1, 0, 1); PG8_SCHED; PG8_LDA(At, 0, 0); PG8_STAGE(PG8_SA(1, 1), a1 + hstepA, voffA);
;             PG8_WAIT_V(8); PG8_WAIT_L(0); PG8_BAR; PG8_MMA(0, 0, At, B0); PG8_MMA(0, 1, At, B1); PG8_BAR; PG8_SCHED;
;             PG8_LDA(At, 0, 1); PG8_STAGE(PG8_SB(0, 0), b2, voffB); PG8_STAGE(PG8_SB(0, 1), b2 + hstepB, voffB); PG8_STAGE(PG8_SA(0, 0), a2, voffA);
;             PG8_WAIT_V(8); PG8_WAIT_L(0); PG8_BAR; PG8_MMA(1, 0, At, B0); PG8_MMA(1, 1, At, B1); PG8_BAR; PG8_SCHED;
.LBB0_580:
	s_add_i32 s42, s42, 2
	s_add_u32 s4, s14, s18
	s_addc_u32 s5, s15, s19
	s_add_u32 s4, s4, 0x100
	s_addc_u32 s5, s5, 0
	s_add_u32 s43, s38, s18
	s_addc_u32 s44, s39, s19
	s_add_i32 s45, 0, 0x10000
	s_cmpk_eq_i32 s18, 0xf00
	s_cselect_b32 s21, s1, s5
	s_cselect_b32 s20, s0, s4
	v_add_u32_e32 v1, s45, v168
	s_cselect_b32 s5, s13, s44
	s_cselect_b32 s4, s12, s43
	s_add_i32 s43, 0, 0x14000
	ds_read_b128 v[174:177], v1
	ds_read_b128 v[178:181], v1 offset:1024
	ds_read_b128 v[184:187], v1 offset:2048
	ds_read_b128 v[188:191], v1 offset:3072
	v_add_u32_e32 v1, s43, v168
	s_add_i32 m0, s25, 0xc000
	v_lshl_add_u64 v[2:3], v[164:165], 0, s[18:19]
	global_load_lds_dwordx4 v[2:3], off
	s_add_i32 m0, s25, 0xe000
	v_lshl_add_u64 v[2:3], v[166:167], 0, s[18:19]
	global_load_lds_dwordx4 v[2:3], off
	ds_read_b128 v[192:195], v1
	ds_read_b128 v[196:199], v1 offset:1024
	ds_read_b128 v[200:203], v1 offset:2048
	ds_read_b128 v[204:207], v1 offset:3072
	ds_read_b128 v[208:211], v170
	ds_read_b128 v[212:215], v170 offset:1024
	ds_read_b128 v[216:219], v170 offset:2048
	ds_read_b128 v[220:223], v170 offset:3072
	ds_read_b128 v[224:227], v170 offset:4096
	ds_read_b128 v[228:231], v170 offset:5120
	ds_read_b128 v[232:235], v170 offset:6144
	ds_read_b128 v[236:239], v170 offset:7168
	s_setprio 1
	s_waitcnt vmcnt(8) lgkmcnt(0)
	s_barrier
	v_mfma_f32_16x16x32_bf16 v[128:131], v[174:177], v[208:211], v[128:131]
	v_mfma_f32_16x16x32_bf16 v[124:127], v[184:187], v[208:211], v[124:127]
	v_mfma_f32_16x16x32_bf16 v[112:115], v[174:177], v[216:219], v[112:115]
	v_mfma_f32_16x16x32_bf16 v[108:111], v[184:187], v[216:219], v[108:111]
	v_mfma_f32_16x16x32_bf16 v[96:99], v[174:177], v[224:227], v[96:99]
	v_mfma_f32_16x16x32_bf16 v[92:95], v[184:187], v[224:227], v[92:95]
	v_mfma_f32_16x16x32_bf16 v[80:83], v[174:177], v[232:235], v[80:83]
	v_mfma_f32_16x16x32_bf16 v[76:79], v[184:187], v[232:235], v[76:79]
	v_mfma_f32_16x16x32_bf16 v[128:131], v[178:181], v[212:215], v[128:131]
	v_mfma_f32_16x16x32_bf16 v[124:127], v[188:191], v[212:215], v[124:127]
	v_mfma_f32_16x16x32_bf16 v[112:115], v[178:181], v[220:223], v[112:115]
	v_mfma_f32_16x16x32_bf16 v[108:111], v[188:191], v[220:223], v[108:111]
	v_mfma_f32_16x16x32_bf16 v[96:99], v[178:181], v[228:231], v[96:99]
	v_mfma_f32_16x16x32_bf16 v[92:95], v[188:191], v[228:231], v[92:95]
	v_mfma_f32_16x16x32_bf16 v[80:83], v[178:181], v[236:239], v[80:83]
	v_mfma_f32_16x16x32_bf16 v[76:79], v[188:191], v[236:239], v[76:79]
	v_mfma_f32_16x16x32_bf16 v[120:123], v[192:195], v[208:211], v[120:123]
	v_mfma_f32_16x16x32_bf16 v[116:119], v[200:203], v[208:211], v[116:119]
	v_mfma_f32_16x16x32_bf16 v[104:107], v[192:195], v[216:219], v[104:107]
	v_mfma_f32_16x16x32_bf16 v[100:103], v[200:203], v[216:219], v[100:103]
	v_mfma_f32_16x16x32_bf16 v[88:91], v[192:195], v[224:227], v[88:91]
	v_mfma_f32_16x16x32_bf16 v[84:87], v[200:203], v[224:227], v[84:87]
	v_mfma_f32_16x16x32_bf16 v[72:75], v[192:195], v[232:235], v[72:75]
	v_mfma_f32_16x16x32_bf16 v[68:71], v[200:203], v[232:235], v[68:71]
	v_mfma_f32_16x16x32_bf16 v[120:123], v[196:199], v[212:215], v[120:123]
	v_mfma_f32_16x16x32_bf16 v[116:119], v[204:207], v[212:215], v[116:119]
	v_mfma_f32_16x16x32_bf16 v[104:107], v[196:199], v[220:223], v[104:107]
	v_mfma_f32_16x16x32_bf16 v[100:103], v[204:207], v[220:223], v[100:103]
	v_mfma_f32_16x16x32_bf16 v[88:91], v[196:199], v[228:231], v[88:91]
	v_mfma_f32_16x16x32_bf16 v[84:87], v[204:207], v[228:231], v[84:87]
	v_mfma_f32_16x16x32_bf16 v[72:75], v[196:199], v[236:239], v[72:75]
	v_mfma_f32_16x16x32_bf16 v[68:71], v[204:207], v[236:239], v[68:71]
	s_barrier
	s_setprio 0
	s_add_i32 s44, s45, s24
	s_mov_b32 m0, s44
	v_lshl_add_u64 v[240:241], s[4:5], 0, v[134:135]
	global_load_lds_dwordx4 v[240:241], off
	s_add_i32 m0, s44, 0x2000
	s_add_u32 s44, s4, 0x84000
	v_lshl_add_u64 v[242:243], s[4:5], 0, v[158:159]
	s_addc_u32 s45, s5, 0
	s_add_i32 s43, s43, s24
	global_load_lds_dwordx4 v[242:243], off
	s_mov_b32 m0, s43
	v_lshl_add_u64 v[2:3], s[44:45], 0, v[134:135]
	global_load_lds_dwordx4 v[2:3], off
	s_add_i32 m0, s43, 0x2000
	v_lshl_add_u64 v[2:3], s[44:45], 0, v[158:159]
	global_load_lds_dwordx4 v[2:3], off
	s_mov_b32 m0, s25
	v_lshl_add_u64 v[244:245], s[20:21], 0, v[132:133]
	global_load_lds_dwordx4 v[244:245], off
	s_mov_b32 m0, s26
	v_lshl_add_u64 v[246:247], s[20:21], 0, v[156:157]
	global_load_lds_dwordx4 v[246:247], off
	ds_read_b128 v[208:211], v170 offset:16384
	ds_read_b128 v[212:215], v170 offset:17408
	ds_read_b128 v[216:219], v170 offset:18432
	ds_read_b128 v[220:223], v170 offset:19456
	ds_read_b128 v[224:227], v170 offset:20480
	ds_read_b128 v[228:231], v170 offset:21504
	ds_read_b128 v[232:235], v170 offset:22528
	ds_read_b128 v[236:239], v170 offset:23552
	s_setprio 1
	s_waitcnt vmcnt(8) lgkmcnt(0)
	s_barrier
; #define PG8_STAGE(bufoff, gbase, voff) do { _Pragma("unroll") for (int _i = 0; _i < 2; ++_i) \
;         __builtin_amdgcn_global_load_lds((const unsigned*)((const char*)(gbase) + (voff)[_i]), (LAS unsigned*)(lds + (bufoff) + ldsw + _i * 8192), 16, 0, 0); } while (0)
; #define PG8_LDA(dst, b, h) do { _Pragma("unroll") for (int m = 0; m < 4; ++m) _Pragma("unroll") for (int k = 0; k < 2; ++k) dst[m][k] = *(const LAS bf16x8*)(lds + PG8_SA(b, h) + aoff + m * 2048 + k * 1024); } while (0)
; #define PG8_LDB(dst, b, h) do { _Pragma("unroll") for (int n = 0; n < 2; ++n) _Pragma("unroll") for (int k = 0; k < 2; ++k) dst[n][k] = *(const LAS bf16x8*)(lds + PG8_SB(b, h) + boff + n * 2048 + k * 1024); } while (0)
; #define PG8_MMA(ai, bj, At, Bt) do { __builtin_amdgcn_s_setprio(1); _Pragma("unroll") for (int m = 0; m < 4; ++m) _Pragma("unroll") for (int n = 0; n < 2; ++n) _Pragma("unroll") for (int k = 0; k < 2; ++k) \
;         acc[ai][bj][m][n] = __builtin_amdgcn_mfma_f32_16x16x32_bf16(Bt[n][k], At[m][k], acc[ai][bj][m][n], 0, 0, 0); __builtin_amdgcn_s_setprio(0); } while (0)
; #define PG8_WAIT_V(n) asm volatile("s_waitcnt vmcnt(" #n ")" ::: "memory")
; #define PG8_WAIT_L(n) asm volatile("s_waitcnt lgkmcnt(" #n ")" ::: "memory")
; #define PG8_BAR __builtin_amdgcn_s_barrier()
; #define PG8_SCHED __builtin_amdgcn_sched_barrier(0)
; template <class Epi, bool ALIGN_EPI = PG8_ALIGN, bool SP2 = PG8_SP2>
; __device__ __forceinline__ void gemm_phase(LAS uchar* lds, const Gemm g, const StaticOrder& S, const Epi& E) {
;     ...
;             PG8_WAIT_V(8); PG8_WAIT_L(0); PG8_BAR; PG8_MMA(1, 0, At, B0); PG8_MMA(1, 1, At, B1); PG8_BAR; PG8_SCHED;
;             PG8_LDB(B0, 1, 0); PG8_LDB(B1, 1, 1); PG8_SCHED; PG8_LDA(At, 1, 0); PG8_STAGE(PG8_SA(0, 1), a2 + hstepA, voffA);
;             PG8_WAIT_V(8); PG8_WAIT_L(0); PG8_BAR; PG8_MMA(0, 0, At, B0); PG8_MMA(0, 1, At, B1); PG8_BAR; PG8_SCHED;
	v_mfma_f32_16x16x32_bf16 v[64:67], v[174:177], v[208:211], v[64:67]
	v_mfma_f32_16x16x32_bf16 v[60:63], v[184:187], v[208:211], v[60:63]
	v_mfma_f32_16x16x32_bf16 v[48:51], v[174:177], v[216:219], v[48:51]
	v_mfma_f32_16x16x32_bf16 v[44:47], v[184:187], v[216:219], v[44:47]
	v_mfma_f32_16x16x32_bf16 v[32:35], v[174:177], v[224:227], v[32:35]
	v_mfma_f32_16x16x32_bf16 v[28:31], v[184:187], v[224:227], v[28:31]
	v_mfma_f32_16x16x32_bf16 v[16:19], v[174:177], v[232:235], v[16:19]
	v_mfma_f32_16x16x32_bf16 v[12:15], v[184:187], v[232:235], v[12:15]
	v_mfma_f32_16x16x32_bf16 v[64:67], v[178:181], v[212:215], v[64:67]
	v_mfma_f32_16x16x32_bf16 v[60:63], v[188:191], v[212:215], v[60:63]
	v_mfma_f32_16x16x32_bf16 v[48:51], v[178:181], v[220:223], v[48:51]
	v_mfma_f32_16x16x32_bf16 v[44:47], v[188:191], v[220:223], v[44:47]
	v_mfma_f32_16x16x32_bf16 v[32:35], v[178:181], v[228:231], v[32:35]
	v_mfma_f32_16x16x32_bf16 v[28:31], v[188:191], v[228:231], v[28:31]
	v_mfma_f32_16x16x32_bf16 v[16:19], v[178:181], v[236:239], v[16:19]
	v_mfma_f32_16x16x32_bf16 v[12:15], v[188:191], v[236:239], v[12:15]
	v_mfma_f32_16x16x32_bf16 v[56:59], v[192:195], v[208:211], v[56:59]
	v_mfma_f32_16x16x32_bf16 v[52:55], v[200:203], v[208:211], v[52:55]
	v_mfma_f32_16x16x32_bf16 v[40:43], v[192:195], v[216:219], v[40:43]
	v_mfma_f32_16x16x32_bf16 v[36:39], v[200:203], v[216:219], v[36:39]
	v_mfma_f32_16x16x32_bf16 v[24:27], v[192:195], v[224:227], v[24:27]
	v_mfma_f32_16x16x32_bf16 v[20:23], v[200:203], v[224:227], v[20:23]
	v_mfma_f32_16x16x32_bf16 v[8:11], v[192:195], v[232:235], v[8:11]
	v_mfma_f32_16x16x32_bf16 v[2:5], v[200:203], v[232:235], v[4:7]
	v_mfma_f32_16x16x32_bf16 v[56:59], v[196:199], v[212:215], v[56:59]
	v_mfma_f32_16x16x32_bf16 v[52:55], v[204:207], v[212:215], v[52:55]
	v_mfma_f32_16x16x32_bf16 v[40:43], v[196:199], v[220:223], v[40:43]
	v_mfma_f32_16x16x32_bf16 v[36:39], v[204:207], v[220:223], v[36:39]
	v_mfma_f32_16x16x32_bf16 v[24:27], v[196:199], v[228:231], v[24:27]
	v_mfma_f32_16x16x32_bf16 v[20:23], v[204:207], v[228:231], v[20:23]
	v_mfma_f32_16x16x32_bf16 v[8:11], v[196:199], v[236:239], v[8:11]
	v_mfma_f32_16x16x32_bf16 v[2:5], v[204:207], v[236:239], v[2:5]
	s_barrier
	s_setprio 0
	s_add_i32 s43, 0, 0x18000
	v_add_u32_e32 v1, s43, v168
	s_add_i32 s44, 0, 0x1c000
	ds_read_b128 v[174:177], v1
	ds_read_b128 v[178:181], v1 offset:1024
	ds_read_b128 v[184:187], v1 offset:2048
	ds_read_b128 v[188:191], v1 offset:3072
	v_add_u32_e32 v1, s44, v168
	s_add_u32 s20, s20, 0x184000
	s_addc_u32 s21, s21, 0
	s_mov_b32 m0, s27
	v_lshl_add_u64 v[6:7], s[20:21], 0, v[132:133]
	global_load_lds_dwordx4 v[6:7], off
	s_mov_b32 m0, s28
	v_lshl_add_u64 v[6:7], s[20:21], 0, v[156:157]
	global_load_lds_dwordx4 v[6:7], off
	ds_read_b128 v[192:195], v1
	ds_read_b128 v[196:199], v1 offset:1024
	ds_read_b128 v[200:203], v1 offset:2048
	ds_read_b128 v[204:207], v1 offset:3072
	ds_read_b128 v[208:211], v170 offset:32768
	ds_read_b128 v[212:215], v170 offset:33792
	ds_read_b128 v[216:219], v170 offset:34816
	ds_read_b128 v[220:223], v170 offset:35840
	ds_read_b128 v[224:227], v170 offset:36864
	ds_read_b128 v[228:231], v170 offset:37888
	ds_read_b128 v[232:235], v170 offset:38912
	ds_read_b128 v[236:239], v170 offset:39936
	s_setprio 1
	s_waitcnt vmcnt(8) lgkmcnt(0)
	s_barrier
	v_mfma_f32_16x16x32_bf16 v[128:131], v[174:177], v[208:211], v[128:131]
	v_mfma_f32_16x16x32_bf16 v[124:127], v[184:187], v[208:211], v[124:127]
	v_mfma_f32_16x16x32_bf16 v[112:115], v[174:177], v[216:219], v[112:115]
	v_mfma_f32_16x16x32_bf16 v[108:111], v[184:187], v[216:219], v[108:111]
	v_mfma_f32_16x16x32_bf16 v[96:99], v[174:177], v[224:227], v[96:99]
	v_mfma_f32_16x16x32_bf16 v[92:95], v[184:187], v[224:227], v[92:95]
	v_mfma_f32_16x16x32_bf16 v[80:83], v[174:177], v[232:235], v[80:83]
	v_mfma_f32_16x16x32_bf16 v[76:79], v[184:187], v[232:235], v[76:79]
	v_mfma_f32_16x16x32_bf16 v[128:131], v[178:181], v[212:215], v[128:131]
	v_mfma_f32_16x16x32_bf16 v[124:127], v[188:191], v[212:215], v[124:127]
	v_mfma_f32_16x16x32_bf16 v[112:115], v[178:181], v[220:223], v[112:115]
	v_mfma_f32_16x16x32_bf16 v[108:111], v[188:191], v[220:223], v[108:111]
	v_mfma_f32_16x16x32_bf16 v[96:99], v[178:181], v[228:231], v[96:99]
	v_mfma_f32_16x16x32_bf16 v[92:95], v[188:191], v[228:231], v[92:95]
	v_mfma_f32_16x16x32_bf16 v[80:83], v[178:181], v[236:239], v[80:83]
	v_mfma_f32_16x16x32_bf16 v[76:79], v[188:191], v[236:239], v[76:79]
	v_mfma_f32_16x16x32_bf16 v[120:123], v[192:195], v[208:211], v[120:123]
	v_mfma_f32_16x16x32_bf16 v[116:119], v[200:203], v[208:211], v[116:119]
	v_mfma_f32_16x16x32_bf16 v[104:107], v[192:195], v[216:219], v[104:107]
	v_mfma_f32_16x16x32_bf16 v[100:103], v[200:203], v[216:219], v[100:103]
	v_mfma_f32_16x16x32_bf16 v[88:91], v[192:195], v[224:227], v[88:91]
	v_mfma_f32_16x16x32_bf16 v[84:87], v[200:203], v[224:227], v[84:87]
	v_mfma_f32_16x16x32_bf16 v[72:75], v[192:195], v[232:235], v[72:75]
	v_mfma_f32_16x16x32_bf16 v[68:71], v[200:203], v[232:235], v[68:71]
	v_mfma_f32_16x16x32_bf16 v[120:123], v[196:199], v[212:215], v[120:123]
	v_mfma_f32_16x16x32_bf16 v[116:119], v[204:207], v[212:215], v[116:119]
	v_mfma_f32_16x16x32_bf16 v[104:107], v[196:199], v[220:223], v[104:107]
	v_mfma_f32_16x16x32_bf16 v[100:103], v[204:207], v[220:223], v[100:103]
	v_mfma_f32_16x16x32_bf16 v[88:91], v[196:199], v[228:231], v[88:91]
	v_mfma_f32_16x16x32_bf16 v[84:87], v[204:207], v[228:231], v[84:87]
	v_mfma_f32_16x16x32_bf16 v[72:75], v[196:199], v[236:239], v[72:75]
	v_mfma_f32_16x16x32_bf16 v[68:71], v[204:207], v[236:239], v[68:71]
	s_barrier
; #define LAS __attribute__((address_space(3)))
; #define PG8_STAGE(bufoff, gbase, voff) do { _Pragma("unroll") for (int _i = 0; _i < 2; ++_i) \
;         __builtin_amdgcn_global_load_lds((const unsigned*)((const char*)(gbase) + (voff)[_i]), (LAS unsigned*)(lds + (bufoff) + ldsw + _i * 8192), 16, 0, 0); } while (0)
; #define PG8_LDA(dst, b, h) do { _Pragma("unroll") for (int m = 0; m < 4; ++m) _Pragma("unroll") for (int k = 0; k < 2; ++k) dst[m][k] = *(const LAS bf16x8*)(lds + PG8_SA(b, h) + aoff + m * 2048 + k * 1024); } while (0)
; #define PG8_MMA(ai, bj, At, Bt) do { __builtin_amdgcn_s_setprio(1); _Pragma("unroll") for (int m = 0; m < 4; ++m) _Pragma("unroll") for (int n = 0; n < 2; ++n) _Pragma("unroll") for (int k = 0; k < 2; ++k) \
;         acc[ai][bj][m][n] = __builtin_amdgcn_mfma_f32_16x16x32_bf16(Bt[n][k], At[m][k], acc[ai][bj][m][n], 0, 0, 0); __builtin_amdgcn_s_setprio(0); } while (0)
; #define PG8_WAIT_V(n) asm volatile("s_waitcnt vmcnt(" #n ")" ::: "memory")
; #define PG8_WAIT_L(n) asm volatile("s_waitcnt lgkmcnt(" #n ")" ::: "memory")
; #define PG8_BAR __builtin_amdgcn_s_barrier()
; #define PG8_SCHED __builtin_amdgcn_sched_barrier(0)
; template <class Epi, bool ALIGN_EPI = PG8_ALIGN, bool SP2 = PG8_SP2>
; __device__ __forceinline__ void gemm_phase(LAS uchar* lds, const Gemm g, const StaticOrder& S, const Epi& E) {
;     ...
;         for (int tb = 0; tb < nt; tb += tblk) {
;         if constexpr (Epi::GROUPS) { if (tb > 0) {
;             const LAS float* rt = (const LAS float*)(lds + LDS_RT) + ((ui & 1) * 256 + wr * 64 + fr) * 8 + ((tb >> 2) - 1);
; #pragma unroll
;             for (int a = 0; a < 2; ++a)
; #pragma unroll
;                 for (int m = 0; m < 4; ++m) { const float f = rt[(a * 128 + m * 16) * 8];
; #pragma unroll
;                     for (int b = 0; b < 2; ++b)
; #pragma unroll
;                         for (int n = 0; n < 2; ++n) acc[a][b][m][n] *= f; } } }
; #pragma unroll 1
;         for (int t = tb; t < tb + tblk; t += 2) {
;     ...
;             PG8_WAIT_V(8); PG8_WAIT_L(0); PG8_BAR; PG8_MMA(0, 0, At, B0); PG8_MMA(0, 1, At, B1); PG8_BAR; PG8_SCHED;
;             PG8_LDA(At, 1, 1); PG8_STAGE(PG8_SB(1, 0), b3, voffB); PG8_STAGE(PG8_SB(1, 1), b3 + hstepB, voffB); PG8_STAGE(PG8_SA(1, 0), a3, voffA);
;             PG8_WAIT_V(8); PG8_WAIT_L(0); PG8_BAR; PG8_MMA(1, 0, At, B0); PG8_MMA(1, 1, At, B1); PG8_BAR; PG8_SCHED;
	s_setprio 0
	s_add_i32 s20, s43, s24
	s_mov_b32 m0, s20
	v_lshl_add_u64 v[6:7], v[240:241], 0, s[84:85]
	global_load_lds_dwordx4 v[6:7], off
	s_add_i32 m0, s20, 0x2000
	s_add_u32 s4, s4, 0x84080
	v_lshl_add_u64 v[6:7], v[242:243], 0, s[84:85]
	s_addc_u32 s5, s5, 0
	s_add_i32 s20, s44, s24
	global_load_lds_dwordx4 v[6:7], off
	s_mov_b32 m0, s20
	v_lshl_add_u64 v[6:7], s[4:5], 0, v[134:135]
	global_load_lds_dwordx4 v[6:7], off
	s_add_i32 m0, s20, 0x2000
	v_lshl_add_u64 v[6:7], s[4:5], 0, v[158:159]
	global_load_lds_dwordx4 v[6:7], off
	s_mov_b32 m0, s29
	v_lshl_add_u64 v[6:7], v[244:245], 0, s[84:85]
	global_load_lds_dwordx4 v[6:7], off
	s_mov_b32 m0, s30
	v_lshl_add_u64 v[6:7], v[246:247], 0, s[84:85]
	global_load_lds_dwordx4 v[6:7], off
	ds_read_b128 v[208:211], v170 offset:49152
	ds_read_b128 v[212:215], v170 offset:50176
	ds_read_b128 v[216:219], v170 offset:51200
	ds_read_b128 v[220:223], v170 offset:52224
	ds_read_b128 v[224:227], v170 offset:53248
	ds_read_b128 v[228:231], v170 offset:54272
	ds_read_b128 v[232:235], v170 offset:55296
	ds_read_b128 v[236:239], v170 offset:56320
	s_setprio 1
	s_waitcnt vmcnt(8) lgkmcnt(0)
	s_barrier
	v_mfma_f32_16x16x32_bf16 v[64:67], v[174:177], v[208:211], v[64:67]
	v_mfma_f32_16x16x32_bf16 v[60:63], v[184:187], v[208:211], v[60:63]
	v_mfma_f32_16x16x32_bf16 v[48:51], v[174:177], v[216:219], v[48:51]
	v_mfma_f32_16x16x32_bf16 v[44:47], v[184:187], v[216:219], v[44:47]
	v_mfma_f32_16x16x32_bf16 v[32:35], v[174:177], v[224:227], v[32:35]
	v_mfma_f32_16x16x32_bf16 v[28:31], v[184:187], v[224:227], v[28:31]
	v_mfma_f32_16x16x32_bf16 v[16:19], v[174:177], v[232:235], v[16:19]
	v_mfma_f32_16x16x32_bf16 v[12:15], v[184:187], v[232:235], v[12:15]
	v_mfma_f32_16x16x32_bf16 v[64:67], v[178:181], v[212:215], v[64:67]
	v_mfma_f32_16x16x32_bf16 v[60:63], v[188:191], v[212:215], v[60:63]
	v_mfma_f32_16x16x32_bf16 v[48:51], v[178:181], v[220:223], v[48:51]
	v_mfma_f32_16x16x32_bf16 v[44:47], v[188:191], v[220:223], v[44:47]
	v_mfma_f32_16x16x32_bf16 v[32:35], v[178:181], v[228:231], v[32:35]
	v_mfma_f32_16x16x32_bf16 v[28:31], v[188:191], v[228:231], v[28:31]
	v_mfma_f32_16x16x32_bf16 v[16:19], v[178:181], v[236:239], v[16:19]
	v_mfma_f32_16x16x32_bf16 v[12:15], v[188:191], v[236:239], v[12:15]
	v_mfma_f32_16x16x32_bf16 v[56:59], v[192:195], v[208:211], v[56:59]
	v_mfma_f32_16x16x32_bf16 v[52:55], v[200:203], v[208:211], v[52:55]
	v_mfma_f32_16x16x32_bf16 v[40:43], v[192:195], v[216:219], v[40:43]
	v_mfma_f32_16x16x32_bf16 v[36:39], v[200:203], v[216:219], v[36:39]
	v_mfma_f32_16x16x32_bf16 v[24:27], v[192:195], v[224:227], v[24:27]
	v_mfma_f32_16x16x32_bf16 v[20:23], v[200:203], v[224:227], v[20:23]
	v_mfma_f32_16x16x32_bf16 v[6:9], v[192:195], v[232:235], v[8:11]
	v_mfma_f32_16x16x32_bf16 v[2:5], v[200:203], v[232:235], v[2:5]
	v_mfma_f32_16x16x32_bf16 v[56:59], v[196:199], v[212:215], v[56:59]
	v_mfma_f32_16x16x32_bf16 v[52:55], v[204:207], v[212:215], v[52:55]
	v_mfma_f32_16x16x32_bf16 v[40:43], v[196:199], v[220:223], v[40:43]
	v_mfma_f32_16x16x32_bf16 v[36:39], v[204:207], v[220:223], v[36:39]
	v_mfma_f32_16x16x32_bf16 v[24:27], v[196:199], v[228:231], v[24:27]
	v_mfma_f32_16x16x32_bf16 v[20:23], v[204:207], v[228:231], v[20:23]
	v_mfma_f32_16x16x32_bf16 v[8:11], v[196:199], v[236:239], v[6:9]
	v_mfma_f32_16x16x32_bf16 v[4:7], v[204:207], v[236:239], v[2:5]
	s_barrier
	s_setprio 0
	s_add_u32 s18, s18, 0x100
	s_addc_u32 s19, s19, 0
	s_cmp_ge_u32 s42, s41
	s_cbranch_scc0 .LBB0_580
	s_add_u32 s16, s16, 0x200
	s_addc_u32 s17, s17, 0
	s_cmp_lt_u32 s40, 28
	s_cbranch_scc0 .LBB0_583
	s_mov_b32 s40, s41
	s_cmp_eq_u32 s40, 0
	s_cbranch_scc0 .LBB0_578
	s_branch .LBB0_579

; #define PG8_STAGE(bufoff, gbase, voff) do { _Pragma("unroll") for (int _i = 0; _i < 2; ++_i) \
;         __builtin_amdgcn_global_load_lds((const unsigned*)((const char*)(gbase) + (voff)[_i]), (LAS unsigned*)(lds + (bufoff) + ldsw + _i * 8192), 16, 0, 0); } while (0)
; #define PG8_LDA(dst, b, h) do { _Pragma("unroll") for (int m = 0; m < 4; ++m) _Pragma("unroll") for (int k = 0; k < 2; ++k) dst[m][k] = *(const LAS bf16x8*)(lds + PG8_SA(b, h) + aoff + m * 2048 + k * 1024); } while (0)
; #define PG8_LDB(dst, b, h) do { _Pragma("unroll") for (int n = 0; n < 2; ++n) _Pragma("unroll") for (int k = 0; k < 2; ++k) dst[n][k] = *(const LAS bf16x8*)(lds + PG8_SB(b, h) + boff + n * 2048 + k * 1024); } while (0)
; #define PG8_MMA(ai, bj, At, Bt) do { __builtin_amdgcn_s_setprio(1); _Pragma("unroll") for (int m = 0; m < 4; ++m) _Pragma("unroll") for (int n = 0; n < 2; ++n) _Pragma("unroll") for (int k = 0; k < 2; ++k) \
;         acc[ai][bj][m][n] = __builtin_amdgcn_mfma_f32_16x16x32_bf16(Bt[n][k], At[m][k], acc[ai][bj][m][n], 0, 0, 0); __builtin_amdgcn_s_setprio(0); } while (0)
; #define PG8_WAIT_V(n) asm volatile("s_waitcnt vmcnt(" #n ")" ::: "memory")
; #define PG8_WAIT_L(n) asm volatile("s_waitcnt lgkmcnt(" #n ")" ::: "memory")
; #define PG8_BAR __builtin_amdgcn_s_barrier()
; template <class Epi, bool ALIGN_EPI = PG8_ALIGN, bool SP2 = PG8_SP2>
; __device__ __forceinline__ void gemm_phase(LAS uchar* lds, const Gemm g, const StaticOrder& S, const Epi& E) {
;     ...
;         for (int t = tb; t < tb + tblk; t += 2) {
;             const bool last = (t == nt - 2);
;             const char* a1 = cA + (size_t)(t + 1) * kstep;
;             const char* a2 = last ? nA : cA + (size_t)(t + 2) * kstep; const char* b2 = last ? nB : cB + (size_t)(t + 2) * kstep;
;             const char* a3 = a2 + kstep; const char* b3 = b2 + kstep;
;             if constexpr (SP2) {
;             PG8_LDB(B0, 0, 0); PG8_LDB(B1, 0, 1); PG8_SCHED; PG8_LDA(At, 0, 0); PG8_STAGE(PG8_SA(1, 1), a1 + hstepA, voffA);
;             PG8_WAIT_V(8); PG8_WAIT_L(0); PG8_BAR; PG8_MMA(0, 0, At, B0); PG8_MMA(0, 1, At, B1); PG8_BAR; PG8_SCHED;
;             PG8_LDA(At, 0, 1); PG8_STAGE(PG8_SB(0, 0), b2, voffB); PG8_STAGE(PG8_SB(0, 1), b2 + hstepB, voffB); PG8_STAGE(PG8_SA(0, 0), a2, voffA);
;             PG8_WAIT_V(8); PG8_WAIT_L(0); PG8_BAR; PG8_MMA(1, 0, At, B0); PG8_MMA(1, 1, At, B1); PG8_BAR; PG8_SCHED;
.LBB0_668:
	s_add_u32 s36, s14, 0x100
	s_addc_u32 s37, s15, 0
	s_mov_b32 s38, -2
	s_add_u32 s14, s12, 0x100
	s_addc_u32 s15, s13, 0
	s_add_i32 s39, 0, 0x10000
	s_cmp_eq_u32 s38, 12
	s_cselect_b32 s19, s5, s15
	s_cselect_b32 s18, s4, s14
	s_cselect_b32 s17, s11, s37
	s_cselect_b32 s16, s10, s36
	s_add_i32 s40, 0, 0x14000
	v_add_u32_e32 v174, s39, v139
	v_add_u32_e32 v192, s40, v139
	s_add_i32 m0, s23, 0xc000
	v_lshl_add_u64 v[228:229], s[12:13], 0, v[156:157]
	global_load_lds_dwordx4 v[228:229], off
	s_add_i32 m0, s23, 0xe000
	v_lshl_add_u64 v[228:229], s[12:13], 0, v[158:159]
	global_load_lds_dwordx4 v[228:229], off
	ds_read_b128 v[160:163], v174
	ds_read_b128 v[164:167], v174 offset:1024
	ds_read_b128 v[168:171], v174 offset:2048
	ds_read_b128 v[174:177], v174 offset:3072
	ds_read_b128 v[178:181], v192
	ds_read_b128 v[184:187], v192 offset:1024
	ds_read_b128 v[188:191], v192 offset:2048
	ds_read_b128 v[192:195], v192 offset:3072
	ds_read_b128 v[196:199], v173
	ds_read_b128 v[200:203], v173 offset:1024
	ds_read_b128 v[204:207], v173 offset:2048
	ds_read_b128 v[208:211], v173 offset:3072
	ds_read_b128 v[212:215], v173 offset:4096
	ds_read_b128 v[216:219], v173 offset:5120
	ds_read_b128 v[220:223], v173 offset:6144
	ds_read_b128 v[224:227], v173 offset:7168
	s_setprio 1
	s_waitcnt vmcnt(8) lgkmcnt(0)
	s_barrier
	v_mfma_f32_16x16x32_bf16 v[126:129], v[160:163], v[196:199], 0
	v_mfma_f32_16x16x32_bf16 v[122:125], v[168:171], v[196:199], 0
	v_mfma_f32_16x16x32_bf16 v[118:121], v[160:163], v[204:207], 0
	v_mfma_f32_16x16x32_bf16 v[110:113], v[168:171], v[204:207], 0
	v_mfma_f32_16x16x32_bf16 v[102:105], v[160:163], v[212:215], 0
	v_mfma_f32_16x16x32_bf16 v[94:97], v[168:171], v[212:215], 0
	v_mfma_f32_16x16x32_bf16 v[86:89], v[160:163], v[220:223], 0
	v_mfma_f32_16x16x32_bf16 v[78:81], v[168:171], v[220:223], 0
	v_mfma_f32_16x16x32_bf16 v[126:129], v[164:167], v[200:203], v[126:129]
	v_mfma_f32_16x16x32_bf16 v[122:125], v[174:177], v[200:203], v[122:125]
	v_mfma_f32_16x16x32_bf16 v[118:121], v[164:167], v[208:211], v[118:121]
	v_mfma_f32_16x16x32_bf16 v[110:113], v[174:177], v[208:211], v[110:113]
	v_mfma_f32_16x16x32_bf16 v[102:105], v[164:167], v[216:219], v[102:105]
	v_mfma_f32_16x16x32_bf16 v[94:97], v[174:177], v[216:219], v[94:97]
	v_mfma_f32_16x16x32_bf16 v[86:89], v[164:167], v[224:227], v[86:89]
	v_mfma_f32_16x16x32_bf16 v[78:81], v[174:177], v[224:227], v[78:81]
	v_mfma_f32_16x16x32_bf16 v[114:117], v[178:181], v[196:199], 0
	v_mfma_f32_16x16x32_bf16 v[106:109], v[188:191], v[196:199], 0
	v_mfma_f32_16x16x32_bf16 v[98:101], v[178:181], v[204:207], 0
	v_mfma_f32_16x16x32_bf16 v[90:93], v[188:191], v[204:207], 0
	v_mfma_f32_16x16x32_bf16 v[82:85], v[178:181], v[212:215], 0
	v_mfma_f32_16x16x32_bf16 v[74:77], v[188:191], v[212:215], 0
	v_mfma_f32_16x16x32_bf16 v[70:73], v[178:181], v[220:223], 0
	v_mfma_f32_16x16x32_bf16 v[66:69], v[188:191], v[220:223], 0
	v_mfma_f32_16x16x32_bf16 v[114:117], v[184:187], v[200:203], v[114:117]
	v_mfma_f32_16x16x32_bf16 v[106:109], v[192:195], v[200:203], v[106:109]
	v_mfma_f32_16x16x32_bf16 v[98:101], v[184:187], v[208:211], v[98:101]
	v_mfma_f32_16x16x32_bf16 v[90:93], v[192:195], v[208:211], v[90:93]
	v_mfma_f32_16x16x32_bf16 v[82:85], v[184:187], v[216:219], v[82:85]
	v_mfma_f32_16x16x32_bf16 v[74:77], v[192:195], v[216:219], v[74:77]
	v_mfma_f32_16x16x32_bf16 v[70:73], v[184:187], v[224:227], v[70:73]
	v_mfma_f32_16x16x32_bf16 v[66:69], v[192:195], v[224:227], v[66:69]
	s_barrier
	s_setprio 0
	s_add_i32 s12, s39, s21
	s_mov_b32 m0, s12
	v_lshl_add_u64 v[228:229], s[16:17], 0, v[134:135]
	global_load_lds_dwordx4 v[228:229], off
	s_add_i32 m0, s12, 0x2000
	s_add_u32 s12, s16, 0x44000
	v_lshl_add_u64 v[230:231], s[16:17], 0, v[130:131]
	s_addc_u32 s13, s17, 0
	s_add_i32 s39, s40, s21
	global_load_lds_dwordx4 v[230:231], off
	s_mov_b32 m0, s39
	v_lshl_add_u64 v[232:233], s[12:13], 0, v[134:135]
	global_load_lds_dwordx4 v[232:233], off
	s_add_i32 m0, s39, 0x2000
	v_lshl_add_u64 v[232:233], s[12:13], 0, v[130:131]
	global_load_lds_dwordx4 v[232:233], off
	s_mov_b32 m0, s23
	v_lshl_add_u64 v[232:233], s[18:19], 0, v[152:153]
	global_load_lds_dwordx4 v[232:233], off
	s_mov_b32 m0, s24
	v_lshl_add_u64 v[234:235], s[18:19], 0, v[132:133]
	global_load_lds_dwordx4 v[234:235], off
	ds_read_b128 v[196:199], v173 offset:16384
	ds_read_b128 v[200:203], v173 offset:17408
	ds_read_b128 v[204:207], v173 offset:18432
	ds_read_b128 v[208:211], v173 offset:19456
	ds_read_b128 v[212:215], v173 offset:20480
	ds_read_b128 v[216:219], v173 offset:21504
	ds_read_b128 v[220:223], v173 offset:22528
	ds_read_b128 v[224:227], v173 offset:23552
	s_setprio 1
	s_waitcnt vmcnt(8) lgkmcnt(0)
	s_barrier
; #define PG8_STAGE(bufoff, gbase, voff) do { _Pragma("unroll") for (int _i = 0; _i < 2; ++_i) \
;         __builtin_amdgcn_global_load_lds((const unsigned*)((const char*)(gbase) + (voff)[_i]), (LAS unsigned*)(lds + (bufoff) + ldsw + _i * 8192), 16, 0, 0); } while (0)
; #define PG8_LDA(dst, b, h) do { _Pragma("unroll") for (int m = 0; m < 4; ++m) _Pragma("unroll") for (int k = 0; k < 2; ++k) dst[m][k] = *(const LAS bf16x8*)(lds + PG8_SA(b, h) + aoff + m * 2048 + k * 1024); } while (0)
; #define PG8_LDB(dst, b, h) do { _Pragma("unroll") for (int n = 0; n < 2; ++n) _Pragma("unroll") for (int k = 0; k < 2; ++k) dst[n][k] = *(const LAS bf16x8*)(lds + PG8_SB(b, h) + boff + n * 2048 + k * 1024); } while (0)
; #define PG8_MMA(ai, bj, At, Bt) do { __builtin_amdgcn_s_setprio(1); _Pragma("unroll") for (int m = 0; m < 4; ++m) _Pragma("unroll") for (int n = 0; n < 2; ++n) _Pragma("unroll") for (int k = 0; k < 2; ++k) \
;         acc[ai][bj][m][n] = __builtin_amdgcn_mfma_f32_16x16x32_bf16(Bt[n][k], At[m][k], acc[ai][bj][m][n], 0, 0, 0); __builtin_amdgcn_s_setprio(0); } while (0)
; #define PG8_WAIT_V(n) asm volatile("s_waitcnt vmcnt(" #n ")" ::: "memory")
; #define PG8_WAIT_L(n) asm volatile("s_waitcnt lgkmcnt(" #n ")" ::: "memory")
; #define PG8_BAR __builtin_amdgcn_s_barrier()
; #define PG8_SCHED __builtin_amdgcn_sched_barrier(0)
; template <class Epi, bool ALIGN_EPI = PG8_ALIGN, bool SP2 = PG8_SP2>
; __device__ __forceinline__ void gemm_phase(LAS uchar* lds, const Gemm g, const StaticOrder& S, const Epi& E) {
;     ...
;             PG8_WAIT_V(8); PG8_WAIT_L(0); PG8_BAR; PG8_MMA(1, 0, At, B0); PG8_MMA(1, 1, At, B1); PG8_BAR; PG8_SCHED;
;             PG8_LDB(B0, 1, 0); PG8_LDB(B1, 1, 1); PG8_SCHED; PG8_LDA(At, 1, 0); PG8_STAGE(PG8_SA(0, 1), a2 + hstepA, voffA);
;             PG8_WAIT_V(8); PG8_WAIT_L(0); PG8_BAR; PG8_MMA(0, 0, At, B0); PG8_MMA(0, 1, At, B1); PG8_BAR; PG8_SCHED;
	v_mfma_f32_16x16x32_bf16 v[62:65], v[160:163], v[196:199], 0
	v_mfma_f32_16x16x32_bf16 v[58:61], v[168:171], v[196:199], 0
	v_mfma_f32_16x16x32_bf16 v[54:57], v[160:163], v[204:207], 0
	v_mfma_f32_16x16x32_bf16 v[46:49], v[168:171], v[204:207], 0
	v_mfma_f32_16x16x32_bf16 v[38:41], v[160:163], v[212:215], 0
	v_mfma_f32_16x16x32_bf16 v[30:33], v[168:171], v[212:215], 0
	v_mfma_f32_16x16x32_bf16 v[22:25], v[160:163], v[220:223], 0
	v_mfma_f32_16x16x32_bf16 v[14:17], v[168:171], v[220:223], 0
	v_mfma_f32_16x16x32_bf16 v[62:65], v[164:167], v[200:203], v[62:65]
	v_mfma_f32_16x16x32_bf16 v[58:61], v[174:177], v[200:203], v[58:61]
	v_mfma_f32_16x16x32_bf16 v[54:57], v[164:167], v[208:211], v[54:57]
	v_mfma_f32_16x16x32_bf16 v[46:49], v[174:177], v[208:211], v[46:49]
	v_mfma_f32_16x16x32_bf16 v[38:41], v[164:167], v[216:219], v[38:41]
	v_mfma_f32_16x16x32_bf16 v[30:33], v[174:177], v[216:219], v[30:33]
	v_mfma_f32_16x16x32_bf16 v[22:25], v[164:167], v[224:227], v[22:25]
	v_mfma_f32_16x16x32_bf16 v[14:17], v[174:177], v[224:227], v[14:17]
	v_mfma_f32_16x16x32_bf16 v[50:53], v[178:181], v[196:199], 0
	v_mfma_f32_16x16x32_bf16 v[42:45], v[188:191], v[196:199], 0
	v_mfma_f32_16x16x32_bf16 v[34:37], v[178:181], v[204:207], 0
	v_mfma_f32_16x16x32_bf16 v[26:29], v[188:191], v[204:207], 0
	v_mfma_f32_16x16x32_bf16 v[18:21], v[178:181], v[212:215], 0
	v_mfma_f32_16x16x32_bf16 v[10:13], v[188:191], v[212:215], 0
	v_mfma_f32_16x16x32_bf16 v[6:9], v[178:181], v[220:223], 0
	v_mfma_f32_16x16x32_bf16 v[2:5], v[188:191], v[220:223], 0
	v_mfma_f32_16x16x32_bf16 v[50:53], v[184:187], v[200:203], v[50:53]
	v_mfma_f32_16x16x32_bf16 v[42:45], v[192:195], v[200:203], v[42:45]
	v_mfma_f32_16x16x32_bf16 v[34:37], v[184:187], v[208:211], v[34:37]
	v_mfma_f32_16x16x32_bf16 v[26:29], v[192:195], v[208:211], v[26:29]
	v_mfma_f32_16x16x32_bf16 v[18:21], v[184:187], v[216:219], v[18:21]
	v_mfma_f32_16x16x32_bf16 v[10:13], v[192:195], v[216:219], v[10:13]
	v_mfma_f32_16x16x32_bf16 v[6:9], v[184:187], v[224:227], v[6:9]
	v_mfma_f32_16x16x32_bf16 v[2:5], v[192:195], v[224:227], v[2:5]
	s_barrier
	s_setprio 0
	s_add_i32 s39, 0, 0x18000
	s_add_i32 s40, 0, 0x1c000
	v_add_u32_e32 v174, s39, v139
	v_add_u32_e32 v192, s40, v139
	s_add_u32 s12, s18, 0x44000
	s_addc_u32 s13, s19, 0
	s_mov_b32 m0, s25
	v_lshl_add_u64 v[236:237], s[12:13], 0, v[152:153]
	global_load_lds_dwordx4 v[236:237], off
	s_mov_b32 m0, s26
	v_lshl_add_u64 v[236:237], s[12:13], 0, v[132:133]
	global_load_lds_dwordx4 v[236:237], off
	ds_read_b128 v[160:163], v174
	ds_read_b128 v[164:167], v174 offset:1024
	ds_read_b128 v[168:171], v174 offset:2048
	ds_read_b128 v[174:177], v174 offset:3072
	ds_read_b128 v[178:181], v192
	ds_read_b128 v[184:187], v192 offset:1024
	ds_read_b128 v[188:191], v192 offset:2048
	ds_read_b128 v[192:195], v192 offset:3072
	ds_read_b128 v[196:199], v173 offset:32768
	ds_read_b128 v[200:203], v173 offset:33792
	ds_read_b128 v[204:207], v173 offset:34816
	ds_read_b128 v[208:211], v173 offset:35840
	ds_read_b128 v[212:215], v173 offset:36864
	ds_read_b128 v[216:219], v173 offset:37888
	ds_read_b128 v[220:223], v173 offset:38912
	ds_read_b128 v[224:227], v173 offset:39936
	s_setprio 1
	s_waitcnt vmcnt(8) lgkmcnt(0)
	s_barrier
	v_mfma_f32_16x16x32_bf16 v[126:129], v[160:163], v[196:199], v[126:129]
	v_mfma_f32_16x16x32_bf16 v[122:125], v[168:171], v[196:199], v[122:125]
	v_mfma_f32_16x16x32_bf16 v[118:121], v[160:163], v[204:207], v[118:121]
	v_mfma_f32_16x16x32_bf16 v[110:113], v[168:171], v[204:207], v[110:113]
	v_mfma_f32_16x16x32_bf16 v[102:105], v[160:163], v[212:215], v[102:105]
	v_mfma_f32_16x16x32_bf16 v[94:97], v[168:171], v[212:215], v[94:97]
	v_mfma_f32_16x16x32_bf16 v[86:89], v[160:163], v[220:223], v[86:89]
	v_mfma_f32_16x16x32_bf16 v[78:81], v[168:171], v[220:223], v[78:81]
	v_mfma_f32_16x16x32_bf16 v[126:129], v[164:167], v[200:203], v[126:129]
	v_mfma_f32_16x16x32_bf16 v[122:125], v[174:177], v[200:203], v[122:125]
	v_mfma_f32_16x16x32_bf16 v[118:121], v[164:167], v[208:211], v[118:121]
	v_mfma_f32_16x16x32_bf16 v[110:113], v[174:177], v[208:211], v[110:113]
	v_mfma_f32_16x16x32_bf16 v[102:105], v[164:167], v[216:219], v[102:105]
	v_mfma_f32_16x16x32_bf16 v[94:97], v[174:177], v[216:219], v[94:97]
	v_mfma_f32_16x16x32_bf16 v[86:89], v[164:167], v[224:227], v[86:89]
	v_mfma_f32_16x16x32_bf16 v[78:81], v[174:177], v[224:227], v[78:81]
	v_mfma_f32_16x16x32_bf16 v[114:117], v[178:181], v[196:199], v[114:117]
	v_mfma_f32_16x16x32_bf16 v[106:109], v[188:191], v[196:199], v[106:109]
	v_mfma_f32_16x16x32_bf16 v[98:101], v[178:181], v[204:207], v[98:101]
	v_mfma_f32_16x16x32_bf16 v[90:93], v[188:191], v[204:207], v[90:93]
	v_mfma_f32_16x16x32_bf16 v[82:85], v[178:181], v[212:215], v[82:85]
	v_mfma_f32_16x16x32_bf16 v[74:77], v[188:191], v[212:215], v[74:77]
	v_mfma_f32_16x16x32_bf16 v[70:73], v[178:181], v[220:223], v[70:73]
	v_mfma_f32_16x16x32_bf16 v[66:69], v[188:191], v[220:223], v[66:69]
	v_mfma_f32_16x16x32_bf16 v[114:117], v[184:187], v[200:203], v[114:117]
	v_mfma_f32_16x16x32_bf16 v[106:109], v[192:195], v[200:203], v[106:109]
	v_mfma_f32_16x16x32_bf16 v[98:101], v[184:187], v[208:211], v[98:101]
	v_mfma_f32_16x16x32_bf16 v[90:93], v[192:195], v[208:211], v[90:93]
	v_mfma_f32_16x16x32_bf16 v[82:85], v[184:187], v[216:219], v[82:85]
	v_mfma_f32_16x16x32_bf16 v[74:77], v[192:195], v[216:219], v[74:77]
	v_mfma_f32_16x16x32_bf16 v[70:73], v[184:187], v[224:227], v[70:73]
	v_mfma_f32_16x16x32_bf16 v[66:69], v[192:195], v[224:227], v[66:69]
	s_barrier
; #define PG8_STAGE(bufoff, gbase, voff) do { _Pragma("unroll") for (int _i = 0; _i < 2; ++_i) \
;         __builtin_amdgcn_global_load_lds((const unsigned*)((const char*)(gbase) + (voff)[_i]), (LAS unsigned*)(lds + (bufoff) + ldsw + _i * 8192), 16, 0, 0); } while (0)
; #define PG8_LDA(dst, b, h) do { _Pragma("unroll") for (int m = 0; m < 4; ++m) _Pragma("unroll") for (int k = 0; k < 2; ++k) dst[m][k] = *(const LAS bf16x8*)(lds + PG8_SA(b, h) + aoff + m * 2048 + k * 1024); } while (0)
; #define PG8_LDB(dst, b, h) do { _Pragma("unroll") for (int n = 0; n < 2; ++n) _Pragma("unroll") for (int k = 0; k < 2; ++k) dst[n][k] = *(const LAS bf16x8*)(lds + PG8_SB(b, h) + boff + n * 2048 + k * 1024); } while (0)
; #define PG8_BAR __builtin_amdgcn_s_barrier()
; template <class Epi, bool ALIGN_EPI = PG8_ALIGN, bool SP2 = PG8_SP2>
; __device__ __forceinline__ void gemm_phase(LAS uchar* lds, const Gemm g, const StaticOrder& S, const Epi& E) {
;     ...
;         for (int t = tb; t < tb + tblk; t += 2) {
;             const bool last = (t == nt - 2);
;             const char* a1 = cA + (size_t)(t + 1) * kstep;
;             const char* a2 = last ? nA : cA + (size_t)(t + 2) * kstep; const char* b2 = last ? nB : cB + (size_t)(t + 2) * kstep;
;             const char* a3 = a2 + kstep; const char* b3 = b2 + kstep;
;             if constexpr (SP2) {
;             PG8_LDB(B0, 0, 0); PG8_LDB(B1, 0, 1); PG8_SCHED; PG8_LDA(At, 0, 0); PG8_STAGE(PG8_SA(1, 1), a1 + hstepA, voffA);
;             PG8_WAIT_V(8); PG8_WAIT_L(0); PG8_BAR; PG8_MMA(0, 0, At, B0); PG8_MMA(0, 1, At, B1); PG8_BAR; PG8_SCHED;
;             PG8_LDA(At, 0, 1); PG8_STAGE(PG8_SB(0, 0), b2, voffB); PG8_STAGE(PG8_SB(0, 1), b2 + hstepB, voffB); PG8_STAGE(PG8_SA(0, 0), a2, voffA);
;             PG8_WAIT_V(8); PG8_WAIT_L(0); PG8_BAR; PG8_MMA(1, 0, At, B0); PG8_MMA(1, 1, At, B1); PG8_BAR; PG8_SCHED;
;             PG8_LDB(B0, 1, 0); PG8_LDB(B1, 1, 1); PG8_SCHED; PG8_LDA(At, 1, 0); PG8_STAGE(PG8_SA(0, 1), a2 + hstepA, voffA);
;             PG8_WAIT_V(8); PG8_WAIT_L(0); PG8_BAR; PG8_MMA(0, 0, At, B0); PG8_MMA(0, 1, At, B1); PG8_BAR; PG8_SCHED;
;             PG8_LDA(At, 1, 1); PG8_STAGE(PG8_SB(1, 0), b3, voffB); PG8_STAGE(PG8_SB(1, 1), b3 + hstepB, voffB); PG8_STAGE(PG8_SA(1, 0), a3, voffA);
;             PG8_WAIT_V(8); PG8_WAIT_L(0); PG8_BAR; PG8_MMA(1, 0, At, B0); PG8_MMA(1, 1, At, B1); PG8_BAR; PG8_SCHED;
	s_setprio 0
	s_add_i32 s12, s39, s21
	s_mov_b32 m0, s12
	v_lshl_add_u64 v[228:229], v[228:229], 0, s[84:85]
	global_load_lds_dwordx4 v[228:229], off
	s_add_i32 m0, s12, 0x2000
	s_add_u32 s12, s16, 0x44080
	v_lshl_add_u64 v[228:229], v[230:231], 0, s[84:85]
	s_addc_u32 s13, s17, 0
	s_add_i32 s16, s40, s21
	global_load_lds_dwordx4 v[228:229], off
	s_mov_b32 m0, s16
	v_lshl_add_u64 v[228:229], s[12:13], 0, v[134:135]
	global_load_lds_dwordx4 v[228:229], off
	s_add_i32 m0, s16, 0x2000
	v_lshl_add_u64 v[228:229], s[12:13], 0, v[130:131]
	global_load_lds_dwordx4 v[228:229], off
	s_mov_b32 m0, s27
	v_lshl_add_u64 v[228:229], v[232:233], 0, s[84:85]
	global_load_lds_dwordx4 v[228:229], off
	s_mov_b32 m0, s28
	v_lshl_add_u64 v[228:229], v[234:235], 0, s[84:85]
	global_load_lds_dwordx4 v[228:229], off
	ds_read_b128 v[196:199], v173 offset:49152
	ds_read_b128 v[200:203], v173 offset:50176
	ds_read_b128 v[204:207], v173 offset:51200
	ds_read_b128 v[208:211], v173 offset:52224
	ds_read_b128 v[212:215], v173 offset:53248
	ds_read_b128 v[216:219], v173 offset:54272
	ds_read_b128 v[220:223], v173 offset:55296
	ds_read_b128 v[224:227], v173 offset:56320
	s_setprio 1
	s_waitcnt vmcnt(8) lgkmcnt(0)
	s_barrier
	v_mfma_f32_16x16x32_bf16 v[62:65], v[160:163], v[196:199], v[62:65]
	v_mfma_f32_16x16x32_bf16 v[58:61], v[168:171], v[196:199], v[58:61]
	v_mfma_f32_16x16x32_bf16 v[54:57], v[160:163], v[204:207], v[54:57]
	v_mfma_f32_16x16x32_bf16 v[46:49], v[168:171], v[204:207], v[46:49]
	v_mfma_f32_16x16x32_bf16 v[38:41], v[160:163], v[212:215], v[38:41]
	v_mfma_f32_16x16x32_bf16 v[30:33], v[168:171], v[212:215], v[30:33]
	v_mfma_f32_16x16x32_bf16 v[22:25], v[160:163], v[220:223], v[22:25]
	v_mfma_f32_16x16x32_bf16 v[14:17], v[168:171], v[220:223], v[14:17]
	v_mfma_f32_16x16x32_bf16 v[62:65], v[164:167], v[200:203], v[62:65]
	v_mfma_f32_16x16x32_bf16 v[58:61], v[174:177], v[200:203], v[58:61]
	v_mfma_f32_16x16x32_bf16 v[54:57], v[164:167], v[208:211], v[54:57]
	v_mfma_f32_16x16x32_bf16 v[46:49], v[174:177], v[208:211], v[46:49]
	v_mfma_f32_16x16x32_bf16 v[38:41], v[164:167], v[216:219], v[38:41]
	v_mfma_f32_16x16x32_bf16 v[30:33], v[174:177], v[216:219], v[30:33]
	v_mfma_f32_16x16x32_bf16 v[22:25], v[164:167], v[224:227], v[22:25]
	v_mfma_f32_16x16x32_bf16 v[14:17], v[174:177], v[224:227], v[14:17]
	v_mfma_f32_16x16x32_bf16 v[50:53], v[178:181], v[196:199], v[50:53]
	v_mfma_f32_16x16x32_bf16 v[42:45], v[188:191], v[196:199], v[42:45]
	v_mfma_f32_16x16x32_bf16 v[34:37], v[178:181], v[204:207], v[34:37]
	v_mfma_f32_16x16x32_bf16 v[26:29], v[188:191], v[204:207], v[26:29]
	v_mfma_f32_16x16x32_bf16 v[18:21], v[178:181], v[212:215], v[18:21]
	v_mfma_f32_16x16x32_bf16 v[10:13], v[188:191], v[212:215], v[10:13]
	v_mfma_f32_16x16x32_bf16 v[6:9], v[178:181], v[220:223], v[6:9]
	v_mfma_f32_16x16x32_bf16 v[2:5], v[188:191], v[220:223], v[2:5]
	v_mfma_f32_16x16x32_bf16 v[50:53], v[184:187], v[200:203], v[50:53]
	v_mfma_f32_16x16x32_bf16 v[42:45], v[192:195], v[200:203], v[42:45]
	v_mfma_f32_16x16x32_bf16 v[34:37], v[184:187], v[208:211], v[34:37]
	v_mfma_f32_16x16x32_bf16 v[26:29], v[192:195], v[208:211], v[26:29]
	v_mfma_f32_16x16x32_bf16 v[18:21], v[184:187], v[216:219], v[18:21]
	v_mfma_f32_16x16x32_bf16 v[10:13], v[192:195], v[216:219], v[10:13]
	v_mfma_f32_16x16x32_bf16 v[6:9], v[184:187], v[224:227], v[6:9]
	v_mfma_f32_16x16x32_bf16 v[2:5], v[192:195], v[224:227], v[2:5]
	s_barrier
	s_setprio 0
	s_add_i32 s38, s38, 2
	s_add_u32 s36, s36, 0x100
	s_addc_u32 s37, s37, 0
	s_cmp_gt_u32 s38, 13
	s_mov_b64 s[12:13], s[14:15]
.LBB0_669:
	s_add_u32 s14, s12, 0x100
	s_addc_u32 s15, s13, 0
	s_add_i32 s39, 0, 0x10000
	s_cmp_eq_u32 s38, 12
	s_cselect_b32 s19, s5, s15
	s_cselect_b32 s18, s4, s14
	s_cselect_b32 s17, s11, s37
	s_cselect_b32 s16, s10, s36
	s_add_i32 s40, 0, 0x14000
	v_add_u32_e32 v174, s39, v139
	v_add_u32_e32 v192, s40, v139
	s_add_i32 m0, s23, 0xc000
	v_lshl_add_u64 v[228:229], s[12:13], 0, v[156:157]
	global_load_lds_dwordx4 v[228:229], off
	s_add_i32 m0, s23, 0xe000
	v_lshl_add_u64 v[228:229], s[12:13], 0, v[158:159]
	global_load_lds_dwordx4 v[228:229], off
	ds_read_b128 v[160:163], v174
	ds_read_b128 v[164:167], v174 offset:1024
	ds_read_b128 v[168:171], v174 offset:2048
	ds_read_b128 v[174:177], v174 offset:3072
	ds_read_b128 v[178:181], v192
	ds_read_b128 v[184:187], v192 offset:1024
	ds_read_b128 v[188:191], v192 offset:2048
	ds_read_b128 v[192:195], v192 offset:3072
	ds_read_b128 v[196:199], v173
	ds_read_b128 v[200:203], v173 offset:1024
	ds_read_b128 v[204:207], v173 offset:2048
	ds_read_b128 v[208:211], v173 offset:3072
	ds_read_b128 v[212:215], v173 offset:4096
	ds_read_b128 v[216:219], v173 offset:5120
	ds_read_b128 v[220:223], v173 offset:6144
	ds_read_b128 v[224:227], v173 offset:7168
	s_setprio 1
	s_waitcnt vmcnt(8) lgkmcnt(0)
	s_barrier
; #define PG8_STAGE(bufoff, gbase, voff) do { _Pragma("unroll") for (int _i = 0; _i < 2; ++_i) \
;         __builtin_amdgcn_global_load_lds((const unsigned*)((const char*)(gbase) + (voff)[_i]), (LAS unsigned*)(lds + (bufoff) + ldsw + _i * 8192), 16, 0, 0); } while (0)
; #define PG8_LDA(dst, b, h) do { _Pragma("unroll") for (int m = 0; m < 4; ++m) _Pragma("unroll") for (int k = 0; k < 2; ++k) dst[m][k] = *(const LAS bf16x8*)(lds + PG8_SA(b, h) + aoff + m * 2048 + k * 1024); } while (0)
; #define PG8_LDB(dst, b, h) do { _Pragma("unroll") for (int n = 0; n < 2; ++n) _Pragma("unroll") for (int k = 0; k < 2; ++k) dst[n][k] = *(const LAS bf16x8*)(lds + PG8_SB(b, h) + boff + n * 2048 + k * 1024); } while (0)
; #define PG8_MMA(ai, bj, At, Bt) do { __builtin_amdgcn_s_setprio(1); _Pragma("unroll") for (int m = 0; m < 4; ++m) _Pragma("unroll") for (int n = 0; n < 2; ++n) _Pragma("unroll") for (int k = 0; k < 2; ++k) \
;         acc[ai][bj][m][n] = __builtin_amdgcn_mfma_f32_16x16x32_bf16(Bt[n][k], At[m][k], acc[ai][bj][m][n], 0, 0, 0); __builtin_amdgcn_s_setprio(0); } while (0)
; #define PG8_WAIT_V(n) asm volatile("s_waitcnt vmcnt(" #n ")" ::: "memory")
; #define PG8_WAIT_L(n) asm volatile("s_waitcnt lgkmcnt(" #n ")" ::: "memory")
; #define PG8_BAR __builtin_amdgcn_s_barrier()
; #define PG8_SCHED __builtin_amdgcn_sched_barrier(0)
; template <class Epi, bool ALIGN_EPI = PG8_ALIGN, bool SP2 = PG8_SP2>
; __device__ __forceinline__ void gemm_phase(LAS uchar* lds, const Gemm g, const StaticOrder& S, const Epi& E) {
;     ...
;             PG8_LDB(B0, 0, 0); PG8_LDB(B1, 0, 1); PG8_SCHED; PG8_LDA(At, 0, 0); PG8_STAGE(PG8_SA(1, 1), a1 + hstepA, voffA);
;             PG8_WAIT_V(8); PG8_WAIT_L(0); PG8_BAR; PG8_MMA(0, 0, At, B0); PG8_MMA(0, 1, At, B1); PG8_BAR; PG8_SCHED;
;             PG8_LDA(At, 0, 1); PG8_STAGE(PG8_SB(0, 0), b2, voffB); PG8_STAGE(PG8_SB(0, 1), b2 + hstepB, voffB); PG8_STAGE(PG8_SA(0, 0), a2, voffA);
;             PG8_WAIT_V(8); PG8_WAIT_L(0); PG8_BAR; PG8_MMA(1, 0, At, B0); PG8_MMA(1, 1, At, B1); PG8_BAR; PG8_SCHED;
	v_mfma_f32_16x16x32_bf16 v[126:129], v[160:163], v[196:199], v[126:129]
	v_mfma_f32_16x16x32_bf16 v[122:125], v[168:171], v[196:199], v[122:125]
	v_mfma_f32_16x16x32_bf16 v[118:121], v[160:163], v[204:207], v[118:121]
	v_mfma_f32_16x16x32_bf16 v[110:113], v[168:171], v[204:207], v[110:113]
	v_mfma_f32_16x16x32_bf16 v[102:105], v[160:163], v[212:215], v[102:105]
	v_mfma_f32_16x16x32_bf16 v[94:97], v[168:171], v[212:215], v[94:97]
	v_mfma_f32_16x16x32_bf16 v[86:89], v[160:163], v[220:223], v[86:89]
	v_mfma_f32_16x16x32_bf16 v[78:81], v[168:171], v[220:223], v[78:81]
	v_mfma_f32_16x16x32_bf16 v[126:129], v[164:167], v[200:203], v[126:129]
	v_mfma_f32_16x16x32_bf16 v[122:125], v[174:177], v[200:203], v[122:125]
	v_mfma_f32_16x16x32_bf16 v[118:121], v[164:167], v[208:211], v[118:121]
	v_mfma_f32_16x16x32_bf16 v[110:113], v[174:177], v[208:211], v[110:113]
	v_mfma_f32_16x16x32_bf16 v[102:105], v[164:167], v[216:219], v[102:105]
	v_mfma_f32_16x16x32_bf16 v[94:97], v[174:177], v[216:219], v[94:97]
	v_mfma_f32_16x16x32_bf16 v[86:89], v[164:167], v[224:227], v[86:89]
	v_mfma_f32_16x16x32_bf16 v[78:81], v[174:177], v[224:227], v[78:81]
	v_mfma_f32_16x16x32_bf16 v[114:117], v[178:181], v[196:199], v[114:117]
	v_mfma_f32_16x16x32_bf16 v[106:109], v[188:191], v[196:199], v[106:109]
	v_mfma_f32_16x16x32_bf16 v[98:101], v[178:181], v[204:207], v[98:101]
	v_mfma_f32_16x16x32_bf16 v[90:93], v[188:191], v[204:207], v[90:93]
	v_mfma_f32_16x16x32_bf16 v[82:85], v[178:181], v[212:215], v[82:85]
	v_mfma_f32_16x16x32_bf16 v[74:77], v[188:191], v[212:215], v[74:77]
	v_mfma_f32_16x16x32_bf16 v[70:73], v[178:181], v[220:223], v[70:73]
	v_mfma_f32_16x16x32_bf16 v[66:69], v[188:191], v[220:223], v[66:69]
	v_mfma_f32_16x16x32_bf16 v[114:117], v[184:187], v[200:203], v[114:117]
	v_mfma_f32_16x16x32_bf16 v[106:109], v[192:195], v[200:203], v[106:109]
	v_mfma_f32_16x16x32_bf16 v[98:101], v[184:187], v[208:211], v[98:101]
	v_mfma_f32_16x16x32_bf16 v[90:93], v[192:195], v[208:211], v[90:93]
	v_mfma_f32_16x16x32_bf16 v[82:85], v[184:187], v[216:219], v[82:85]
	v_mfma_f32_16x16x32_bf16 v[74:77], v[192:195], v[216:219], v[74:77]
	v_mfma_f32_16x16x32_bf16 v[70:73], v[184:187], v[224:227], v[70:73]
	v_mfma_f32_16x16x32_bf16 v[66:69], v[192:195], v[224:227], v[66:69]
	s_barrier
	s_setprio 0
	s_add_i32 s12, s39, s21
	s_mov_b32 m0, s12
	v_lshl_add_u64 v[228:229], s[16:17], 0, v[134:135]
	global_load_lds_dwordx4 v[228:229], off
	s_add_i32 m0, s12, 0x2000
	s_add_u32 s12, s16, 0x44000
	v_lshl_add_u64 v[230:231], s[16:17], 0, v[130:131]
	s_addc_u32 s13, s17, 0
	s_add_i32 s39, s40, s21
	global_load_lds_dwordx4 v[230:231], off
	s_mov_b32 m0, s39
	v_lshl_add_u64 v[232:233], s[12:13], 0, v[134:135]
	global_load_lds_dwordx4 v[232:233], off
	s_add_i32 m0, s39, 0x2000
	v_lshl_add_u64 v[232:233], s[12:13], 0, v[130:131]
	global_load_lds_dwordx4 v[232:233], off
	s_mov_b32 m0, s23
	v_lshl_add_u64 v[232:233], s[18:19], 0, v[152:153]
	global_load_lds_dwordx4 v[232:233], off
	s_mov_b32 m0, s24
	v_lshl_add_u64 v[234:235], s[18:19], 0, v[132:133]
	global_load_lds_dwordx4 v[234:235], off
	ds_read_b128 v[196:199], v173 offset:16384
	ds_read_b128 v[200:203], v173 offset:17408
	ds_read_b128 v[204:207], v173 offset:18432
	ds_read_b128 v[208:211], v173 offset:19456
	ds_read_b128 v[212:215], v173 offset:20480
	ds_read_b128 v[216:219], v173 offset:21504
	ds_read_b128 v[220:223], v173 offset:22528
	ds_read_b128 v[224:227], v173 offset:23552
	s_setprio 1
	s_waitcnt vmcnt(8) lgkmcnt(0)
	s_barrier
	v_mfma_f32_16x16x32_bf16 v[62:65], v[160:163], v[196:199], v[62:65]
	v_mfma_f32_16x16x32_bf16 v[58:61], v[168:171], v[196:199], v[58:61]
	v_mfma_f32_16x16x32_bf16 v[54:57], v[160:163], v[204:207], v[54:57]
	v_mfma_f32_16x16x32_bf16 v[46:49], v[168:171], v[204:207], v[46:49]
	v_mfma_f32_16x16x32_bf16 v[38:41], v[160:163], v[212:215], v[38:41]
	v_mfma_f32_16x16x32_bf16 v[30:33], v[168:171], v[212:215], v[30:33]
	v_mfma_f32_16x16x32_bf16 v[22:25], v[160:163], v[220:223], v[22:25]
	v_mfma_f32_16x16x32_bf16 v[14:17], v[168:171], v[220:223], v[14:17]
	v_mfma_f32_16x16x32_bf16 v[62:65], v[164:167], v[200:203], v[62:65]
	v_mfma_f32_16x16x32_bf16 v[58:61], v[174:177], v[200:203], v[58:61]
	v_mfma_f32_16x16x32_bf16 v[54:57], v[164:167], v[208:211], v[54:57]
	v_mfma_f32_16x16x32_bf16 v[46:49], v[174:177], v[208:211], v[46:49]
	v_mfma_f32_16x16x32_bf16 v[38:41], v[164:167], v[216:219], v[38:41]
	v_mfma_f32_16x16x32_bf16 v[30:33], v[174:177], v[216:219], v[30:33]
	v_mfma_f32_16x16x32_bf16 v[22:25], v[164:167], v[224:227], v[22:25]
	v_mfma_f32_16x16x32_bf16 v[14:17], v[174:177], v[224:227], v[14:17]
	v_mfma_f32_16x16x32_bf16 v[50:53], v[178:181], v[196:199], v[50:53]
	v_mfma_f32_16x16x32_bf16 v[42:45], v[188:191], v[196:199], v[42:45]
	v_mfma_f32_16x16x32_bf16 v[34:37], v[178:181], v[204:207], v[34:37]
	v_mfma_f32_16x16x32_bf16 v[26:29], v[188:191], v[204:207], v[26:29]
	v_mfma_f32_16x16x32_bf16 v[18:21], v[178:181], v[212:215], v[18:21]
	v_mfma_f32_16x16x32_bf16 v[10:13], v[188:191], v[212:215], v[10:13]
	v_mfma_f32_16x16x32_bf16 v[6:9], v[178:181], v[220:223], v[6:9]
	v_mfma_f32_16x16x32_bf16 v[2:5], v[188:191], v[220:223], v[2:5]
	v_mfma_f32_16x16x32_bf16 v[50:53], v[184:187], v[200:203], v[50:53]
	v_mfma_f32_16x16x32_bf16 v[42:45], v[192:195], v[200:203], v[42:45]
	v_mfma_f32_16x16x32_bf16 v[34:37], v[184:187], v[208:211], v[34:37]
	v_mfma_f32_16x16x32_bf16 v[26:29], v[192:195], v[208:211], v[26:29]
	v_mfma_f32_16x16x32_bf16 v[18:21], v[184:187], v[216:219], v[18:21]
	v_mfma_f32_16x16x32_bf16 v[10:13], v[192:195], v[216:219], v[10:13]
	v_mfma_f32_16x16x32_bf16 v[6:9], v[184:187], v[224:227], v[6:9]
	v_mfma_f32_16x16x32_bf16 v[2:5], v[192:195], v[224:227], v[2:5]
	s_barrier
; #define PG8_STAGE(bufoff, gbase, voff) do { _Pragma("unroll") for (int _i = 0; _i < 2; ++_i) \
;         __builtin_amdgcn_global_load_lds((const unsigned*)((const char*)(gbase) + (voff)[_i]), (LAS unsigned*)(lds + (bufoff) + ldsw + _i * 8192), 16, 0, 0); } while (0)
; #define PG8_LDA(dst, b, h) do { _Pragma("unroll") for (int m = 0; m < 4; ++m) _Pragma("unroll") for (int k = 0; k < 2; ++k) dst[m][k] = *(const LAS bf16x8*)(lds + PG8_SA(b, h) + aoff + m * 2048 + k * 1024); } while (0)
; #define PG8_LDB(dst, b, h) do { _Pragma("unroll") for (int n = 0; n < 2; ++n) _Pragma("unroll") for (int k = 0; k < 2; ++k) dst[n][k] = *(const LAS bf16x8*)(lds + PG8_SB(b, h) + boff + n * 2048 + k * 1024); } while (0)
; #define PG8_MMA(ai, bj, At, Bt) do { __builtin_amdgcn_s_setprio(1); _Pragma("unroll") for (int m = 0; m < 4; ++m) _Pragma("unroll") for (int n = 0; n < 2; ++n) _Pragma("unroll") for (int k = 0; k < 2; ++k) \
;         acc[ai][bj][m][n] = __builtin_amdgcn_mfma_f32_16x16x32_bf16(Bt[n][k], At[m][k], acc[ai][bj][m][n], 0, 0, 0); __builtin_amdgcn_s_setprio(0); } while (0)
; #define PG8_WAIT_V(n) asm volatile("s_waitcnt vmcnt(" #n ")" ::: "memory")
; #define PG8_WAIT_L(n) asm volatile("s_waitcnt lgkmcnt(" #n ")" ::: "memory")
; #define PG8_BAR __builtin_amdgcn_s_barrier()
; #define PG8_SCHED __builtin_amdgcn_sched_barrier(0)
; template <class Epi, bool ALIGN_EPI = PG8_ALIGN, bool SP2 = PG8_SP2>
; __device__ __forceinline__ void gemm_phase(LAS uchar* lds, const Gemm g, const StaticOrder& S, const Epi& E) {
;     ...
;             PG8_LDB(B0, 1, 0); PG8_LDB(B1, 1, 1); PG8_SCHED; PG8_LDA(At, 1, 0); PG8_STAGE(PG8_SA(0, 1), a2 + hstepA, voffA);
;             PG8_WAIT_V(8); PG8_WAIT_L(0); PG8_BAR; PG8_MMA(0, 0, At, B0); PG8_MMA(0, 1, At, B1); PG8_BAR; PG8_SCHED;
	s_setprio 0
	s_add_i32 s39, 0, 0x18000
	s_add_i32 s40, 0, 0x1c000
	v_add_u32_e32 v174, s39, v139
	v_add_u32_e32 v192, s40, v139
	s_add_u32 s12, s18, 0x44000
	s_addc_u32 s13, s19, 0
	s_mov_b32 m0, s25
	v_lshl_add_u64 v[236:237], s[12:13], 0, v[152:153]
	global_load_lds_dwordx4 v[236:237], off
	s_mov_b32 m0, s26
	v_lshl_add_u64 v[236:237], s[12:13], 0, v[132:133]
	global_load_lds_dwordx4 v[236:237], off
	ds_read_b128 v[160:163], v174
	ds_read_b128 v[164:167], v174 offset:1024
	ds_read_b128 v[168:171], v174 offset:2048
	ds_read_b128 v[174:177], v174 offset:3072
	ds_read_b128 v[178:181], v192
	ds_read_b128 v[184:187], v192 offset:1024
	ds_read_b128 v[188:191], v192 offset:2048
	ds_read_b128 v[192:195], v192 offset:3072
	ds_read_b128 v[196:199], v173 offset:32768
	ds_read_b128 v[200:203], v173 offset:33792
	ds_read_b128 v[204:207], v173 offset:34816
	ds_read_b128 v[208:211], v173 offset:35840
	ds_read_b128 v[212:215], v173 offset:36864
	ds_read_b128 v[216:219], v173 offset:37888
	ds_read_b128 v[220:223], v173 offset:38912
	ds_read_b128 v[224:227], v173 offset:39936
	s_setprio 1
	s_waitcnt vmcnt(8) lgkmcnt(0)
	s_barrier
	v_mfma_f32_16x16x32_bf16 v[126:129], v[160:163], v[196:199], v[126:129]
	v_mfma_f32_16x16x32_bf16 v[122:125], v[168:171], v[196:199], v[122:125]
	v_mfma_f32_16x16x32_bf16 v[118:121], v[160:163], v[204:207], v[118:121]
	v_mfma_f32_16x16x32_bf16 v[110:113], v[168:171], v[204:207], v[110:113]
	v_mfma_f32_16x16x32_bf16 v[102:105], v[160:163], v[212:215], v[102:105]
	v_mfma_f32_16x16x32_bf16 v[94:97], v[168:171], v[212:215], v[94:97]
	v_mfma_f32_16x16x32_bf16 v[86:89], v[160:163], v[220:223], v[86:89]
	v_mfma_f32_16x16x32_bf16 v[78:81], v[168:171], v[220:223], v[78:81]
	v_mfma_f32_16x16x32_bf16 v[126:129], v[164:167], v[200:203], v[126:129]
	v_mfma_f32_16x16x32_bf16 v[122:125], v[174:177], v[200:203], v[122:125]
	v_mfma_f32_16x16x32_bf16 v[118:121], v[164:167], v[208:211], v[118:121]
	v_mfma_f32_16x16x32_bf16 v[110:113], v[174:177], v[208:211], v[110:113]
	v_mfma_f32_16x16x32_bf16 v[102:105], v[164:167], v[216:219], v[102:105]
	v_mfma_f32_16x16x32_bf16 v[94:97], v[174:177], v[216:219], v[94:97]
	v_mfma_f32_16x16x32_bf16 v[86:89], v[164:167], v[224:227], v[86:89]
	v_mfma_f32_16x16x32_bf16 v[78:81], v[174:177], v[224:227], v[78:81]
	v_mfma_f32_16x16x32_bf16 v[114:117], v[178:181], v[196:199], v[114:117]
	v_mfma_f32_16x16x32_bf16 v[106:109], v[188:191], v[196:199], v[106:109]
	v_mfma_f32_16x16x32_bf16 v[98:101], v[178:181], v[204:207], v[98:101]
	v_mfma_f32_16x16x32_bf16 v[90:93], v[188:191], v[204:207], v[90:93]
	v_mfma_f32_16x16x32_bf16 v[82:85], v[178:181], v[212:215], v[82:85]
	v_mfma_f32_16x16x32_bf16 v[74:77], v[188:191], v[212:215], v[74:77]
	v_mfma_f32_16x16x32_bf16 v[70:73], v[178:181], v[220:223], v[70:73]
	v_mfma_f32_16x16x32_bf16 v[66:69], v[188:191], v[220:223], v[66:69]
	v_mfma_f32_16x16x32_bf16 v[114:117], v[184:187], v[200:203], v[114:117]
	v_mfma_f32_16x16x32_bf16 v[106:109], v[192:195], v[200:203], v[106:109]
	v_mfma_f32_16x16x32_bf16 v[98:101], v[184:187], v[208:211], v[98:101]
	v_mfma_f32_16x16x32_bf16 v[90:93], v[192:195], v[208:211], v[90:93]
	v_mfma_f32_16x16x32_bf16 v[82:85], v[184:187], v[216:219], v[82:85]
	v_mfma_f32_16x16x32_bf16 v[74:77], v[192:195], v[216:219], v[74:77]
	v_mfma_f32_16x16x32_bf16 v[70:73], v[184:187], v[224:227], v[70:73]
	v_mfma_f32_16x16x32_bf16 v[66:69], v[192:195], v[224:227], v[66:69]
	s_barrier
; #define PG8_STAGE(bufoff, gbase, voff) do { _Pragma("unroll") for (int _i = 0; _i < 2; ++_i) \
;         __builtin_amdgcn_global_load_lds((const unsigned*)((const char*)(gbase) + (voff)[_i]), (LAS unsigned*)(lds + (bufoff) + ldsw + _i * 8192), 16, 0, 0); } while (0)
; #define PG8_LDA(dst, b, h) do { _Pragma("unroll") for (int m = 0; m < 4; ++m) _Pragma("unroll") for (int k = 0; k < 2; ++k) dst[m][k] = *(const LAS bf16x8*)(lds + PG8_SA(b, h) + aoff + m * 2048 + k * 1024); } while (0)
; #define PG8_MMA(ai, bj, At, Bt) do { __builtin_amdgcn_s_setprio(1); _Pragma("unroll") for (int m = 0; m < 4; ++m) _Pragma("unroll") for (int n = 0; n < 2; ++n) _Pragma("unroll") for (int k = 0; k < 2; ++k) \
;         acc[ai][bj][m][n] = __builtin_amdgcn_mfma_f32_16x16x32_bf16(Bt[n][k], At[m][k], acc[ai][bj][m][n], 0, 0, 0); __builtin_amdgcn_s_setprio(0); } while (0)
; #define PG8_WAIT_V(n) asm volatile("s_waitcnt vmcnt(" #n ")" ::: "memory")
; #define PG8_WAIT_L(n) asm volatile("s_waitcnt lgkmcnt(" #n ")" ::: "memory")
; #define PG8_BAR __builtin_amdgcn_s_barrier()
; #define PG8_SCHED __builtin_amdgcn_sched_barrier(0)
; template <class Epi, bool ALIGN_EPI = PG8_ALIGN, bool SP2 = PG8_SP2>
; __device__ __forceinline__ void gemm_phase(LAS uchar* lds, const Gemm g, const StaticOrder& S, const Epi& E) {
;     ...
;             PG8_LDA(At, 1, 1); PG8_STAGE(PG8_SB(1, 0), b3, voffB); PG8_STAGE(PG8_SB(1, 1), b3 + hstepB, voffB); PG8_STAGE(PG8_SA(1, 0), a3, voffA);
;             PG8_WAIT_V(8); PG8_WAIT_L(0); PG8_BAR; PG8_MMA(1, 0, At, B0); PG8_MMA(1, 1, At, B1); PG8_BAR; PG8_SCHED;
;     ...
;         if constexpr (ALIGN_EPI) { if (wr == 0) PG8_BAR; }
	s_setprio 0
	s_add_i32 s12, s39, s21
	s_mov_b32 m0, s12
	v_lshl_add_u64 v[228:229], v[228:229], 0, s[84:85]
	global_load_lds_dwordx4 v[228:229], off
	s_add_i32 m0, s12, 0x2000
	s_add_u32 s12, s16, 0x44080
	v_lshl_add_u64 v[228:229], v[230:231], 0, s[84:85]
	s_addc_u32 s13, s17, 0
	s_add_i32 s16, s40, s21
	global_load_lds_dwordx4 v[228:229], off
	s_mov_b32 m0, s16
	v_lshl_add_u64 v[228:229], s[12:13], 0, v[134:135]
	global_load_lds_dwordx4 v[228:229], off
	s_add_i32 m0, s16, 0x2000
	v_lshl_add_u64 v[228:229], s[12:13], 0, v[130:131]
	global_load_lds_dwordx4 v[228:229], off
	s_mov_b32 m0, s27
	v_lshl_add_u64 v[228:229], v[232:233], 0, s[84:85]
	global_load_lds_dwordx4 v[228:229], off
	s_mov_b32 m0, s28
	v_lshl_add_u64 v[228:229], v[234:235], 0, s[84:85]
	global_load_lds_dwordx4 v[228:229], off
	ds_read_b128 v[196:199], v173 offset:49152
	ds_read_b128 v[200:203], v173 offset:50176
	ds_read_b128 v[204:207], v173 offset:51200
	ds_read_b128 v[208:211], v173 offset:52224
	ds_read_b128 v[212:215], v173 offset:53248
	ds_read_b128 v[216:219], v173 offset:54272
	ds_read_b128 v[220:223], v173 offset:55296
	ds_read_b128 v[224:227], v173 offset:56320
	s_setprio 1
	s_waitcnt vmcnt(8) lgkmcnt(0)
	s_barrier
	v_mfma_f32_16x16x32_bf16 v[62:65], v[160:163], v[196:199], v[62:65]
	v_mfma_f32_16x16x32_bf16 v[58:61], v[168:171], v[196:199], v[58:61]
	v_mfma_f32_16x16x32_bf16 v[54:57], v[160:163], v[204:207], v[54:57]
	v_mfma_f32_16x16x32_bf16 v[46:49], v[168:171], v[204:207], v[46:49]
	v_mfma_f32_16x16x32_bf16 v[38:41], v[160:163], v[212:215], v[38:41]
	v_mfma_f32_16x16x32_bf16 v[30:33], v[168:171], v[212:215], v[30:33]
	v_mfma_f32_16x16x32_bf16 v[22:25], v[160:163], v[220:223], v[22:25]
	v_mfma_f32_16x16x32_bf16 v[14:17], v[168:171], v[220:223], v[14:17]
	v_mfma_f32_16x16x32_bf16 v[62:65], v[164:167], v[200:203], v[62:65]
	v_mfma_f32_16x16x32_bf16 v[58:61], v[174:177], v[200:203], v[58:61]
	v_mfma_f32_16x16x32_bf16 v[54:57], v[164:167], v[208:211], v[54:57]
	v_mfma_f32_16x16x32_bf16 v[46:49], v[174:177], v[208:211], v[46:49]
	v_mfma_f32_16x16x32_bf16 v[38:41], v[164:167], v[216:219], v[38:41]
	v_mfma_f32_16x16x32_bf16 v[30:33], v[174:177], v[216:219], v[30:33]
	v_mfma_f32_16x16x32_bf16 v[22:25], v[164:167], v[224:227], v[22:25]
	v_mfma_f32_16x16x32_bf16 v[14:17], v[174:177], v[224:227], v[14:17]
	v_mfma_f32_16x16x32_bf16 v[50:53], v[178:181], v[196:199], v[50:53]
	v_mfma_f32_16x16x32_bf16 v[42:45], v[188:191], v[196:199], v[42:45]
	v_mfma_f32_16x16x32_bf16 v[34:37], v[178:181], v[204:207], v[34:37]
	v_mfma_f32_16x16x32_bf16 v[26:29], v[188:191], v[204:207], v[26:29]
	v_mfma_f32_16x16x32_bf16 v[18:21], v[178:181], v[212:215], v[18:21]
	v_mfma_f32_16x16x32_bf16 v[10:13], v[188:191], v[212:215], v[10:13]
	v_mfma_f32_16x16x32_bf16 v[6:9], v[178:181], v[220:223], v[6:9]
	v_mfma_f32_16x16x32_bf16 v[2:5], v[188:191], v[220:223], v[2:5]
	v_mfma_f32_16x16x32_bf16 v[50:53], v[184:187], v[200:203], v[50:53]
	v_mfma_f32_16x16x32_bf16 v[42:45], v[192:195], v[200:203], v[42:45]
	v_mfma_f32_16x16x32_bf16 v[34:37], v[184:187], v[208:211], v[34:37]
	v_mfma_f32_16x16x32_bf16 v[26:29], v[192:195], v[208:211], v[26:29]
	v_mfma_f32_16x16x32_bf16 v[18:21], v[184:187], v[216:219], v[18:21]
	v_mfma_f32_16x16x32_bf16 v[10:13], v[192:195], v[216:219], v[10:13]
	v_mfma_f32_16x16x32_bf16 v[6:9], v[184:187], v[224:227], v[6:9]
	v_mfma_f32_16x16x32_bf16 v[2:5], v[192:195], v[224:227], v[2:5]
	s_barrier
	s_setprio 0
	s_add_i32 s38, s38, 2
	s_add_u32 s36, s36, 0x100
	s_addc_u32 s37, s37, 0
	s_cmp_gt_u32 s38, 13
	s_mov_b64 s[12:13], s[14:15]
	s_cbranch_scc0 .LBB0_669
	s_and_b64 vcc, exec, s[8:9]
	s_cbranch_vccz .LBB0_672
	s_barrier

; #define LAS __attribute__((address_space(3)))
; #define PG8_STAGE(bufoff, gbase, voff) do { _Pragma("unroll") for (int _i = 0; _i < 2; ++_i) \
;         __builtin_amdgcn_global_load_lds((const unsigned*)((const char*)(gbase) + (voff)[_i]), (LAS unsigned*)(lds + (bufoff) + ldsw + _i * 8192), 16, 0, 0); } while (0)
; #define PG8_WAIT_V(n) asm volatile("s_waitcnt vmcnt(" #n ")" ::: "memory")
; template <class Epi, bool ALIGN_EPI = PG8_ALIGN, bool SP2 = PG8_SP2>
; __device__ __forceinline__ void gemm_phase(LAS uchar* lds, const Gemm g, const StaticOrder& S, const Epi& E) {
;     ...
;         const bool has_next = S.next(ui + 1, nxt);
;         const char* nA = has_next ? (const char*)g.A + (size_t)nxt.pm * tstepA : cA; const char* nB = has_next ? (const char*)g.Bt + (size_t)nxt.pn * tstepB : cB;
;         const int tblk = Epi::GROUPS ? 4 : nt;
; #pragma unroll 1
;         for (int tb = 0; tb < nt; tb += tblk) {
;         if constexpr (Epi::GROUPS) { if (tb > 0) {
;             const LAS float* rt = (const LAS float*)(lds + LDS_RT) + ((ui & 1) * 256 + wr * 64 + fr) * 8 + ((tb >> 2) - 1);
; #pragma unroll
;             for (int a = 0; a < 2; ++a)
; #pragma unroll
;                 for (int m = 0; m < 4; ++m) { const float f = rt[(a * 128 + m * 16) * 8];
; #pragma unroll
;                     for (int b = 0; b < 2; ++b)
; #pragma unroll
;                         for (int n = 0; n < 2; ++n) acc[a][b][m][n] *= f; } } }
; #pragma unroll 1
;         for (int t = tb; t < tb + tblk; t += 2) {
;             const bool last = (t == nt - 2);
;             const char* a1 = cA + (size_t)(t + 1) * kstep;
;             const char* a2 = last ? nA : cA + (size_t)(t + 2) * kstep; const char* b2 = last ? nB : cB + (size_t)(t + 2) * kstep;
;             const char* a3 = a2 + kstep; const char* b3 = b2 + kstep;
;             if constexpr (SP2) {
;             PG8_LDB(B0, 0, 0); PG8_LDB(B1, 0, 1); PG8_SCHED; PG8_LDA(At, 0, 0); PG8_STAGE(PG8_SA(1, 1), a1 + hstepA, voffA);
;             PG8_WAIT_V(8); PG8_WAIT_L(0); PG8_BAR; PG8_MMA(0, 0, At, B0); PG8_MMA(0, 1, At, B1); PG8_BAR; PG8_SCHED;
;             PG8_LDA(At, 0, 1); PG8_STAGE(PG8_SB(0, 0), b2, voffB); PG8_STAGE(PG8_SB(0, 1), b2 + hstepB, voffB); PG8_STAGE(PG8_SA(0, 0), a2, voffA);
;             PG8_WAIT_V(8); PG8_WAIT_L(0); PG8_BAR; PG8_MMA(1, 0, At, B0); PG8_MMA(1, 1, At, B1); PG8_BAR; PG8_SCHED;
.LBB0_836:
	s_add_u32 s36, s14, 0x100
	s_addc_u32 s37, s15, 0
	s_mov_b32 s38, -2
	s_add_u32 s14, s12, 0x100
	s_addc_u32 s15, s13, 0
	s_add_i32 s39, 0, 0x10000
	s_cmp_eq_u32 s38, 12
	s_cselect_b32 s19, s5, s15
	s_cselect_b32 s18, s4, s14
	s_cselect_b32 s17, s11, s37
	s_cselect_b32 s16, s10, s36
	s_add_i32 s40, 0, 0x14000
	v_add_u32_e32 v174, s39, v139
	v_add_u32_e32 v192, s40, v139
	s_add_i32 m0, s23, 0xc000
	v_lshl_add_u64 v[228:229], s[12:13], 0, v[156:157]
	global_load_lds_dwordx4 v[228:229], off
	s_add_i32 m0, s23, 0xe000
	v_lshl_add_u64 v[228:229], s[12:13], 0, v[158:159]
	global_load_lds_dwordx4 v[228:229], off
	ds_read_b128 v[160:163], v174
	ds_read_b128 v[166:169], v174 offset:1024
	ds_read_b128 v[170:173], v174 offset:2048
	ds_read_b128 v[174:177], v174 offset:3072
	ds_read_b128 v[178:181], v192
	ds_read_b128 v[184:187], v192 offset:1024
	ds_read_b128 v[188:191], v192 offset:2048
	ds_read_b128 v[192:195], v192 offset:3072
	ds_read_b128 v[196:199], v165
	ds_read_b128 v[200:203], v165 offset:1024
	ds_read_b128 v[204:207], v165 offset:2048
	ds_read_b128 v[208:211], v165 offset:3072
	ds_read_b128 v[212:215], v165 offset:4096
	ds_read_b128 v[216:219], v165 offset:5120
	ds_read_b128 v[220:223], v165 offset:6144
	ds_read_b128 v[224:227], v165 offset:7168
	s_setprio 1
	s_waitcnt vmcnt(8) lgkmcnt(0)
	s_barrier
	v_mfma_f32_16x16x32_bf16 v[126:129], v[160:163], v[196:199], 0
	v_mfma_f32_16x16x32_bf16 v[122:125], v[170:173], v[196:199], 0
	v_mfma_f32_16x16x32_bf16 v[118:121], v[160:163], v[204:207], 0
	v_mfma_f32_16x16x32_bf16 v[110:113], v[170:173], v[204:207], 0
	v_mfma_f32_16x16x32_bf16 v[102:105], v[160:163], v[212:215], 0
	v_mfma_f32_16x16x32_bf16 v[94:97], v[170:173], v[212:215], 0
	v_mfma_f32_16x16x32_bf16 v[86:89], v[160:163], v[220:223], 0
	v_mfma_f32_16x16x32_bf16 v[78:81], v[170:173], v[220:223], 0
	v_mfma_f32_16x16x32_bf16 v[126:129], v[166:169], v[200:203], v[126:129]
	v_mfma_f32_16x16x32_bf16 v[122:125], v[174:177], v[200:203], v[122:125]
	v_mfma_f32_16x16x32_bf16 v[118:121], v[166:169], v[208:211], v[118:121]
	v_mfma_f32_16x16x32_bf16 v[110:113], v[174:177], v[208:211], v[110:113]
	v_mfma_f32_16x16x32_bf16 v[102:105], v[166:169], v[216:219], v[102:105]
	v_mfma_f32_16x16x32_bf16 v[94:97], v[174:177], v[216:219], v[94:97]
	v_mfma_f32_16x16x32_bf16 v[86:89], v[166:169], v[224:227], v[86:89]
	v_mfma_f32_16x16x32_bf16 v[78:81], v[174:177], v[224:227], v[78:81]
	v_mfma_f32_16x16x32_bf16 v[114:117], v[178:181], v[196:199], 0
	v_mfma_f32_16x16x32_bf16 v[106:109], v[188:191], v[196:199], 0
	v_mfma_f32_16x16x32_bf16 v[98:101], v[178:181], v[204:207], 0
	v_mfma_f32_16x16x32_bf16 v[90:93], v[188:191], v[204:207], 0
	v_mfma_f32_16x16x32_bf16 v[82:85], v[178:181], v[212:215], 0
	v_mfma_f32_16x16x32_bf16 v[74:77], v[188:191], v[212:215], 0
	v_mfma_f32_16x16x32_bf16 v[70:73], v[178:181], v[220:223], 0
	v_mfma_f32_16x16x32_bf16 v[66:69], v[188:191], v[220:223], 0
	v_mfma_f32_16x16x32_bf16 v[114:117], v[184:187], v[200:203], v[114:117]
	v_mfma_f32_16x16x32_bf16 v[106:109], v[192:195], v[200:203], v[106:109]
	v_mfma_f32_16x16x32_bf16 v[98:101], v[184:187], v[208:211], v[98:101]
	v_mfma_f32_16x16x32_bf16 v[90:93], v[192:195], v[208:211], v[90:93]
	v_mfma_f32_16x16x32_bf16 v[82:85], v[184:187], v[216:219], v[82:85]
	v_mfma_f32_16x16x32_bf16 v[74:77], v[192:195], v[216:219], v[74:77]
	v_mfma_f32_16x16x32_bf16 v[70:73], v[184:187], v[224:227], v[70:73]
	v_mfma_f32_16x16x32_bf16 v[66:69], v[192:195], v[224:227], v[66:69]
	s_barrier
	s_setprio 0
	s_add_i32 s12, s39, s22
	s_mov_b32 m0, s12
	v_lshl_add_u64 v[228:229], s[16:17], 0, v[132:133]
	global_load_lds_dwordx4 v[228:229], off
	s_add_i32 m0, s12, 0x2000
	s_add_u32 s12, s16, 0x44000
	v_lshl_add_u64 v[230:231], s[16:17], 0, v[152:153]
	s_addc_u32 s13, s17, 0
	s_add_i32 s39, s40, s22
	global_load_lds_dwordx4 v[230:231], off
	s_mov_b32 m0, s39
	v_lshl_add_u64 v[232:233], s[12:13], 0, v[132:133]
	global_load_lds_dwordx4 v[232:233], off
	s_add_i32 m0, s39, 0x2000
	v_lshl_add_u64 v[232:233], s[12:13], 0, v[152:153]
	global_load_lds_dwordx4 v[232:233], off
	s_mov_b32 m0, s23
	v_lshl_add_u64 v[232:233], s[18:19], 0, v[130:131]
	global_load_lds_dwordx4 v[232:233], off
	s_mov_b32 m0, s24
	v_lshl_add_u64 v[234:235], s[18:19], 0, v[134:135]
	global_load_lds_dwordx4 v[234:235], off
	ds_read_b128 v[196:199], v165 offset:16384
	ds_read_b128 v[200:203], v165 offset:17408
	ds_read_b128 v[204:207], v165 offset:18432
	ds_read_b128 v[208:211], v165 offset:19456
	ds_read_b128 v[212:215], v165 offset:20480
	ds_read_b128 v[216:219], v165 offset:21504
	ds_read_b128 v[220:223], v165 offset:22528
	ds_read_b128 v[224:227], v165 offset:23552
	s_setprio 1
	s_waitcnt vmcnt(8) lgkmcnt(0)
	s_barrier
; #define PG8_STAGE(bufoff, gbase, voff) do { _Pragma("unroll") for (int _i = 0; _i < 2; ++_i) \
;         __builtin_amdgcn_global_load_lds((const unsigned*)((const char*)(gbase) + (voff)[_i]), (LAS unsigned*)(lds + (bufoff) + ldsw + _i * 8192), 16, 0, 0); } while (0)
; #define PG8_LDA(dst, b, h) do { _Pragma("unroll") for (int m = 0; m < 4; ++m) _Pragma("unroll") for (int k = 0; k < 2; ++k) dst[m][k] = *(const LAS bf16x8*)(lds + PG8_SA(b, h) + aoff + m * 2048 + k * 1024); } while (0)
; #define PG8_LDB(dst, b, h) do { _Pragma("unroll") for (int n = 0; n < 2; ++n) _Pragma("unroll") for (int k = 0; k < 2; ++k) dst[n][k] = *(const LAS bf16x8*)(lds + PG8_SB(b, h) + boff + n * 2048 + k * 1024); } while (0)
; #define PG8_MMA(ai, bj, At, Bt) do { __builtin_amdgcn_s_setprio(1); _Pragma("unroll") for (int m = 0; m < 4; ++m) _Pragma("unroll") for (int n = 0; n < 2; ++n) _Pragma("unroll") for (int k = 0; k < 2; ++k) \
;         acc[ai][bj][m][n] = __builtin_amdgcn_mfma_f32_16x16x32_bf16(Bt[n][k], At[m][k], acc[ai][bj][m][n], 0, 0, 0); __builtin_amdgcn_s_setprio(0); } while (0)
; #define PG8_WAIT_V(n) asm volatile("s_waitcnt vmcnt(" #n ")" ::: "memory")
; #define PG8_WAIT_L(n) asm volatile("s_waitcnt lgkmcnt(" #n ")" ::: "memory")
; #define PG8_BAR __builtin_amdgcn_s_barrier()
; #define PG8_SCHED __builtin_amdgcn_sched_barrier(0)
; template <class Epi, bool ALIGN_EPI = PG8_ALIGN, bool SP2 = PG8_SP2>
; __device__ __forceinline__ void gemm_phase(LAS uchar* lds, const Gemm g, const StaticOrder& S, const Epi& E) {
;     ...
;             PG8_WAIT_V(8); PG8_WAIT_L(0); PG8_BAR; PG8_MMA(1, 0, At, B0); PG8_MMA(1, 1, At, B1); PG8_BAR; PG8_SCHED;
;             PG8_LDB(B0, 1, 0); PG8_LDB(B1, 1, 1); PG8_SCHED; PG8_LDA(At, 1, 0); PG8_STAGE(PG8_SA(0, 1), a2 + hstepA, voffA);
;             PG8_WAIT_V(8); PG8_WAIT_L(0); PG8_BAR; PG8_MMA(0, 0, At, B0); PG8_MMA(0, 1, At, B1); PG8_BAR; PG8_SCHED;
	v_mfma_f32_16x16x32_bf16 v[62:65], v[160:163], v[196:199], 0
	v_mfma_f32_16x16x32_bf16 v[58:61], v[170:173], v[196:199], 0
	v_mfma_f32_16x16x32_bf16 v[54:57], v[160:163], v[204:207], 0
	v_mfma_f32_16x16x32_bf16 v[46:49], v[170:173], v[204:207], 0
	v_mfma_f32_16x16x32_bf16 v[38:41], v[160:163], v[212:215], 0
	v_mfma_f32_16x16x32_bf16 v[30:33], v[170:173], v[212:215], 0
	v_mfma_f32_16x16x32_bf16 v[22:25], v[160:163], v[220:223], 0
	v_mfma_f32_16x16x32_bf16 v[14:17], v[170:173], v[220:223], 0
	v_mfma_f32_16x16x32_bf16 v[62:65], v[166:169], v[200:203], v[62:65]
	v_mfma_f32_16x16x32_bf16 v[58:61], v[174:177], v[200:203], v[58:61]
	v_mfma_f32_16x16x32_bf16 v[54:57], v[166:169], v[208:211], v[54:57]
	v_mfma_f32_16x16x32_bf16 v[46:49], v[174:177], v[208:211], v[46:49]
	v_mfma_f32_16x16x32_bf16 v[38:41], v[166:169], v[216:219], v[38:41]
	v_mfma_f32_16x16x32_bf16 v[30:33], v[174:177], v[216:219], v[30:33]
	v_mfma_f32_16x16x32_bf16 v[22:25], v[166:169], v[224:227], v[22:25]
	v_mfma_f32_16x16x32_bf16 v[14:17], v[174:177], v[224:227], v[14:17]
	v_mfma_f32_16x16x32_bf16 v[50:53], v[178:181], v[196:199], 0
	v_mfma_f32_16x16x32_bf16 v[42:45], v[188:191], v[196:199], 0
	v_mfma_f32_16x16x32_bf16 v[34:37], v[178:181], v[204:207], 0
	v_mfma_f32_16x16x32_bf16 v[26:29], v[188:191], v[204:207], 0
	v_mfma_f32_16x16x32_bf16 v[18:21], v[178:181], v[212:215], 0
	v_mfma_f32_16x16x32_bf16 v[10:13], v[188:191], v[212:215], 0
	v_mfma_f32_16x16x32_bf16 v[6:9], v[178:181], v[220:223], 0
	v_mfma_f32_16x16x32_bf16 v[2:5], v[188:191], v[220:223], 0
	v_mfma_f32_16x16x32_bf16 v[50:53], v[184:187], v[200:203], v[50:53]
	v_mfma_f32_16x16x32_bf16 v[42:45], v[192:195], v[200:203], v[42:45]
	v_mfma_f32_16x16x32_bf16 v[34:37], v[184:187], v[208:211], v[34:37]
	v_mfma_f32_16x16x32_bf16 v[26:29], v[192:195], v[208:211], v[26:29]
	v_mfma_f32_16x16x32_bf16 v[18:21], v[184:187], v[216:219], v[18:21]
	v_mfma_f32_16x16x32_bf16 v[10:13], v[192:195], v[216:219], v[10:13]
	v_mfma_f32_16x16x32_bf16 v[6:9], v[184:187], v[224:227], v[6:9]
	v_mfma_f32_16x16x32_bf16 v[2:5], v[192:195], v[224:227], v[2:5]
	s_barrier
	s_setprio 0
	s_add_i32 s39, 0, 0x18000
	s_add_i32 s40, 0, 0x1c000
	v_add_u32_e32 v174, s39, v139
	v_add_u32_e32 v192, s40, v139
	s_add_u32 s12, s18, 0x44000
	s_addc_u32 s13, s19, 0
	s_mov_b32 m0, s25
	v_lshl_add_u64 v[236:237], s[12:13], 0, v[130:131]
	global_load_lds_dwordx4 v[236:237], off
	s_mov_b32 m0, s26
	v_lshl_add_u64 v[236:237], s[12:13], 0, v[134:135]
	global_load_lds_dwordx4 v[236:237], off
	ds_read_b128 v[160:163], v174
	ds_read_b128 v[166:169], v174 offset:1024
	ds_read_b128 v[170:173], v174 offset:2048
	ds_read_b128 v[174:177], v174 offset:3072
	ds_read_b128 v[178:181], v192
	ds_read_b128 v[184:187], v192 offset:1024
	ds_read_b128 v[188:191], v192 offset:2048
	ds_read_b128 v[192:195], v192 offset:3072
	ds_read_b128 v[196:199], v165 offset:32768
	ds_read_b128 v[200:203], v165 offset:33792
	ds_read_b128 v[204:207], v165 offset:34816
	ds_read_b128 v[208:211], v165 offset:35840
	ds_read_b128 v[212:215], v165 offset:36864
	ds_read_b128 v[216:219], v165 offset:37888
	ds_read_b128 v[220:223], v165 offset:38912
	ds_read_b128 v[224:227], v165 offset:39936
	s_setprio 1
	s_waitcnt vmcnt(8) lgkmcnt(0)
	s_barrier
	v_mfma_f32_16x16x32_bf16 v[126:129], v[160:163], v[196:199], v[126:129]
	v_mfma_f32_16x16x32_bf16 v[122:125], v[170:173], v[196:199], v[122:125]
	v_mfma_f32_16x16x32_bf16 v[118:121], v[160:163], v[204:207], v[118:121]
	v_mfma_f32_16x16x32_bf16 v[110:113], v[170:173], v[204:207], v[110:113]
	v_mfma_f32_16x16x32_bf16 v[102:105], v[160:163], v[212:215], v[102:105]
	v_mfma_f32_16x16x32_bf16 v[94:97], v[170:173], v[212:215], v[94:97]
	v_mfma_f32_16x16x32_bf16 v[86:89], v[160:163], v[220:223], v[86:89]
	v_mfma_f32_16x16x32_bf16 v[78:81], v[170:173], v[220:223], v[78:81]
	v_mfma_f32_16x16x32_bf16 v[126:129], v[166:169], v[200:203], v[126:129]
	v_mfma_f32_16x16x32_bf16 v[122:125], v[174:177], v[200:203], v[122:125]
	v_mfma_f32_16x16x32_bf16 v[118:121], v[166:169], v[208:211], v[118:121]
	v_mfma_f32_16x16x32_bf16 v[110:113], v[174:177], v[208:211], v[110:113]
	v_mfma_f32_16x16x32_bf16 v[102:105], v[166:169], v[216:219], v[102:105]
	v_mfma_f32_16x16x32_bf16 v[94:97], v[174:177], v[216:219], v[94:97]
	v_mfma_f32_16x16x32_bf16 v[86:89], v[166:169], v[224:227], v[86:89]
	v_mfma_f32_16x16x32_bf16 v[78:81], v[174:177], v[224:227], v[78:81]
	v_mfma_f32_16x16x32_bf16 v[114:117], v[178:181], v[196:199], v[114:117]
	v_mfma_f32_16x16x32_bf16 v[106:109], v[188:191], v[196:199], v[106:109]
	v_mfma_f32_16x16x32_bf16 v[98:101], v[178:181], v[204:207], v[98:101]
	v_mfma_f32_16x16x32_bf16 v[90:93], v[188:191], v[204:207], v[90:93]
	v_mfma_f32_16x16x32_bf16 v[82:85], v[178:181], v[212:215], v[82:85]
	v_mfma_f32_16x16x32_bf16 v[74:77], v[188:191], v[212:215], v[74:77]
	v_mfma_f32_16x16x32_bf16 v[70:73], v[178:181], v[220:223], v[70:73]
	v_mfma_f32_16x16x32_bf16 v[66:69], v[188:191], v[220:223], v[66:69]
	v_mfma_f32_16x16x32_bf16 v[114:117], v[184:187], v[200:203], v[114:117]
	v_mfma_f32_16x16x32_bf16 v[106:109], v[192:195], v[200:203], v[106:109]
	v_mfma_f32_16x16x32_bf16 v[98:101], v[184:187], v[208:211], v[98:101]
	v_mfma_f32_16x16x32_bf16 v[90:93], v[192:195], v[208:211], v[90:93]
	v_mfma_f32_16x16x32_bf16 v[82:85], v[184:187], v[216:219], v[82:85]
	v_mfma_f32_16x16x32_bf16 v[74:77], v[192:195], v[216:219], v[74:77]
	v_mfma_f32_16x16x32_bf16 v[70:73], v[184:187], v[224:227], v[70:73]
	v_mfma_f32_16x16x32_bf16 v[66:69], v[192:195], v[224:227], v[66:69]
	s_barrier
; #define PG8_STAGE(bufoff, gbase, voff) do { _Pragma("unroll") for (int _i = 0; _i < 2; ++_i) \
;         __builtin_amdgcn_global_load_lds((const unsigned*)((const char*)(gbase) + (voff)[_i]), (LAS unsigned*)(lds + (bufoff) + ldsw + _i * 8192), 16, 0, 0); } while (0)
; #define PG8_LDA(dst, b, h) do { _Pragma("unroll") for (int m = 0; m < 4; ++m) _Pragma("unroll") for (int k = 0; k < 2; ++k) dst[m][k] = *(const LAS bf16x8*)(lds + PG8_SA(b, h) + aoff + m * 2048 + k * 1024); } while (0)
; #define PG8_LDB(dst, b, h) do { _Pragma("unroll") for (int n = 0; n < 2; ++n) _Pragma("unroll") for (int k = 0; k < 2; ++k) dst[n][k] = *(const LAS bf16x8*)(lds + PG8_SB(b, h) + boff + n * 2048 + k * 1024); } while (0)
; #define PG8_BAR __builtin_amdgcn_s_barrier()
; template <class Epi, bool ALIGN_EPI = PG8_ALIGN, bool SP2 = PG8_SP2>
; __device__ __forceinline__ void gemm_phase(LAS uchar* lds, const Gemm g, const StaticOrder& S, const Epi& E) {
;     ...
;         for (int t = tb; t < tb + tblk; t += 2) {
;             const bool last = (t == nt - 2);
;             const char* a1 = cA + (size_t)(t + 1) * kstep;
;             const char* a2 = last ? nA : cA + (size_t)(t + 2) * kstep; const char* b2 = last ? nB : cB + (size_t)(t + 2) * kstep;
;             const char* a3 = a2 + kstep; const char* b3 = b2 + kstep;
;             if constexpr (SP2) {
;             PG8_LDB(B0, 0, 0); PG8_LDB(B1, 0, 1); PG8_SCHED; PG8_LDA(At, 0, 0); PG8_STAGE(PG8_SA(1, 1), a1 + hstepA, voffA);
;             PG8_WAIT_V(8); PG8_WAIT_L(0); PG8_BAR; PG8_MMA(0, 0, At, B0); PG8_MMA(0, 1, At, B1); PG8_BAR; PG8_SCHED;
;             PG8_LDA(At, 0, 1); PG8_STAGE(PG8_SB(0, 0), b2, voffB); PG8_STAGE(PG8_SB(0, 1), b2 + hstepB, voffB); PG8_STAGE(PG8_SA(0, 0), a2, voffA);
;             PG8_WAIT_V(8); PG8_WAIT_L(0); PG8_BAR; PG8_MMA(1, 0, At, B0); PG8_MMA(1, 1, At, B1); PG8_BAR; PG8_SCHED;
;             PG8_LDB(B0, 1, 0); PG8_LDB(B1, 1, 1); PG8_SCHED; PG8_LDA(At, 1, 0); PG8_STAGE(PG8_SA(0, 1), a2 + hstepA, voffA);
;             PG8_WAIT_V(8); PG8_WAIT_L(0); PG8_BAR; PG8_MMA(0, 0, At, B0); PG8_MMA(0, 1, At, B1); PG8_BAR; PG8_SCHED;
;             PG8_LDA(At, 1, 1); PG8_STAGE(PG8_SB(1, 0), b3, voffB); PG8_STAGE(PG8_SB(1, 1), b3 + hstepB, voffB); PG8_STAGE(PG8_SA(1, 0), a3, voffA);
;             PG8_WAIT_V(8); PG8_WAIT_L(0); PG8_BAR; PG8_MMA(1, 0, At, B0); PG8_MMA(1, 1, At, B1); PG8_BAR; PG8_SCHED;
	s_setprio 0
	s_add_i32 s12, s39, s22
	s_mov_b32 m0, s12
	v_lshl_add_u64 v[228:229], v[228:229], 0, s[84:85]
	global_load_lds_dwordx4 v[228:229], off
	s_add_i32 m0, s12, 0x2000
	s_add_u32 s12, s16, 0x44080
	v_lshl_add_u64 v[228:229], v[230:231], 0, s[84:85]
	s_addc_u32 s13, s17, 0
	s_add_i32 s16, s40, s22
	global_load_lds_dwordx4 v[228:229], off
	s_mov_b32 m0, s16
	v_lshl_add_u64 v[228:229], s[12:13], 0, v[132:133]
	global_load_lds_dwordx4 v[228:229], off
	s_add_i32 m0, s16, 0x2000
	v_lshl_add_u64 v[228:229], s[12:13], 0, v[152:153]
	global_load_lds_dwordx4 v[228:229], off
	s_mov_b32 m0, s27
	v_lshl_add_u64 v[228:229], v[232:233], 0, s[84:85]
	global_load_lds_dwordx4 v[228:229], off
	s_mov_b32 m0, s28
	v_lshl_add_u64 v[228:229], v[234:235], 0, s[84:85]
	global_load_lds_dwordx4 v[228:229], off
	ds_read_b128 v[196:199], v165 offset:49152
	ds_read_b128 v[200:203], v165 offset:50176
	ds_read_b128 v[204:207], v165 offset:51200
	ds_read_b128 v[208:211], v165 offset:52224
	ds_read_b128 v[212:215], v165 offset:53248
	ds_read_b128 v[216:219], v165 offset:54272
	ds_read_b128 v[220:223], v165 offset:55296
	ds_read_b128 v[224:227], v165 offset:56320
	s_setprio 1
	s_waitcnt vmcnt(8) lgkmcnt(0)
	s_barrier
	v_mfma_f32_16x16x32_bf16 v[62:65], v[160:163], v[196:199], v[62:65]
	v_mfma_f32_16x16x32_bf16 v[58:61], v[170:173], v[196:199], v[58:61]
	v_mfma_f32_16x16x32_bf16 v[54:57], v[160:163], v[204:207], v[54:57]
	v_mfma_f32_16x16x32_bf16 v[46:49], v[170:173], v[204:207], v[46:49]
	v_mfma_f32_16x16x32_bf16 v[38:41], v[160:163], v[212:215], v[38:41]
	v_mfma_f32_16x16x32_bf16 v[30:33], v[170:173], v[212:215], v[30:33]
	v_mfma_f32_16x16x32_bf16 v[22:25], v[160:163], v[220:223], v[22:25]
	v_mfma_f32_16x16x32_bf16 v[14:17], v[170:173], v[220:223], v[14:17]
	v_mfma_f32_16x16x32_bf16 v[62:65], v[166:169], v[200:203], v[62:65]
	v_mfma_f32_16x16x32_bf16 v[58:61], v[174:177], v[200:203], v[58:61]
	v_mfma_f32_16x16x32_bf16 v[54:57], v[166:169], v[208:211], v[54:57]
	v_mfma_f32_16x16x32_bf16 v[46:49], v[174:177], v[208:211], v[46:49]
	v_mfma_f32_16x16x32_bf16 v[38:41], v[166:169], v[216:219], v[38:41]
	v_mfma_f32_16x16x32_bf16 v[30:33], v[174:177], v[216:219], v[30:33]
	v_mfma_f32_16x16x32_bf16 v[22:25], v[166:169], v[224:227], v[22:25]
	v_mfma_f32_16x16x32_bf16 v[14:17], v[174:177], v[224:227], v[14:17]
	v_mfma_f32_16x16x32_bf16 v[50:53], v[178:181], v[196:199], v[50:53]
	v_mfma_f32_16x16x32_bf16 v[42:45], v[188:191], v[196:199], v[42:45]
	v_mfma_f32_16x16x32_bf16 v[34:37], v[178:181], v[204:207], v[34:37]
	v_mfma_f32_16x16x32_bf16 v[26:29], v[188:191], v[204:207], v[26:29]
	v_mfma_f32_16x16x32_bf16 v[18:21], v[178:181], v[212:215], v[18:21]
	v_mfma_f32_16x16x32_bf16 v[10:13], v[188:191], v[212:215], v[10:13]
	v_mfma_f32_16x16x32_bf16 v[6:9], v[178:181], v[220:223], v[6:9]
	v_mfma_f32_16x16x32_bf16 v[2:5], v[188:191], v[220:223], v[2:5]
	v_mfma_f32_16x16x32_bf16 v[50:53], v[184:187], v[200:203], v[50:53]
	v_mfma_f32_16x16x32_bf16 v[42:45], v[192:195], v[200:203], v[42:45]
	v_mfma_f32_16x16x32_bf16 v[34:37], v[184:187], v[208:211], v[34:37]
	v_mfma_f32_16x16x32_bf16 v[26:29], v[192:195], v[208:211], v[26:29]
	v_mfma_f32_16x16x32_bf16 v[18:21], v[184:187], v[216:219], v[18:21]
	v_mfma_f32_16x16x32_bf16 v[10:13], v[192:195], v[216:219], v[10:13]
	v_mfma_f32_16x16x32_bf16 v[6:9], v[184:187], v[224:227], v[6:9]
	v_mfma_f32_16x16x32_bf16 v[2:5], v[192:195], v[224:227], v[2:5]
	s_barrier
	s_setprio 0
	s_add_i32 s38, s38, 2
	s_add_u32 s36, s36, 0x100
	s_addc_u32 s37, s37, 0
	s_cmp_gt_u32 s38, 13
	s_mov_b64 s[12:13], s[14:15]
.LBB0_837:
	s_add_u32 s14, s12, 0x100
	s_addc_u32 s15, s13, 0
	s_add_i32 s39, 0, 0x10000
	s_cmp_eq_u32 s38, 12
	s_cselect_b32 s19, s5, s15
	s_cselect_b32 s18, s4, s14
	s_cselect_b32 s17, s11, s37
	s_cselect_b32 s16, s10, s36
	s_add_i32 s40, 0, 0x14000
	v_add_u32_e32 v174, s39, v139
	v_add_u32_e32 v192, s40, v139
	s_add_i32 m0, s23, 0xc000
	v_lshl_add_u64 v[228:229], s[12:13], 0, v[156:157]
	global_load_lds_dwordx4 v[228:229], off
	s_add_i32 m0, s23, 0xe000
	v_lshl_add_u64 v[228:229], s[12:13], 0, v[158:159]
	global_load_lds_dwordx4 v[228:229], off
	ds_read_b128 v[160:163], v174
	ds_read_b128 v[166:169], v174 offset:1024
	ds_read_b128 v[170:173], v174 offset:2048
	ds_read_b128 v[174:177], v174 offset:3072
	ds_read_b128 v[178:181], v192
	ds_read_b128 v[184:187], v192 offset:1024
	ds_read_b128 v[188:191], v192 offset:2048
	ds_read_b128 v[192:195], v192 offset:3072
	ds_read_b128 v[196:199], v165
	ds_read_b128 v[200:203], v165 offset:1024
	ds_read_b128 v[204:207], v165 offset:2048
	ds_read_b128 v[208:211], v165 offset:3072
	ds_read_b128 v[212:215], v165 offset:4096
	ds_read_b128 v[216:219], v165 offset:5120
	ds_read_b128 v[220:223], v165 offset:6144
	ds_read_b128 v[224:227], v165 offset:7168
	s_setprio 1
	s_waitcnt vmcnt(8) lgkmcnt(0)
	s_barrier
; #define PG8_STAGE(bufoff, gbase, voff) do { _Pragma("unroll") for (int _i = 0; _i < 2; ++_i) \
;         __builtin_amdgcn_global_load_lds((const unsigned*)((const char*)(gbase) + (voff)[_i]), (LAS unsigned*)(lds + (bufoff) + ldsw + _i * 8192), 16, 0, 0); } while (0)
; #define PG8_LDA(dst, b, h) do { _Pragma("unroll") for (int m = 0; m < 4; ++m) _Pragma("unroll") for (int k = 0; k < 2; ++k) dst[m][k] = *(const LAS bf16x8*)(lds + PG8_SA(b, h) + aoff + m * 2048 + k * 1024); } while (0)
; #define PG8_LDB(dst, b, h) do { _Pragma("unroll") for (int n = 0; n < 2; ++n) _Pragma("unroll") for (int k = 0; k < 2; ++k) dst[n][k] = *(const LAS bf16x8*)(lds + PG8_SB(b, h) + boff + n * 2048 + k * 1024); } while (0)
; #define PG8_MMA(ai, bj, At, Bt) do { __builtin_amdgcn_s_setprio(1); _Pragma("unroll") for (int m = 0; m < 4; ++m) _Pragma("unroll") for (int n = 0; n < 2; ++n) _Pragma("unroll") for (int k = 0; k < 2; ++k) \
;         acc[ai][bj][m][n] = __builtin_amdgcn_mfma_f32_16x16x32_bf16(Bt[n][k], At[m][k], acc[ai][bj][m][n], 0, 0, 0); __builtin_amdgcn_s_setprio(0); } while (0)
; #define PG8_WAIT_V(n) asm volatile("s_waitcnt vmcnt(" #n ")" ::: "memory")
; #define PG8_WAIT_L(n) asm volatile("s_waitcnt lgkmcnt(" #n ")" ::: "memory")
; #define PG8_BAR __builtin_amdgcn_s_barrier()
; #define PG8_SCHED __builtin_amdgcn_sched_barrier(0)
; template <class Epi, bool ALIGN_EPI = PG8_ALIGN, bool SP2 = PG8_SP2>
; __device__ __forceinline__ void gemm_phase(LAS uchar* lds, const Gemm g, const StaticOrder& S, const Epi& E) {
;     ...
;             PG8_LDB(B0, 0, 0); PG8_LDB(B1, 0, 1); PG8_SCHED; PG8_LDA(At, 0, 0); PG8_STAGE(PG8_SA(1, 1), a1 + hstepA, voffA);
;             PG8_WAIT_V(8); PG8_WAIT_L(0); PG8_BAR; PG8_MMA(0, 0, At, B0); PG8_MMA(0, 1, At, B1); PG8_BAR; PG8_SCHED;
;             PG8_LDA(At, 0, 1); PG8_STAGE(PG8_SB(0, 0), b2, voffB); PG8_STAGE(PG8_SB(0, 1), b2 + hstepB, voffB); PG8_STAGE(PG8_SA(0, 0), a2, voffA);
;             PG8_WAIT_V(8); PG8_WAIT_L(0); PG8_BAR; PG8_MMA(1, 0, At, B0); PG8_MMA(1, 1, At, B1); PG8_BAR; PG8_SCHED;
	v_mfma_f32_16x16x32_bf16 v[126:129], v[160:163], v[196:199], v[126:129]
	v_mfma_f32_16x16x32_bf16 v[122:125], v[170:173], v[196:199], v[122:125]
	v_mfma_f32_16x16x32_bf16 v[118:121], v[160:163], v[204:207], v[118:121]
	v_mfma_f32_16x16x32_bf16 v[110:113], v[170:173], v[204:207], v[110:113]
	v_mfma_f32_16x16x32_bf16 v[102:105], v[160:163], v[212:215], v[102:105]
	v_mfma_f32_16x16x32_bf16 v[94:97], v[170:173], v[212:215], v[94:97]
	v_mfma_f32_16x16x32_bf16 v[86:89], v[160:163], v[220:223], v[86:89]
	v_mfma_f32_16x16x32_bf16 v[78:81], v[170:173], v[220:223], v[78:81]
	v_mfma_f32_16x16x32_bf16 v[126:129], v[166:169], v[200:203], v[126:129]
	v_mfma_f32_16x16x32_bf16 v[122:125], v[174:177], v[200:203], v[122:125]
	v_mfma_f32_16x16x32_bf16 v[118:121], v[166:169], v[208:211], v[118:121]
	v_mfma_f32_16x16x32_bf16 v[110:113], v[174:177], v[208:211], v[110:113]
	v_mfma_f32_16x16x32_bf16 v[102:105], v[166:169], v[216:219], v[102:105]
	v_mfma_f32_16x16x32_bf16 v[94:97], v[174:177], v[216:219], v[94:97]
	v_mfma_f32_16x16x32_bf16 v[86:89], v[166:169], v[224:227], v[86:89]
	v_mfma_f32_16x16x32_bf16 v[78:81], v[174:177], v[224:227], v[78:81]
	v_mfma_f32_16x16x32_bf16 v[114:117], v[178:181], v[196:199], v[114:117]
	v_mfma_f32_16x16x32_bf16 v[106:109], v[188:191], v[196:199], v[106:109]
	v_mfma_f32_16x16x32_bf16 v[98:101], v[178:181], v[204:207], v[98:101]
	v_mfma_f32_16x16x32_bf16 v[90:93], v[188:191], v[204:207], v[90:93]
	v_mfma_f32_16x16x32_bf16 v[82:85], v[178:181], v[212:215], v[82:85]
	v_mfma_f32_16x16x32_bf16 v[74:77], v[188:191], v[212:215], v[74:77]
	v_mfma_f32_16x16x32_bf16 v[70:73], v[178:181], v[220:223], v[70:73]
	v_mfma_f32_16x16x32_bf16 v[66:69], v[188:191], v[220:223], v[66:69]
	v_mfma_f32_16x16x32_bf16 v[114:117], v[184:187], v[200:203], v[114:117]
	v_mfma_f32_16x16x32_bf16 v[106:109], v[192:195], v[200:203], v[106:109]
	v_mfma_f32_16x16x32_bf16 v[98:101], v[184:187], v[208:211], v[98:101]
	v_mfma_f32_16x16x32_bf16 v[90:93], v[192:195], v[208:211], v[90:93]
	v_mfma_f32_16x16x32_bf16 v[82:85], v[184:187], v[216:219], v[82:85]
	v_mfma_f32_16x16x32_bf16 v[74:77], v[192:195], v[216:219], v[74:77]
	v_mfma_f32_16x16x32_bf16 v[70:73], v[184:187], v[224:227], v[70:73]
	v_mfma_f32_16x16x32_bf16 v[66:69], v[192:195], v[224:227], v[66:69]
	s_barrier
	s_setprio 0
	s_add_i32 s12, s39, s22
	s_mov_b32 m0, s12
	v_lshl_add_u64 v[228:229], s[16:17], 0, v[132:133]
	global_load_lds_dwordx4 v[228:229], off
	s_add_i32 m0, s12, 0x2000
	s_add_u32 s12, s16, 0x44000
	v_lshl_add_u64 v[230:231], s[16:17], 0, v[152:153]
	s_addc_u32 s13, s17, 0
	s_add_i32 s39, s40, s22
	global_load_lds_dwordx4 v[230:231], off
	s_mov_b32 m0, s39
	v_lshl_add_u64 v[232:233], s[12:13], 0, v[132:133]
	global_load_lds_dwordx4 v[232:233], off
	s_add_i32 m0, s39, 0x2000
	v_lshl_add_u64 v[232:233], s[12:13], 0, v[152:153]
	global_load_lds_dwordx4 v[232:233], off
	s_mov_b32 m0, s23
	v_lshl_add_u64 v[232:233], s[18:19], 0, v[130:131]
	global_load_lds_dwordx4 v[232:233], off
	s_mov_b32 m0, s24
	v_lshl_add_u64 v[234:235], s[18:19], 0, v[134:135]
	global_load_lds_dwordx4 v[234:235], off
	ds_read_b128 v[196:199], v165 offset:16384
	ds_read_b128 v[200:203], v165 offset:17408
	ds_read_b128 v[204:207], v165 offset:18432
	ds_read_b128 v[208:211], v165 offset:19456
	ds_read_b128 v[212:215], v165 offset:20480
	ds_read_b128 v[216:219], v165 offset:21504
	ds_read_b128 v[220:223], v165 offset:22528
	ds_read_b128 v[224:227], v165 offset:23552
	s_setprio 1
	s_waitcnt vmcnt(8) lgkmcnt(0)
	s_barrier
	v_mfma_f32_16x16x32_bf16 v[62:65], v[160:163], v[196:199], v[62:65]
	v_mfma_f32_16x16x32_bf16 v[58:61], v[170:173], v[196:199], v[58:61]
	v_mfma_f32_16x16x32_bf16 v[54:57], v[160:163], v[204:207], v[54:57]
	v_mfma_f32_16x16x32_bf16 v[46:49], v[170:173], v[204:207], v[46:49]
	v_mfma_f32_16x16x32_bf16 v[38:41], v[160:163], v[212:215], v[38:41]
	v_mfma_f32_16x16x32_bf16 v[30:33], v[170:173], v[212:215], v[30:33]
	v_mfma_f32_16x16x32_bf16 v[22:25], v[160:163], v[220:223], v[22:25]
	v_mfma_f32_16x16x32_bf16 v[14:17], v[170:173], v[220:223], v[14:17]
	v_mfma_f32_16x16x32_bf16 v[62:65], v[166:169], v[200:203], v[62:65]
	v_mfma_f32_16x16x32_bf16 v[58:61], v[174:177], v[200:203], v[58:61]
	v_mfma_f32_16x16x32_bf16 v[54:57], v[166:169], v[208:211], v[54:57]
	v_mfma_f32_16x16x32_bf16 v[46:49], v[174:177], v[208:211], v[46:49]
	v_mfma_f32_16x16x32_bf16 v[38:41], v[166:169], v[216:219], v[38:41]
	v_mfma_f32_16x16x32_bf16 v[30:33], v[174:177], v[216:219], v[30:33]
	v_mfma_f32_16x16x32_bf16 v[22:25], v[166:169], v[224:227], v[22:25]
	v_mfma_f32_16x16x32_bf16 v[14:17], v[174:177], v[224:227], v[14:17]
	v_mfma_f32_16x16x32_bf16 v[50:53], v[178:181], v[196:199], v[50:53]
	v_mfma_f32_16x16x32_bf16 v[42:45], v[188:191], v[196:199], v[42:45]
	v_mfma_f32_16x16x32_bf16 v[34:37], v[178:181], v[204:207], v[34:37]
	v_mfma_f32_16x16x32_bf16 v[26:29], v[188:191], v[204:207], v[26:29]
	v_mfma_f32_16x16x32_bf16 v[18:21], v[178:181], v[212:215], v[18:21]
	v_mfma_f32_16x16x32_bf16 v[10:13], v[188:191], v[212:215], v[10:13]
	v_mfma_f32_16x16x32_bf16 v[6:9], v[178:181], v[220:223], v[6:9]
	v_mfma_f32_16x16x32_bf16 v[2:5], v[188:191], v[220:223], v[2:5]
	v_mfma_f32_16x16x32_bf16 v[50:53], v[184:187], v[200:203], v[50:53]
	v_mfma_f32_16x16x32_bf16 v[42:45], v[192:195], v[200:203], v[42:45]
	v_mfma_f32_16x16x32_bf16 v[34:37], v[184:187], v[208:211], v[34:37]
	v_mfma_f32_16x16x32_bf16 v[26:29], v[192:195], v[208:211], v[26:29]
	v_mfma_f32_16x16x32_bf16 v[18:21], v[184:187], v[216:219], v[18:21]
	v_mfma_f32_16x16x32_bf16 v[10:13], v[192:195], v[216:219], v[10:13]
	v_mfma_f32_16x16x32_bf16 v[6:9], v[184:187], v[224:227], v[6:9]
	v_mfma_f32_16x16x32_bf16 v[2:5], v[192:195], v[224:227], v[2:5]
	s_barrier
; #define PG8_STAGE(bufoff, gbase, voff) do { _Pragma("unroll") for (int _i = 0; _i < 2; ++_i) \
;         __builtin_amdgcn_global_load_lds((const unsigned*)((const char*)(gbase) + (voff)[_i]), (LAS unsigned*)(lds + (bufoff) + ldsw + _i * 8192), 16, 0, 0); } while (0)
; #define PG8_LDA(dst, b, h) do { _Pragma("unroll") for (int m = 0; m < 4; ++m) _Pragma("unroll") for (int k = 0; k < 2; ++k) dst[m][k] = *(const LAS bf16x8*)(lds + PG8_SA(b, h) + aoff + m * 2048 + k * 1024); } while (0)
; #define PG8_LDB(dst, b, h) do { _Pragma("unroll") for (int n = 0; n < 2; ++n) _Pragma("unroll") for (int k = 0; k < 2; ++k) dst[n][k] = *(const LAS bf16x8*)(lds + PG8_SB(b, h) + boff + n * 2048 + k * 1024); } while (0)
; #define PG8_MMA(ai, bj, At, Bt) do { __builtin_amdgcn_s_setprio(1); _Pragma("unroll") for (int m = 0; m < 4; ++m) _Pragma("unroll") for (int n = 0; n < 2; ++n) _Pragma("unroll") for (int k = 0; k < 2; ++k) \
;         acc[ai][bj][m][n] = __builtin_amdgcn_mfma_f32_16x16x32_bf16(Bt[n][k], At[m][k], acc[ai][bj][m][n], 0, 0, 0); __builtin_amdgcn_s_setprio(0); } while (0)
; #define PG8_WAIT_V(n) asm volatile("s_waitcnt vmcnt(" #n ")" ::: "memory")
; #define PG8_WAIT_L(n) asm volatile("s_waitcnt lgkmcnt(" #n ")" ::: "memory")
; #define PG8_BAR __builtin_amdgcn_s_barrier()
; #define PG8_SCHED __builtin_amdgcn_sched_barrier(0)
; template <class Epi, bool ALIGN_EPI = PG8_ALIGN, bool SP2 = PG8_SP2>
; __device__ __forceinline__ void gemm_phase(LAS uchar* lds, const Gemm g, const StaticOrder& S, const Epi& E) {
;     ...
;             PG8_LDB(B0, 1, 0); PG8_LDB(B1, 1, 1); PG8_SCHED; PG8_LDA(At, 1, 0); PG8_STAGE(PG8_SA(0, 1), a2 + hstepA, voffA);
;             PG8_WAIT_V(8); PG8_WAIT_L(0); PG8_BAR; PG8_MMA(0, 0, At, B0); PG8_MMA(0, 1, At, B1); PG8_BAR; PG8_SCHED;
	s_setprio 0
	s_add_i32 s39, 0, 0x18000
	s_add_i32 s40, 0, 0x1c000
	v_add_u32_e32 v174, s39, v139
	v_add_u32_e32 v192, s40, v139
	s_add_u32 s12, s18, 0x44000
	s_addc_u32 s13, s19, 0
	s_mov_b32 m0, s25
	v_lshl_add_u64 v[236:237], s[12:13], 0, v[130:131]
	global_load_lds_dwordx4 v[236:237], off
	s_mov_b32 m0, s26
	v_lshl_add_u64 v[236:237], s[12:13], 0, v[134:135]
	global_load_lds_dwordx4 v[236:237], off
	ds_read_b128 v[160:163], v174
	ds_read_b128 v[166:169], v174 offset:1024
	ds_read_b128 v[170:173], v174 offset:2048
	ds_read_b128 v[174:177], v174 offset:3072
	ds_read_b128 v[178:181], v192
	ds_read_b128 v[184:187], v192 offset:1024
	ds_read_b128 v[188:191], v192 offset:2048
	ds_read_b128 v[192:195], v192 offset:3072
	ds_read_b128 v[196:199], v165 offset:32768
	ds_read_b128 v[200:203], v165 offset:33792
	ds_read_b128 v[204:207], v165 offset:34816
	ds_read_b128 v[208:211], v165 offset:35840
	ds_read_b128 v[212:215], v165 offset:36864
	ds_read_b128 v[216:219], v165 offset:37888
	ds_read_b128 v[220:223], v165 offset:38912
	ds_read_b128 v[224:227], v165 offset:39936
	s_setprio 1
	s_waitcnt vmcnt(8) lgkmcnt(0)
	s_barrier
	v_mfma_f32_16x16x32_bf16 v[126:129], v[160:163], v[196:199], v[126:129]
	v_mfma_f32_16x16x32_bf16 v[122:125], v[170:173], v[196:199], v[122:125]
	v_mfma_f32_16x16x32_bf16 v[118:121], v[160:163], v[204:207], v[118:121]
	v_mfma_f32_16x16x32_bf16 v[110:113], v[170:173], v[204:207], v[110:113]
	v_mfma_f32_16x16x32_bf16 v[102:105], v[160:163], v[212:215], v[102:105]
	v_mfma_f32_16x16x32_bf16 v[94:97], v[170:173], v[212:215], v[94:97]
	v_mfma_f32_16x16x32_bf16 v[86:89], v[160:163], v[220:223], v[86:89]
	v_mfma_f32_16x16x32_bf16 v[78:81], v[170:173], v[220:223], v[78:81]
	v_mfma_f32_16x16x32_bf16 v[126:129], v[166:169], v[200:203], v[126:129]
	v_mfma_f32_16x16x32_bf16 v[122:125], v[174:177], v[200:203], v[122:125]
	v_mfma_f32_16x16x32_bf16 v[118:121], v[166:169], v[208:211], v[118:121]
	v_mfma_f32_16x16x32_bf16 v[110:113], v[174:177], v[208:211], v[110:113]
	v_mfma_f32_16x16x32_bf16 v[102:105], v[166:169], v[216:219], v[102:105]
	v_mfma_f32_16x16x32_bf16 v[94:97], v[174:177], v[216:219], v[94:97]
	v_mfma_f32_16x16x32_bf16 v[86:89], v[166:169], v[224:227], v[86:89]
	v_mfma_f32_16x16x32_bf16 v[78:81], v[174:177], v[224:227], v[78:81]
	v_mfma_f32_16x16x32_bf16 v[114:117], v[178:181], v[196:199], v[114:117]
	v_mfma_f32_16x16x32_bf16 v[106:109], v[188:191], v[196:199], v[106:109]
	v_mfma_f32_16x16x32_bf16 v[98:101], v[178:181], v[204:207], v[98:101]
	v_mfma_f32_16x16x32_bf16 v[90:93], v[188:191], v[204:207], v[90:93]
	v_mfma_f32_16x16x32_bf16 v[82:85], v[178:181], v[212:215], v[82:85]
	v_mfma_f32_16x16x32_bf16 v[74:77], v[188:191], v[212:215], v[74:77]
	v_mfma_f32_16x16x32_bf16 v[70:73], v[178:181], v[220:223], v[70:73]
	v_mfma_f32_16x16x32_bf16 v[66:69], v[188:191], v[220:223], v[66:69]
	v_mfma_f32_16x16x32_bf16 v[114:117], v[184:187], v[200:203], v[114:117]
	v_mfma_f32_16x16x32_bf16 v[106:109], v[192:195], v[200:203], v[106:109]
	v_mfma_f32_16x16x32_bf16 v[98:101], v[184:187], v[208:211], v[98:101]
	v_mfma_f32_16x16x32_bf16 v[90:93], v[192:195], v[208:211], v[90:93]
	v_mfma_f32_16x16x32_bf16 v[82:85], v[184:187], v[216:219], v[82:85]
	v_mfma_f32_16x16x32_bf16 v[74:77], v[192:195], v[216:219], v[74:77]
	v_mfma_f32_16x16x32_bf16 v[70:73], v[184:187], v[224:227], v[70:73]
	v_mfma_f32_16x16x32_bf16 v[66:69], v[192:195], v[224:227], v[66:69]
	s_barrier
; #define PG8_STAGE(bufoff, gbase, voff) do { _Pragma("unroll") for (int _i = 0; _i < 2; ++_i) \
;         __builtin_amdgcn_global_load_lds((const unsigned*)((const char*)(gbase) + (voff)[_i]), (LAS unsigned*)(lds + (bufoff) + ldsw + _i * 8192), 16, 0, 0); } while (0)
; #define PG8_LDA(dst, b, h) do { _Pragma("unroll") for (int m = 0; m < 4; ++m) _Pragma("unroll") for (int k = 0; k < 2; ++k) dst[m][k] = *(const LAS bf16x8*)(lds + PG8_SA(b, h) + aoff + m * 2048 + k * 1024); } while (0)
; #define PG8_MMA(ai, bj, At, Bt) do { __builtin_amdgcn_s_setprio(1); _Pragma("unroll") for (int m = 0; m < 4; ++m) _Pragma("unroll") for (int n = 0; n < 2; ++n) _Pragma("unroll") for (int k = 0; k < 2; ++k) \
;         acc[ai][bj][m][n] = __builtin_amdgcn_mfma_f32_16x16x32_bf16(Bt[n][k], At[m][k], acc[ai][bj][m][n], 0, 0, 0); __builtin_amdgcn_s_setprio(0); } while (0)
; #define PG8_WAIT_V(n) asm volatile("s_waitcnt vmcnt(" #n ")" ::: "memory")
; #define PG8_WAIT_L(n) asm volatile("s_waitcnt lgkmcnt(" #n ")" ::: "memory")
; #define PG8_BAR __builtin_amdgcn_s_barrier()
; #define PG8_SCHED __builtin_amdgcn_sched_barrier(0)
; template <class Epi, bool ALIGN_EPI = PG8_ALIGN, bool SP2 = PG8_SP2>
; __device__ __forceinline__ void gemm_phase(LAS uchar* lds, const Gemm g, const StaticOrder& S, const Epi& E) {
;     ...
;             PG8_LDA(At, 1, 1); PG8_STAGE(PG8_SB(1, 0), b3, voffB); PG8_STAGE(PG8_SB(1, 1), b3 + hstepB, voffB); PG8_STAGE(PG8_SA(1, 0), a3, voffA);
;             PG8_WAIT_V(8); PG8_WAIT_L(0); PG8_BAR; PG8_MMA(1, 0, At, B0); PG8_MMA(1, 1, At, B1); PG8_BAR; PG8_SCHED;
;     ...
;         if constexpr (ALIGN_EPI) { if (wr == 0) PG8_BAR; }
	s_setprio 0
	s_add_i32 s12, s39, s22
	s_mov_b32 m0, s12
	v_lshl_add_u64 v[228:229], v[228:229], 0, s[84:85]
	global_load_lds_dwordx4 v[228:229], off
	s_add_i32 m0, s12, 0x2000
	s_add_u32 s12, s16, 0x44080
	v_lshl_add_u64 v[228:229], v[230:231], 0, s[84:85]
	s_addc_u32 s13, s17, 0
	s_add_i32 s16, s40, s22
	global_load_lds_dwordx4 v[228:229], off
	s_mov_b32 m0, s16
	v_lshl_add_u64 v[228:229], s[12:13], 0, v[132:133]
	global_load_lds_dwordx4 v[228:229], off
	s_add_i32 m0, s16, 0x2000
	v_lshl_add_u64 v[228:229], s[12:13], 0, v[152:153]
	global_load_lds_dwordx4 v[228:229], off
	s_mov_b32 m0, s27
	v_lshl_add_u64 v[228:229], v[232:233], 0, s[84:85]
	global_load_lds_dwordx4 v[228:229], off
	s_mov_b32 m0, s28
	v_lshl_add_u64 v[228:229], v[234:235], 0, s[84:85]
	global_load_lds_dwordx4 v[228:229], off
	ds_read_b128 v[196:199], v165 offset:49152
	ds_read_b128 v[200:203], v165 offset:50176
	ds_read_b128 v[204:207], v165 offset:51200
	ds_read_b128 v[208:211], v165 offset:52224
	ds_read_b128 v[212:215], v165 offset:53248
	ds_read_b128 v[216:219], v165 offset:54272
	ds_read_b128 v[220:223], v165 offset:55296
	ds_read_b128 v[224:227], v165 offset:56320
	s_setprio 1
	s_waitcnt vmcnt(8) lgkmcnt(0)
	s_barrier
	v_mfma_f32_16x16x32_bf16 v[62:65], v[160:163], v[196:199], v[62:65]
	v_mfma_f32_16x16x32_bf16 v[58:61], v[170:173], v[196:199], v[58:61]
	v_mfma_f32_16x16x32_bf16 v[54:57], v[160:163], v[204:207], v[54:57]
	v_mfma_f32_16x16x32_bf16 v[46:49], v[170:173], v[204:207], v[46:49]
	v_mfma_f32_16x16x32_bf16 v[38:41], v[160:163], v[212:215], v[38:41]
	v_mfma_f32_16x16x32_bf16 v[30:33], v[170:173], v[212:215], v[30:33]
	v_mfma_f32_16x16x32_bf16 v[22:25], v[160:163], v[220:223], v[22:25]
	v_mfma_f32_16x16x32_bf16 v[14:17], v[170:173], v[220:223], v[14:17]
	v_mfma_f32_16x16x32_bf16 v[62:65], v[166:169], v[200:203], v[62:65]
	v_mfma_f32_16x16x32_bf16 v[58:61], v[174:177], v[200:203], v[58:61]
	v_mfma_f32_16x16x32_bf16 v[54:57], v[166:169], v[208:211], v[54:57]
	v_mfma_f32_16x16x32_bf16 v[46:49], v[174:177], v[208:211], v[46:49]
	v_mfma_f32_16x16x32_bf16 v[38:41], v[166:169], v[216:219], v[38:41]
	v_mfma_f32_16x16x32_bf16 v[30:33], v[174:177], v[216:219], v[30:33]
	v_mfma_f32_16x16x32_bf16 v[22:25], v[166:169], v[224:227], v[22:25]
	v_mfma_f32_16x16x32_bf16 v[14:17], v[174:177], v[224:227], v[14:17]
	v_mfma_f32_16x16x32_bf16 v[50:53], v[178:181], v[196:199], v[50:53]
	v_mfma_f32_16x16x32_bf16 v[42:45], v[188:191], v[196:199], v[42:45]
	v_mfma_f32_16x16x32_bf16 v[34:37], v[178:181], v[204:207], v[34:37]
	v_mfma_f32_16x16x32_bf16 v[26:29], v[188:191], v[204:207], v[26:29]
	v_mfma_f32_16x16x32_bf16 v[18:21], v[178:181], v[212:215], v[18:21]
	v_mfma_f32_16x16x32_bf16 v[10:13], v[188:191], v[212:215], v[10:13]
	v_mfma_f32_16x16x32_bf16 v[6:9], v[178:181], v[220:223], v[6:9]
	v_mfma_f32_16x16x32_bf16 v[2:5], v[188:191], v[220:223], v[2:5]
	v_mfma_f32_16x16x32_bf16 v[50:53], v[184:187], v[200:203], v[50:53]
	v_mfma_f32_16x16x32_bf16 v[42:45], v[192:195], v[200:203], v[42:45]
	v_mfma_f32_16x16x32_bf16 v[34:37], v[184:187], v[208:211], v[34:37]
	v_mfma_f32_16x16x32_bf16 v[26:29], v[192:195], v[208:211], v[26:29]
	v_mfma_f32_16x16x32_bf16 v[18:21], v[184:187], v[216:219], v[18:21]
	v_mfma_f32_16x16x32_bf16 v[10:13], v[192:195], v[216:219], v[10:13]
	v_mfma_f32_16x16x32_bf16 v[6:9], v[184:187], v[224:227], v[6:9]
	v_mfma_f32_16x16x32_bf16 v[2:5], v[192:195], v[224:227], v[2:5]
	s_barrier
	s_setprio 0
	s_add_i32 s38, s38, 2
	s_add_u32 s36, s36, 0x100
	s_addc_u32 s37, s37, 0
	s_cmp_gt_u32 s38, 13
	s_mov_b64 s[12:13], s[14:15]
	s_cbranch_scc0 .LBB0_837
	s_and_b64 vcc, exec, s[8:9]
	s_cbranch_vccz .LBB0_840
	s_barrier

; #define PG8_STAGE(bufoff, gbase, voff) do { _Pragma("unroll") for (int _i = 0; _i < 2; ++_i) \
;         __builtin_amdgcn_global_load_lds((const unsigned*)((const char*)(gbase) + (voff)[_i]), (LAS unsigned*)(lds + (bufoff) + ldsw + _i * 8192), 16, 0, 0); } while (0)
; #define PG8_LDA(dst, b, h) do { _Pragma("unroll") for (int m = 0; m < 4; ++m) _Pragma("unroll") for (int k = 0; k < 2; ++k) dst[m][k] = *(const LAS bf16x8*)(lds + PG8_SA(b, h) + aoff + m * 2048 + k * 1024); } while (0)
; #define PG8_LDB(dst, b, h) do { _Pragma("unroll") for (int n = 0; n < 2; ++n) _Pragma("unroll") for (int k = 0; k < 2; ++k) dst[n][k] = *(const LAS bf16x8*)(lds + PG8_SB(b, h) + boff + n * 2048 + k * 1024); } while (0)
; #define PG8_MMA(ai, bj, At, Bt) do { __builtin_amdgcn_s_setprio(1); _Pragma("unroll") for (int m = 0; m < 4; ++m) _Pragma("unroll") for (int n = 0; n < 2; ++n) _Pragma("unroll") for (int k = 0; k < 2; ++k) \
;         acc[ai][bj][m][n] = __builtin_amdgcn_mfma_f32_16x16x32_bf16(Bt[n][k], At[m][k], acc[ai][bj][m][n], 0, 0, 0); __builtin_amdgcn_s_setprio(0); } while (0)
; #define PG8_WAIT_V(n) asm volatile("s_waitcnt vmcnt(" #n ")" ::: "memory")
; #define PG8_WAIT_L(n) asm volatile("s_waitcnt lgkmcnt(" #n ")" ::: "memory")
; #define PG8_BAR __builtin_amdgcn_s_barrier()
; #define PG8_SCHED __builtin_amdgcn_sched_barrier(0)
; template <class Epi, bool ALIGN_EPI = PG8_ALIGN, bool SP2 = PG8_SP2>
; __device__ __forceinline__ void gemm_phase(LAS uchar* lds, const Gemm g, const StaticOrder& S, const Epi& E) {
;     ...
;             PG8_LDB(B0, 0, 0); PG8_LDB(B1, 0, 1); PG8_SCHED; PG8_LDA(At, 0, 0); PG8_STAGE(PG8_SA(1, 1), a1 + hstepA, voffA);
;             PG8_WAIT_V(8); PG8_WAIT_L(0); PG8_BAR; PG8_MMA(0, 0, At, B0); PG8_MMA(0, 1, At, B1); PG8_BAR; PG8_SCHED;
;             PG8_LDA(At, 0, 1); PG8_STAGE(PG8_SB(0, 0), b2, voffB); PG8_STAGE(PG8_SB(0, 1), b2 + hstepB, voffB); PG8_STAGE(PG8_SA(0, 0), a2, voffA);
;             PG8_WAIT_V(8); PG8_WAIT_L(0); PG8_BAR; PG8_MMA(1, 0, At, B0); PG8_MMA(1, 1, At, B1); PG8_BAR; PG8_SCHED;
.Lrw_done_1050_0_pl:
	s_waitcnt lgkmcnt(0)
	s_setprio 1
	s_barrier
	v_mfma_f32_16x16x32_bf16 v[126:129], v[164:167], v[200:203], 0
	v_mfma_f32_16x16x32_bf16 v[118:121], v[172:175], v[200:203], 0
	v_mfma_f32_16x16x32_bf16 v[110:113], v[164:167], v[208:211], 0
	v_mfma_f32_16x16x32_bf16 v[102:105], v[172:175], v[208:211], 0
	v_mfma_f32_16x16x32_bf16 v[94:97], v[164:167], v[216:219], 0
	v_mfma_f32_16x16x32_bf16 v[86:89], v[172:175], v[216:219], 0
	v_mfma_f32_16x16x32_bf16 v[78:81], v[164:167], v[224:227], 0
	v_mfma_f32_16x16x32_bf16 v[70:73], v[172:175], v[224:227], 0
	v_mfma_f32_16x16x32_bf16 v[126:129], v[168:171], v[204:207], v[126:129]
	v_mfma_f32_16x16x32_bf16 v[118:121], v[176:179], v[204:207], v[118:121]
	v_mfma_f32_16x16x32_bf16 v[110:113], v[168:171], v[212:215], v[110:113]
	v_mfma_f32_16x16x32_bf16 v[102:105], v[176:179], v[212:215], v[102:105]
	v_mfma_f32_16x16x32_bf16 v[94:97], v[168:171], v[220:223], v[94:97]
	v_mfma_f32_16x16x32_bf16 v[86:89], v[176:179], v[220:223], v[86:89]
	v_mfma_f32_16x16x32_bf16 v[78:81], v[168:171], v[228:231], v[78:81]
	v_mfma_f32_16x16x32_bf16 v[70:73], v[176:179], v[228:231], v[70:73]
	v_mfma_f32_16x16x32_bf16 v[122:125], v[184:187], v[200:203], 0
	v_mfma_f32_16x16x32_bf16 v[114:117], v[192:195], v[200:203], 0
	v_mfma_f32_16x16x32_bf16 v[106:109], v[184:187], v[208:211], 0
	v_mfma_f32_16x16x32_bf16 v[98:101], v[192:195], v[208:211], 0
	v_mfma_f32_16x16x32_bf16 v[90:93], v[184:187], v[216:219], 0
	v_mfma_f32_16x16x32_bf16 v[82:85], v[192:195], v[216:219], 0
	v_mfma_f32_16x16x32_bf16 v[74:77], v[184:187], v[224:227], 0
	v_mfma_f32_16x16x32_bf16 v[66:69], v[192:195], v[224:227], 0
	v_mfma_f32_16x16x32_bf16 v[122:125], v[188:191], v[204:207], v[122:125]
	v_mfma_f32_16x16x32_bf16 v[114:117], v[196:199], v[204:207], v[114:117]
	v_mfma_f32_16x16x32_bf16 v[106:109], v[188:191], v[212:215], v[106:109]
	v_mfma_f32_16x16x32_bf16 v[98:101], v[196:199], v[212:215], v[98:101]
	v_mfma_f32_16x16x32_bf16 v[90:93], v[188:191], v[220:223], v[90:93]
	v_mfma_f32_16x16x32_bf16 v[82:85], v[196:199], v[220:223], v[82:85]
	v_mfma_f32_16x16x32_bf16 v[74:77], v[188:191], v[228:231], v[74:77]
	v_mfma_f32_16x16x32_bf16 v[66:69], v[196:199], v[228:231], v[66:69]
	s_barrier
	s_setprio 0
	s_add_i32 s12, s39, s21
	v_lshl_add_u64 v[160:161], s[16:17], 0, v[134:135]
	s_mov_b32 m0, s12
	ds_read_b128 v[200:203], v163 offset:16384
	ds_read_b128 v[204:207], v163 offset:17408
	ds_read_b128 v[208:211], v163 offset:18432
	ds_read_b128 v[212:215], v163 offset:19456
	ds_read_b128 v[216:219], v163 offset:20480
	ds_read_b128 v[220:223], v163 offset:21504
	ds_read_b128 v[224:227], v163 offset:22528
	ds_read_b128 v[228:231], v163 offset:23552
	global_load_lds_dwordx4 v[160:161], off
	s_add_i32 m0, s12, 0x2000
	s_add_u32 s12, s16, 0x44000
	v_lshl_add_u64 v[180:181], s[16:17], 0, v[130:131]
	s_addc_u32 s13, s17, 0
	s_add_i32 s39, s40, s21
	global_load_lds_dwordx4 v[180:181], off
	s_mov_b32 m0, s39
	v_lshl_add_u64 v[232:233], s[12:13], 0, v[134:135]
	global_load_lds_dwordx4 v[232:233], off
	s_add_i32 m0, s39, 0x2000
	v_lshl_add_u64 v[232:233], s[12:13], 0, v[130:131]
	global_load_lds_dwordx4 v[232:233], off
	s_mov_b32 m0, s23
	v_lshl_add_u64 v[232:233], s[18:19], 0, v[154:155]
	global_load_lds_dwordx4 v[232:233], off
	s_mov_b32 m0, s24
	v_lshl_add_u64 v[234:235], s[18:19], 0, v[132:133]
	global_load_lds_dwordx4 v[234:235], off
	s_cmp_lt_u32 s29, 2
	s_cbranch_scc1 .Lrw_std_1050_1_pl
	s_waitcnt vmcnt(16)
	s_branch .Lrw_done_1050_1_pl

; #define PG8_STAGE(bufoff, gbase, voff) do { _Pragma("unroll") for (int _i = 0; _i < 2; ++_i) \
;         __builtin_amdgcn_global_load_lds((const unsigned*)((const char*)(gbase) + (voff)[_i]), (LAS unsigned*)(lds + (bufoff) + ldsw + _i * 8192), 16, 0, 0); } while (0)
; #define PG8_LDA(dst, b, h) do { _Pragma("unroll") for (int m = 0; m < 4; ++m) _Pragma("unroll") for (int k = 0; k < 2; ++k) dst[m][k] = *(const LAS bf16x8*)(lds + PG8_SA(b, h) + aoff + m * 2048 + k * 1024); } while (0)
; #define PG8_LDB(dst, b, h) do { _Pragma("unroll") for (int n = 0; n < 2; ++n) _Pragma("unroll") for (int k = 0; k < 2; ++k) dst[n][k] = *(const LAS bf16x8*)(lds + PG8_SB(b, h) + boff + n * 2048 + k * 1024); } while (0)
; #define PG8_MMA(ai, bj, At, Bt) do { __builtin_amdgcn_s_setprio(1); _Pragma("unroll") for (int m = 0; m < 4; ++m) _Pragma("unroll") for (int n = 0; n < 2; ++n) _Pragma("unroll") for (int k = 0; k < 2; ++k) \
;         acc[ai][bj][m][n] = __builtin_amdgcn_mfma_f32_16x16x32_bf16(Bt[n][k], At[m][k], acc[ai][bj][m][n], 0, 0, 0); __builtin_amdgcn_s_setprio(0); } while (0)
; #define PG8_WAIT_V(n) asm volatile("s_waitcnt vmcnt(" #n ")" ::: "memory")
; #define PG8_WAIT_L(n) asm volatile("s_waitcnt lgkmcnt(" #n ")" ::: "memory")
; #define PG8_BAR __builtin_amdgcn_s_barrier()
; #define PG8_SCHED __builtin_amdgcn_sched_barrier(0)
; template <class Epi, bool ALIGN_EPI = PG8_ALIGN, bool SP2 = PG8_SP2>
; __device__ __forceinline__ void gemm_phase(LAS uchar* lds, const Gemm g, const StaticOrder& S, const Epi& E) {
;     ...
;             PG8_WAIT_V(8); PG8_WAIT_L(0); PG8_BAR; PG8_MMA(1, 0, At, B0); PG8_MMA(1, 1, At, B1); PG8_BAR; PG8_SCHED;
;             PG8_LDB(B0, 1, 0); PG8_LDB(B1, 1, 1); PG8_SCHED; PG8_LDA(At, 1, 0); PG8_STAGE(PG8_SA(0, 1), a2 + hstepA, voffA);
;             PG8_WAIT_V(8); PG8_WAIT_L(0); PG8_BAR; PG8_MMA(0, 0, At, B0); PG8_MMA(0, 1, At, B1); PG8_BAR; PG8_SCHED;
.Lrw_done_1050_1_pl:
	s_waitcnt lgkmcnt(0)
	s_setprio 1
	s_barrier
	v_mfma_f32_16x16x32_bf16 v[62:65], v[164:167], v[200:203], 0
	v_mfma_f32_16x16x32_bf16 v[54:57], v[172:175], v[200:203], 0
	v_mfma_f32_16x16x32_bf16 v[46:49], v[164:167], v[208:211], 0
	v_mfma_f32_16x16x32_bf16 v[38:41], v[172:175], v[208:211], 0
	v_mfma_f32_16x16x32_bf16 v[30:33], v[164:167], v[216:219], 0
	v_mfma_f32_16x16x32_bf16 v[22:25], v[172:175], v[216:219], 0
	v_mfma_f32_16x16x32_bf16 v[14:17], v[164:167], v[224:227], 0
	v_mfma_f32_16x16x32_bf16 v[6:9], v[172:175], v[224:227], 0
	v_mfma_f32_16x16x32_bf16 v[62:65], v[168:171], v[204:207], v[62:65]
	v_mfma_f32_16x16x32_bf16 v[54:57], v[176:179], v[204:207], v[54:57]
	v_mfma_f32_16x16x32_bf16 v[46:49], v[168:171], v[212:215], v[46:49]
	v_mfma_f32_16x16x32_bf16 v[38:41], v[176:179], v[212:215], v[38:41]
	v_mfma_f32_16x16x32_bf16 v[30:33], v[168:171], v[220:223], v[30:33]
	v_mfma_f32_16x16x32_bf16 v[22:25], v[176:179], v[220:223], v[22:25]
	v_mfma_f32_16x16x32_bf16 v[14:17], v[168:171], v[228:231], v[14:17]
	v_mfma_f32_16x16x32_bf16 v[6:9], v[176:179], v[228:231], v[6:9]
	v_mfma_f32_16x16x32_bf16 v[58:61], v[184:187], v[200:203], 0
	v_mfma_f32_16x16x32_bf16 v[50:53], v[192:195], v[200:203], 0
	v_mfma_f32_16x16x32_bf16 v[42:45], v[184:187], v[208:211], 0
	v_mfma_f32_16x16x32_bf16 v[34:37], v[192:195], v[208:211], 0
	v_mfma_f32_16x16x32_bf16 v[26:29], v[184:187], v[216:219], 0
	v_mfma_f32_16x16x32_bf16 v[18:21], v[192:195], v[216:219], 0
	v_mfma_f32_16x16x32_bf16 v[10:13], v[184:187], v[224:227], 0
	v_mfma_f32_16x16x32_bf16 v[2:5], v[192:195], v[224:227], 0
	v_mfma_f32_16x16x32_bf16 v[58:61], v[188:191], v[204:207], v[58:61]
	v_mfma_f32_16x16x32_bf16 v[50:53], v[196:199], v[204:207], v[50:53]
	v_mfma_f32_16x16x32_bf16 v[42:45], v[188:191], v[212:215], v[42:45]
	v_mfma_f32_16x16x32_bf16 v[34:37], v[196:199], v[212:215], v[34:37]
	v_mfma_f32_16x16x32_bf16 v[26:29], v[188:191], v[220:223], v[26:29]
	v_mfma_f32_16x16x32_bf16 v[18:21], v[196:199], v[220:223], v[18:21]
	v_mfma_f32_16x16x32_bf16 v[10:13], v[188:191], v[228:231], v[10:13]
	v_mfma_f32_16x16x32_bf16 v[2:5], v[196:199], v[228:231], v[2:5]
	s_barrier
	s_setprio 0
	s_add_i32 s39, 0, 0x18000
	v_add_u32_e32 v144, s39, v139
	s_add_i32 s40, 0, 0x1c000
	ds_read_b128 v[164:167], v144
	ds_read_b128 v[168:171], v144 offset:1024
	ds_read_b128 v[172:175], v144 offset:2048
	ds_read_b128 v[176:179], v144 offset:3072
	v_add_u32_e32 v144, s40, v139
	s_add_u32 s12, s18, 0x44000
	s_addc_u32 s13, s19, 0
	s_mov_b32 m0, s25
	v_lshl_add_u64 v[236:237], s[12:13], 0, v[154:155]
	global_load_lds_dwordx4 v[236:237], off
	s_mov_b32 m0, s26
	v_lshl_add_u64 v[236:237], s[12:13], 0, v[132:133]
	global_load_lds_dwordx4 v[236:237], off
	ds_read_b128 v[184:187], v144
	ds_read_b128 v[188:191], v144 offset:1024
	ds_read_b128 v[192:195], v144 offset:2048
	ds_read_b128 v[196:199], v144 offset:3072
	ds_read_b128 v[200:203], v163 offset:32768
	ds_read_b128 v[204:207], v163 offset:33792
	ds_read_b128 v[208:211], v163 offset:34816
	ds_read_b128 v[212:215], v163 offset:35840
	ds_read_b128 v[216:219], v163 offset:36864
	ds_read_b128 v[220:223], v163 offset:37888
	ds_read_b128 v[224:227], v163 offset:38912
	ds_read_b128 v[228:231], v163 offset:39936
	s_setprio 1
	s_waitcnt vmcnt(8) lgkmcnt(0)
	s_barrier
	v_mfma_f32_16x16x32_bf16 v[126:129], v[164:167], v[200:203], v[126:129]
	v_mfma_f32_16x16x32_bf16 v[118:121], v[172:175], v[200:203], v[118:121]
	v_mfma_f32_16x16x32_bf16 v[110:113], v[164:167], v[208:211], v[110:113]
	v_mfma_f32_16x16x32_bf16 v[102:105], v[172:175], v[208:211], v[102:105]
	v_mfma_f32_16x16x32_bf16 v[94:97], v[164:167], v[216:219], v[94:97]
	v_mfma_f32_16x16x32_bf16 v[86:89], v[172:175], v[216:219], v[86:89]
	v_mfma_f32_16x16x32_bf16 v[78:81], v[164:167], v[224:227], v[78:81]
	v_mfma_f32_16x16x32_bf16 v[70:73], v[172:175], v[224:227], v[70:73]
	v_mfma_f32_16x16x32_bf16 v[126:129], v[168:171], v[204:207], v[126:129]
	v_mfma_f32_16x16x32_bf16 v[118:121], v[176:179], v[204:207], v[118:121]
	v_mfma_f32_16x16x32_bf16 v[110:113], v[168:171], v[212:215], v[110:113]
	v_mfma_f32_16x16x32_bf16 v[102:105], v[176:179], v[212:215], v[102:105]
	v_mfma_f32_16x16x32_bf16 v[94:97], v[168:171], v[220:223], v[94:97]
	v_mfma_f32_16x16x32_bf16 v[86:89], v[176:179], v[220:223], v[86:89]
	v_mfma_f32_16x16x32_bf16 v[78:81], v[168:171], v[228:231], v[78:81]
	v_mfma_f32_16x16x32_bf16 v[70:73], v[176:179], v[228:231], v[70:73]
	v_mfma_f32_16x16x32_bf16 v[122:125], v[184:187], v[200:203], v[122:125]
	v_mfma_f32_16x16x32_bf16 v[114:117], v[192:195], v[200:203], v[114:117]
	v_mfma_f32_16x16x32_bf16 v[106:109], v[184:187], v[208:211], v[106:109]
	v_mfma_f32_16x16x32_bf16 v[98:101], v[192:195], v[208:211], v[98:101]
	v_mfma_f32_16x16x32_bf16 v[90:93], v[184:187], v[216:219], v[90:93]
	v_mfma_f32_16x16x32_bf16 v[82:85], v[192:195], v[216:219], v[82:85]
	v_mfma_f32_16x16x32_bf16 v[74:77], v[184:187], v[224:227], v[74:77]
	v_mfma_f32_16x16x32_bf16 v[66:69], v[192:195], v[224:227], v[66:69]
	v_mfma_f32_16x16x32_bf16 v[122:125], v[188:191], v[204:207], v[122:125]
	v_mfma_f32_16x16x32_bf16 v[114:117], v[196:199], v[204:207], v[114:117]
	v_mfma_f32_16x16x32_bf16 v[106:109], v[188:191], v[212:215], v[106:109]
	v_mfma_f32_16x16x32_bf16 v[98:101], v[196:199], v[212:215], v[98:101]
	v_mfma_f32_16x16x32_bf16 v[90:93], v[188:191], v[220:223], v[90:93]
	v_mfma_f32_16x16x32_bf16 v[82:85], v[196:199], v[220:223], v[82:85]
	v_mfma_f32_16x16x32_bf16 v[74:77], v[188:191], v[228:231], v[74:77]
	v_mfma_f32_16x16x32_bf16 v[66:69], v[196:199], v[228:231], v[66:69]
	s_barrier
; #define PG8_STAGE(bufoff, gbase, voff) do { _Pragma("unroll") for (int _i = 0; _i < 2; ++_i) \
;         __builtin_amdgcn_global_load_lds((const unsigned*)((const char*)(gbase) + (voff)[_i]), (LAS unsigned*)(lds + (bufoff) + ldsw + _i * 8192), 16, 0, 0); } while (0)
; #define PG8_LDA(dst, b, h) do { _Pragma("unroll") for (int m = 0; m < 4; ++m) _Pragma("unroll") for (int k = 0; k < 2; ++k) dst[m][k] = *(const LAS bf16x8*)(lds + PG8_SA(b, h) + aoff + m * 2048 + k * 1024); } while (0)
; #define PG8_LDB(dst, b, h) do { _Pragma("unroll") for (int n = 0; n < 2; ++n) _Pragma("unroll") for (int k = 0; k < 2; ++k) dst[n][k] = *(const LAS bf16x8*)(lds + PG8_SB(b, h) + boff + n * 2048 + k * 1024); } while (0)
; #define PG8_BAR __builtin_amdgcn_s_barrier()
; template <class Epi, bool ALIGN_EPI = PG8_ALIGN, bool SP2 = PG8_SP2>
; __device__ __forceinline__ void gemm_phase(LAS uchar* lds, const Gemm g, const StaticOrder& S, const Epi& E) {
;     ...
;         for (int t = tb; t < tb + tblk; t += 2) {
;             const bool last = (t == nt - 2);
;             const char* a1 = cA + (size_t)(t + 1) * kstep;
;             const char* a2 = last ? nA : cA + (size_t)(t + 2) * kstep; const char* b2 = last ? nB : cB + (size_t)(t + 2) * kstep;
;             const char* a3 = a2 + kstep; const char* b3 = b2 + kstep;
;             if constexpr (SP2) {
;             PG8_LDB(B0, 0, 0); PG8_LDB(B1, 0, 1); PG8_SCHED; PG8_LDA(At, 0, 0); PG8_STAGE(PG8_SA(1, 1), a1 + hstepA, voffA);
;             PG8_WAIT_V(8); PG8_WAIT_L(0); PG8_BAR; PG8_MMA(0, 0, At, B0); PG8_MMA(0, 1, At, B1); PG8_BAR; PG8_SCHED;
;             PG8_LDA(At, 0, 1); PG8_STAGE(PG8_SB(0, 0), b2, voffB); PG8_STAGE(PG8_SB(0, 1), b2 + hstepB, voffB); PG8_STAGE(PG8_SA(0, 0), a2, voffA);
;             PG8_WAIT_V(8); PG8_WAIT_L(0); PG8_BAR; PG8_MMA(1, 0, At, B0); PG8_MMA(1, 1, At, B1); PG8_BAR; PG8_SCHED;
;             PG8_LDB(B0, 1, 0); PG8_LDB(B1, 1, 1); PG8_SCHED; PG8_LDA(At, 1, 0); PG8_STAGE(PG8_SA(0, 1), a2 + hstepA, voffA);
;             PG8_WAIT_V(8); PG8_WAIT_L(0); PG8_BAR; PG8_MMA(0, 0, At, B0); PG8_MMA(0, 1, At, B1); PG8_BAR; PG8_SCHED;
;             PG8_LDA(At, 1, 1); PG8_STAGE(PG8_SB(1, 0), b3, voffB); PG8_STAGE(PG8_SB(1, 1), b3 + hstepB, voffB); PG8_STAGE(PG8_SA(1, 0), a3, voffA);
;             PG8_WAIT_V(8); PG8_WAIT_L(0); PG8_BAR; PG8_MMA(1, 0, At, B0); PG8_MMA(1, 1, At, B1); PG8_BAR; PG8_SCHED;
	s_setprio 0
	s_add_i32 s12, s39, s21
	s_mov_b32 m0, s12
	v_lshl_add_u64 v[160:161], v[160:161], 0, s[84:85]
	global_load_lds_dwordx4 v[160:161], off
	s_add_i32 m0, s12, 0x2000
	s_add_u32 s12, s16, 0x44080
	v_lshl_add_u64 v[160:161], v[180:181], 0, s[84:85]
	s_addc_u32 s13, s17, 0
	s_add_i32 s16, s40, s21
	global_load_lds_dwordx4 v[160:161], off
	s_mov_b32 m0, s16
	v_lshl_add_u64 v[160:161], s[12:13], 0, v[134:135]
	global_load_lds_dwordx4 v[160:161], off
	s_add_i32 m0, s16, 0x2000
	v_lshl_add_u64 v[160:161], s[12:13], 0, v[130:131]
	global_load_lds_dwordx4 v[160:161], off
	s_mov_b32 m0, s27
	v_lshl_add_u64 v[160:161], v[232:233], 0, s[84:85]
	global_load_lds_dwordx4 v[160:161], off
	s_mov_b32 m0, s28
	v_lshl_add_u64 v[160:161], v[234:235], 0, s[84:85]
	global_load_lds_dwordx4 v[160:161], off
	ds_read_b128 v[200:203], v163 offset:49152
	ds_read_b128 v[204:207], v163 offset:50176
	ds_read_b128 v[208:211], v163 offset:51200
	ds_read_b128 v[212:215], v163 offset:52224
	ds_read_b128 v[216:219], v163 offset:53248
	ds_read_b128 v[220:223], v163 offset:54272
	ds_read_b128 v[224:227], v163 offset:55296
	ds_read_b128 v[228:231], v163 offset:56320
	s_setprio 1
	s_waitcnt vmcnt(8) lgkmcnt(0)
	s_barrier
	v_mfma_f32_16x16x32_bf16 v[62:65], v[164:167], v[200:203], v[62:65]
	v_mfma_f32_16x16x32_bf16 v[54:57], v[172:175], v[200:203], v[54:57]
	v_mfma_f32_16x16x32_bf16 v[46:49], v[164:167], v[208:211], v[46:49]
	v_mfma_f32_16x16x32_bf16 v[38:41], v[172:175], v[208:211], v[38:41]
	v_mfma_f32_16x16x32_bf16 v[30:33], v[164:167], v[216:219], v[30:33]
	v_mfma_f32_16x16x32_bf16 v[22:25], v[172:175], v[216:219], v[22:25]
	v_mfma_f32_16x16x32_bf16 v[14:17], v[164:167], v[224:227], v[14:17]
	v_mfma_f32_16x16x32_bf16 v[6:9], v[172:175], v[224:227], v[6:9]
	v_mfma_f32_16x16x32_bf16 v[62:65], v[168:171], v[204:207], v[62:65]
	v_mfma_f32_16x16x32_bf16 v[54:57], v[176:179], v[204:207], v[54:57]
	v_mfma_f32_16x16x32_bf16 v[46:49], v[168:171], v[212:215], v[46:49]
	v_mfma_f32_16x16x32_bf16 v[38:41], v[176:179], v[212:215], v[38:41]
	v_mfma_f32_16x16x32_bf16 v[30:33], v[168:171], v[220:223], v[30:33]
	v_mfma_f32_16x16x32_bf16 v[22:25], v[176:179], v[220:223], v[22:25]
	v_mfma_f32_16x16x32_bf16 v[14:17], v[168:171], v[228:231], v[14:17]
	v_mfma_f32_16x16x32_bf16 v[6:9], v[176:179], v[228:231], v[6:9]
	v_mfma_f32_16x16x32_bf16 v[58:61], v[184:187], v[200:203], v[58:61]
	v_mfma_f32_16x16x32_bf16 v[50:53], v[192:195], v[200:203], v[50:53]
	v_mfma_f32_16x16x32_bf16 v[42:45], v[184:187], v[208:211], v[42:45]
	v_mfma_f32_16x16x32_bf16 v[34:37], v[192:195], v[208:211], v[34:37]
	v_mfma_f32_16x16x32_bf16 v[26:29], v[184:187], v[216:219], v[26:29]
	v_mfma_f32_16x16x32_bf16 v[18:21], v[192:195], v[216:219], v[18:21]
	v_mfma_f32_16x16x32_bf16 v[10:13], v[184:187], v[224:227], v[10:13]
	v_mfma_f32_16x16x32_bf16 v[2:5], v[192:195], v[224:227], v[2:5]
	v_mfma_f32_16x16x32_bf16 v[58:61], v[188:191], v[204:207], v[58:61]
	v_mfma_f32_16x16x32_bf16 v[50:53], v[196:199], v[204:207], v[50:53]
	v_mfma_f32_16x16x32_bf16 v[42:45], v[188:191], v[212:215], v[42:45]
	v_mfma_f32_16x16x32_bf16 v[34:37], v[196:199], v[212:215], v[34:37]
	v_mfma_f32_16x16x32_bf16 v[26:29], v[188:191], v[220:223], v[26:29]
	v_mfma_f32_16x16x32_bf16 v[18:21], v[196:199], v[220:223], v[18:21]
	v_mfma_f32_16x16x32_bf16 v[10:13], v[188:191], v[228:231], v[10:13]
	v_mfma_f32_16x16x32_bf16 v[2:5], v[196:199], v[228:231], v[2:5]
	s_barrier
	s_setprio 0
	s_add_i32 s38, s38, 2
	s_add_u32 s36, s36, 0x100
	s_addc_u32 s37, s37, 0
	s_cmp_gt_u32 s38, 13
	s_mov_b64 s[12:13], s[14:15]
.LBB0_1050:
	s_add_u32 s14, s12, 0x100
	s_addc_u32 s15, s13, 0
	s_add_i32 s39, 0, 0x10000
	s_cmp_eq_u32 s38, 12
	s_cselect_b32 s19, s1, s15
	s_cselect_b32 s18, s0, s14
	v_add_u32_e32 v144, s39, v139
	s_cselect_b32 s17, s11, s37
	s_cselect_b32 s16, s10, s36
	s_add_i32 s40, 0, 0x14000
	ds_read_b128 v[164:167], v144
	ds_read_b128 v[168:171], v144 offset:1024
	ds_read_b128 v[172:175], v144 offset:2048
	ds_read_b128 v[176:179], v144 offset:3072
	v_add_u32_e32 v144, s40, v139
	s_add_i32 m0, s23, 0xc000
	v_lshl_add_u64 v[160:161], s[12:13], 0, v[156:157]
	global_load_lds_dwordx4 v[160:161], off
	s_add_i32 m0, s23, 0xe000
	v_lshl_add_u64 v[160:161], s[12:13], 0, v[158:159]
	global_load_lds_dwordx4 v[160:161], off
	ds_read_b128 v[184:187], v144
	ds_read_b128 v[188:191], v144 offset:1024
	ds_read_b128 v[192:195], v144 offset:2048
	ds_read_b128 v[196:199], v144 offset:3072
	ds_read_b128 v[200:203], v163
	ds_read_b128 v[204:207], v163 offset:1024
	ds_read_b128 v[208:211], v163 offset:2048
	ds_read_b128 v[212:215], v163 offset:3072
	ds_read_b128 v[216:219], v163 offset:4096
	ds_read_b128 v[220:223], v163 offset:5120
	ds_read_b128 v[224:227], v163 offset:6144
	ds_read_b128 v[228:231], v163 offset:7168
	s_setprio 1
	s_waitcnt vmcnt(8) lgkmcnt(0)
	s_barrier
; #define PG8_STAGE(bufoff, gbase, voff) do { _Pragma("unroll") for (int _i = 0; _i < 2; ++_i) \
;         __builtin_amdgcn_global_load_lds((const unsigned*)((const char*)(gbase) + (voff)[_i]), (LAS unsigned*)(lds + (bufoff) + ldsw + _i * 8192), 16, 0, 0); } while (0)
; #define PG8_LDA(dst, b, h) do { _Pragma("unroll") for (int m = 0; m < 4; ++m) _Pragma("unroll") for (int k = 0; k < 2; ++k) dst[m][k] = *(const LAS bf16x8*)(lds + PG8_SA(b, h) + aoff + m * 2048 + k * 1024); } while (0)
; #define PG8_LDB(dst, b, h) do { _Pragma("unroll") for (int n = 0; n < 2; ++n) _Pragma("unroll") for (int k = 0; k < 2; ++k) dst[n][k] = *(const LAS bf16x8*)(lds + PG8_SB(b, h) + boff + n * 2048 + k * 1024); } while (0)
; #define PG8_MMA(ai, bj, At, Bt) do { __builtin_amdgcn_s_setprio(1); _Pragma("unroll") for (int m = 0; m < 4; ++m) _Pragma("unroll") for (int n = 0; n < 2; ++n) _Pragma("unroll") for (int k = 0; k < 2; ++k) \
;         acc[ai][bj][m][n] = __builtin_amdgcn_mfma_f32_16x16x32_bf16(Bt[n][k], At[m][k], acc[ai][bj][m][n], 0, 0, 0); __builtin_amdgcn_s_setprio(0); } while (0)
; #define PG8_WAIT_V(n) asm volatile("s_waitcnt vmcnt(" #n ")" ::: "memory")
; #define PG8_WAIT_L(n) asm volatile("s_waitcnt lgkmcnt(" #n ")" ::: "memory")
; #define PG8_BAR __builtin_amdgcn_s_barrier()
; #define PG8_SCHED __builtin_amdgcn_sched_barrier(0)
; template <class Epi, bool ALIGN_EPI = PG8_ALIGN, bool SP2 = PG8_SP2>
; __device__ __forceinline__ void gemm_phase(LAS uchar* lds, const Gemm g, const StaticOrder& S, const Epi& E) {
;     ...
;             PG8_LDB(B0, 0, 0); PG8_LDB(B1, 0, 1); PG8_SCHED; PG8_LDA(At, 0, 0); PG8_STAGE(PG8_SA(1, 1), a1 + hstepA, voffA);
;             PG8_WAIT_V(8); PG8_WAIT_L(0); PG8_BAR; PG8_MMA(0, 0, At, B0); PG8_MMA(0, 1, At, B1); PG8_BAR; PG8_SCHED;
;             PG8_LDA(At, 0, 1); PG8_STAGE(PG8_SB(0, 0), b2, voffB); PG8_STAGE(PG8_SB(0, 1), b2 + hstepB, voffB); PG8_STAGE(PG8_SA(0, 0), a2, voffA);
;             PG8_WAIT_V(8); PG8_WAIT_L(0); PG8_BAR; PG8_MMA(1, 0, At, B0); PG8_MMA(1, 1, At, B1); PG8_BAR; PG8_SCHED;
	v_mfma_f32_16x16x32_bf16 v[126:129], v[164:167], v[200:203], v[126:129]
	v_mfma_f32_16x16x32_bf16 v[118:121], v[172:175], v[200:203], v[118:121]
	v_mfma_f32_16x16x32_bf16 v[110:113], v[164:167], v[208:211], v[110:113]
	v_mfma_f32_16x16x32_bf16 v[102:105], v[172:175], v[208:211], v[102:105]
	v_mfma_f32_16x16x32_bf16 v[94:97], v[164:167], v[216:219], v[94:97]
	v_mfma_f32_16x16x32_bf16 v[86:89], v[172:175], v[216:219], v[86:89]
	v_mfma_f32_16x16x32_bf16 v[78:81], v[164:167], v[224:227], v[78:81]
	v_mfma_f32_16x16x32_bf16 v[70:73], v[172:175], v[224:227], v[70:73]
	v_mfma_f32_16x16x32_bf16 v[126:129], v[168:171], v[204:207], v[126:129]
	v_mfma_f32_16x16x32_bf16 v[118:121], v[176:179], v[204:207], v[118:121]
	v_mfma_f32_16x16x32_bf16 v[110:113], v[168:171], v[212:215], v[110:113]
	v_mfma_f32_16x16x32_bf16 v[102:105], v[176:179], v[212:215], v[102:105]
	v_mfma_f32_16x16x32_bf16 v[94:97], v[168:171], v[220:223], v[94:97]
	v_mfma_f32_16x16x32_bf16 v[86:89], v[176:179], v[220:223], v[86:89]
	v_mfma_f32_16x16x32_bf16 v[78:81], v[168:171], v[228:231], v[78:81]
	v_mfma_f32_16x16x32_bf16 v[70:73], v[176:179], v[228:231], v[70:73]
	v_mfma_f32_16x16x32_bf16 v[122:125], v[184:187], v[200:203], v[122:125]
	v_mfma_f32_16x16x32_bf16 v[114:117], v[192:195], v[200:203], v[114:117]
	v_mfma_f32_16x16x32_bf16 v[106:109], v[184:187], v[208:211], v[106:109]
	v_mfma_f32_16x16x32_bf16 v[98:101], v[192:195], v[208:211], v[98:101]
	v_mfma_f32_16x16x32_bf16 v[90:93], v[184:187], v[216:219], v[90:93]
	v_mfma_f32_16x16x32_bf16 v[82:85], v[192:195], v[216:219], v[82:85]
	v_mfma_f32_16x16x32_bf16 v[74:77], v[184:187], v[224:227], v[74:77]
	v_mfma_f32_16x16x32_bf16 v[66:69], v[192:195], v[224:227], v[66:69]
	v_mfma_f32_16x16x32_bf16 v[122:125], v[188:191], v[204:207], v[122:125]
	v_mfma_f32_16x16x32_bf16 v[114:117], v[196:199], v[204:207], v[114:117]
	v_mfma_f32_16x16x32_bf16 v[106:109], v[188:191], v[212:215], v[106:109]
	v_mfma_f32_16x16x32_bf16 v[98:101], v[196:199], v[212:215], v[98:101]
	v_mfma_f32_16x16x32_bf16 v[90:93], v[188:191], v[220:223], v[90:93]
	v_mfma_f32_16x16x32_bf16 v[82:85], v[196:199], v[220:223], v[82:85]
	v_mfma_f32_16x16x32_bf16 v[74:77], v[188:191], v[228:231], v[74:77]
	v_mfma_f32_16x16x32_bf16 v[66:69], v[196:199], v[228:231], v[66:69]
	s_barrier
	s_setprio 0
	s_add_i32 s12, s39, s21
	s_mov_b32 m0, s12
	v_lshl_add_u64 v[160:161], s[16:17], 0, v[134:135]
	global_load_lds_dwordx4 v[160:161], off
	s_add_i32 m0, s12, 0x2000
	s_add_u32 s12, s16, 0x44000
	v_lshl_add_u64 v[180:181], s[16:17], 0, v[130:131]
	s_addc_u32 s13, s17, 0
	s_add_i32 s39, s40, s21
	global_load_lds_dwordx4 v[180:181], off
	s_mov_b32 m0, s39
	v_lshl_add_u64 v[232:233], s[12:13], 0, v[134:135]
	global_load_lds_dwordx4 v[232:233], off
	s_add_i32 m0, s39, 0x2000
	v_lshl_add_u64 v[232:233], s[12:13], 0, v[130:131]
	global_load_lds_dwordx4 v[232:233], off
	s_mov_b32 m0, s23
	v_lshl_add_u64 v[232:233], s[18:19], 0, v[154:155]
	global_load_lds_dwordx4 v[232:233], off
	s_mov_b32 m0, s24
	v_lshl_add_u64 v[234:235], s[18:19], 0, v[132:133]
	global_load_lds_dwordx4 v[234:235], off
	ds_read_b128 v[200:203], v163 offset:16384
	ds_read_b128 v[204:207], v163 offset:17408
	ds_read_b128 v[208:211], v163 offset:18432
	ds_read_b128 v[212:215], v163 offset:19456
	ds_read_b128 v[216:219], v163 offset:20480
	ds_read_b128 v[220:223], v163 offset:21504
	ds_read_b128 v[224:227], v163 offset:22528
	ds_read_b128 v[228:231], v163 offset:23552
	s_setprio 1
	s_waitcnt vmcnt(8) lgkmcnt(0)
	s_barrier
	v_mfma_f32_16x16x32_bf16 v[62:65], v[164:167], v[200:203], v[62:65]
	v_mfma_f32_16x16x32_bf16 v[54:57], v[172:175], v[200:203], v[54:57]
	v_mfma_f32_16x16x32_bf16 v[46:49], v[164:167], v[208:211], v[46:49]
	v_mfma_f32_16x16x32_bf16 v[38:41], v[172:175], v[208:211], v[38:41]
	v_mfma_f32_16x16x32_bf16 v[30:33], v[164:167], v[216:219], v[30:33]
	v_mfma_f32_16x16x32_bf16 v[22:25], v[172:175], v[216:219], v[22:25]
	v_mfma_f32_16x16x32_bf16 v[14:17], v[164:167], v[224:227], v[14:17]
	v_mfma_f32_16x16x32_bf16 v[6:9], v[172:175], v[224:227], v[6:9]
	v_mfma_f32_16x16x32_bf16 v[62:65], v[168:171], v[204:207], v[62:65]
	v_mfma_f32_16x16x32_bf16 v[54:57], v[176:179], v[204:207], v[54:57]
	v_mfma_f32_16x16x32_bf16 v[46:49], v[168:171], v[212:215], v[46:49]
	v_mfma_f32_16x16x32_bf16 v[38:41], v[176:179], v[212:215], v[38:41]
	v_mfma_f32_16x16x32_bf16 v[30:33], v[168:171], v[220:223], v[30:33]
	v_mfma_f32_16x16x32_bf16 v[22:25], v[176:179], v[220:223], v[22:25]
	v_mfma_f32_16x16x32_bf16 v[14:17], v[168:171], v[228:231], v[14:17]
	v_mfma_f32_16x16x32_bf16 v[6:9], v[176:179], v[228:231], v[6:9]
	v_mfma_f32_16x16x32_bf16 v[58:61], v[184:187], v[200:203], v[58:61]
	v_mfma_f32_16x16x32_bf16 v[50:53], v[192:195], v[200:203], v[50:53]
	v_mfma_f32_16x16x32_bf16 v[42:45], v[184:187], v[208:211], v[42:45]
	v_mfma_f32_16x16x32_bf16 v[34:37], v[192:195], v[208:211], v[34:37]
	v_mfma_f32_16x16x32_bf16 v[26:29], v[184:187], v[216:219], v[26:29]
	v_mfma_f32_16x16x32_bf16 v[18:21], v[192:195], v[216:219], v[18:21]
	v_mfma_f32_16x16x32_bf16 v[10:13], v[184:187], v[224:227], v[10:13]
	v_mfma_f32_16x16x32_bf16 v[2:5], v[192:195], v[224:227], v[2:5]
	v_mfma_f32_16x16x32_bf16 v[58:61], v[188:191], v[204:207], v[58:61]
	v_mfma_f32_16x16x32_bf16 v[50:53], v[196:199], v[204:207], v[50:53]
	v_mfma_f32_16x16x32_bf16 v[42:45], v[188:191], v[212:215], v[42:45]
	v_mfma_f32_16x16x32_bf16 v[34:37], v[196:199], v[212:215], v[34:37]
	v_mfma_f32_16x16x32_bf16 v[26:29], v[188:191], v[220:223], v[26:29]
	v_mfma_f32_16x16x32_bf16 v[18:21], v[196:199], v[220:223], v[18:21]
	v_mfma_f32_16x16x32_bf16 v[10:13], v[188:191], v[228:231], v[10:13]
	v_mfma_f32_16x16x32_bf16 v[2:5], v[196:199], v[228:231], v[2:5]
	s_barrier
; #define PG8_STAGE(bufoff, gbase, voff) do { _Pragma("unroll") for (int _i = 0; _i < 2; ++_i) \
;         __builtin_amdgcn_global_load_lds((const unsigned*)((const char*)(gbase) + (voff)[_i]), (LAS unsigned*)(lds + (bufoff) + ldsw + _i * 8192), 16, 0, 0); } while (0)
; #define PG8_LDA(dst, b, h) do { _Pragma("unroll") for (int m = 0; m < 4; ++m) _Pragma("unroll") for (int k = 0; k < 2; ++k) dst[m][k] = *(const LAS bf16x8*)(lds + PG8_SA(b, h) + aoff + m * 2048 + k * 1024); } while (0)
; #define PG8_LDB(dst, b, h) do { _Pragma("unroll") for (int n = 0; n < 2; ++n) _Pragma("unroll") for (int k = 0; k < 2; ++k) dst[n][k] = *(const LAS bf16x8*)(lds + PG8_SB(b, h) + boff + n * 2048 + k * 1024); } while (0)
; #define PG8_MMA(ai, bj, At, Bt) do { __builtin_amdgcn_s_setprio(1); _Pragma("unroll") for (int m = 0; m < 4; ++m) _Pragma("unroll") for (int n = 0; n < 2; ++n) _Pragma("unroll") for (int k = 0; k < 2; ++k) \
;         acc[ai][bj][m][n] = __builtin_amdgcn_mfma_f32_16x16x32_bf16(Bt[n][k], At[m][k], acc[ai][bj][m][n], 0, 0, 0); __builtin_amdgcn_s_setprio(0); } while (0)
; #define PG8_WAIT_V(n) asm volatile("s_waitcnt vmcnt(" #n ")" ::: "memory")
; #define PG8_WAIT_L(n) asm volatile("s_waitcnt lgkmcnt(" #n ")" ::: "memory")
; #define PG8_BAR __builtin_amdgcn_s_barrier()
; #define PG8_SCHED __builtin_amdgcn_sched_barrier(0)
; template <class Epi, bool ALIGN_EPI = PG8_ALIGN, bool SP2 = PG8_SP2>
; __device__ __forceinline__ void gemm_phase(LAS uchar* lds, const Gemm g, const StaticOrder& S, const Epi& E) {
;     ...
;             PG8_LDB(B0, 1, 0); PG8_LDB(B1, 1, 1); PG8_SCHED; PG8_LDA(At, 1, 0); PG8_STAGE(PG8_SA(0, 1), a2 + hstepA, voffA);
;             PG8_WAIT_V(8); PG8_WAIT_L(0); PG8_BAR; PG8_MMA(0, 0, At, B0); PG8_MMA(0, 1, At, B1); PG8_BAR; PG8_SCHED;
	s_setprio 0
	s_add_i32 s39, 0, 0x18000
	v_add_u32_e32 v144, s39, v139
	s_add_i32 s40, 0, 0x1c000
	ds_read_b128 v[164:167], v144
	ds_read_b128 v[168:171], v144 offset:1024
	ds_read_b128 v[172:175], v144 offset:2048
	ds_read_b128 v[176:179], v144 offset:3072
	v_add_u32_e32 v144, s40, v139
	s_add_u32 s12, s18, 0x44000
	s_addc_u32 s13, s19, 0
	s_mov_b32 m0, s25
	v_lshl_add_u64 v[236:237], s[12:13], 0, v[154:155]
	global_load_lds_dwordx4 v[236:237], off
	s_mov_b32 m0, s26
	v_lshl_add_u64 v[236:237], s[12:13], 0, v[132:133]
	global_load_lds_dwordx4 v[236:237], off
	ds_read_b128 v[184:187], v144
	ds_read_b128 v[188:191], v144 offset:1024
	ds_read_b128 v[192:195], v144 offset:2048
	ds_read_b128 v[196:199], v144 offset:3072
	ds_read_b128 v[200:203], v163 offset:32768
	ds_read_b128 v[204:207], v163 offset:33792
	ds_read_b128 v[208:211], v163 offset:34816
	ds_read_b128 v[212:215], v163 offset:35840
	ds_read_b128 v[216:219], v163 offset:36864
	ds_read_b128 v[220:223], v163 offset:37888
	ds_read_b128 v[224:227], v163 offset:38912
	ds_read_b128 v[228:231], v163 offset:39936
	s_setprio 1
	s_waitcnt vmcnt(8) lgkmcnt(0)
	s_barrier
	v_mfma_f32_16x16x32_bf16 v[126:129], v[164:167], v[200:203], v[126:129]
	v_mfma_f32_16x16x32_bf16 v[118:121], v[172:175], v[200:203], v[118:121]
	v_mfma_f32_16x16x32_bf16 v[110:113], v[164:167], v[208:211], v[110:113]
	v_mfma_f32_16x16x32_bf16 v[102:105], v[172:175], v[208:211], v[102:105]
	v_mfma_f32_16x16x32_bf16 v[94:97], v[164:167], v[216:219], v[94:97]
	v_mfma_f32_16x16x32_bf16 v[86:89], v[172:175], v[216:219], v[86:89]
	v_mfma_f32_16x16x32_bf16 v[78:81], v[164:167], v[224:227], v[78:81]
	v_mfma_f32_16x16x32_bf16 v[70:73], v[172:175], v[224:227], v[70:73]
	v_mfma_f32_16x16x32_bf16 v[126:129], v[168:171], v[204:207], v[126:129]
	v_mfma_f32_16x16x32_bf16 v[118:121], v[176:179], v[204:207], v[118:121]
	v_mfma_f32_16x16x32_bf16 v[110:113], v[168:171], v[212:215], v[110:113]
	v_mfma_f32_16x16x32_bf16 v[102:105], v[176:179], v[212:215], v[102:105]
	v_mfma_f32_16x16x32_bf16 v[94:97], v[168:171], v[220:223], v[94:97]
	v_mfma_f32_16x16x32_bf16 v[86:89], v[176:179], v[220:223], v[86:89]
	v_mfma_f32_16x16x32_bf16 v[78:81], v[168:171], v[228:231], v[78:81]
	v_mfma_f32_16x16x32_bf16 v[70:73], v[176:179], v[228:231], v[70:73]
	v_mfma_f32_16x16x32_bf16 v[122:125], v[184:187], v[200:203], v[122:125]
	v_mfma_f32_16x16x32_bf16 v[114:117], v[192:195], v[200:203], v[114:117]
	v_mfma_f32_16x16x32_bf16 v[106:109], v[184:187], v[208:211], v[106:109]
	v_mfma_f32_16x16x32_bf16 v[98:101], v[192:195], v[208:211], v[98:101]
	v_mfma_f32_16x16x32_bf16 v[90:93], v[184:187], v[216:219], v[90:93]
	v_mfma_f32_16x16x32_bf16 v[82:85], v[192:195], v[216:219], v[82:85]
	v_mfma_f32_16x16x32_bf16 v[74:77], v[184:187], v[224:227], v[74:77]
	v_mfma_f32_16x16x32_bf16 v[66:69], v[192:195], v[224:227], v[66:69]
	v_mfma_f32_16x16x32_bf16 v[122:125], v[188:191], v[204:207], v[122:125]
	v_mfma_f32_16x16x32_bf16 v[114:117], v[196:199], v[204:207], v[114:117]
	v_mfma_f32_16x16x32_bf16 v[106:109], v[188:191], v[212:215], v[106:109]
	v_mfma_f32_16x16x32_bf16 v[98:101], v[196:199], v[212:215], v[98:101]
	v_mfma_f32_16x16x32_bf16 v[90:93], v[188:191], v[220:223], v[90:93]
	v_mfma_f32_16x16x32_bf16 v[82:85], v[196:199], v[220:223], v[82:85]
	v_mfma_f32_16x16x32_bf16 v[74:77], v[188:191], v[228:231], v[74:77]
	v_mfma_f32_16x16x32_bf16 v[66:69], v[196:199], v[228:231], v[66:69]
	s_barrier
; #define PG8_STAGE(bufoff, gbase, voff) do { _Pragma("unroll") for (int _i = 0; _i < 2; ++_i) \
;         __builtin_amdgcn_global_load_lds((const unsigned*)((const char*)(gbase) + (voff)[_i]), (LAS unsigned*)(lds + (bufoff) + ldsw + _i * 8192), 16, 0, 0); } while (0)
; #define PG8_LDA(dst, b, h) do { _Pragma("unroll") for (int m = 0; m < 4; ++m) _Pragma("unroll") for (int k = 0; k < 2; ++k) dst[m][k] = *(const LAS bf16x8*)(lds + PG8_SA(b, h) + aoff + m * 2048 + k * 1024); } while (0)
; #define PG8_MMA(ai, bj, At, Bt) do { __builtin_amdgcn_s_setprio(1); _Pragma("unroll") for (int m = 0; m < 4; ++m) _Pragma("unroll") for (int n = 0; n < 2; ++n) _Pragma("unroll") for (int k = 0; k < 2; ++k) \
;         acc[ai][bj][m][n] = __builtin_amdgcn_mfma_f32_16x16x32_bf16(Bt[n][k], At[m][k], acc[ai][bj][m][n], 0, 0, 0); __builtin_amdgcn_s_setprio(0); } while (0)
; #define PG8_WAIT_V(n) asm volatile("s_waitcnt vmcnt(" #n ")" ::: "memory")
; #define PG8_WAIT_L(n) asm volatile("s_waitcnt lgkmcnt(" #n ")" ::: "memory")
; #define PG8_BAR __builtin_amdgcn_s_barrier()
; #define PG8_SCHED __builtin_amdgcn_sched_barrier(0)
; template <class Epi, bool ALIGN_EPI = PG8_ALIGN, bool SP2 = PG8_SP2>
; __device__ __forceinline__ void gemm_phase(LAS uchar* lds, const Gemm g, const StaticOrder& S, const Epi& E) {
;     ...
;             PG8_LDA(At, 1, 1); PG8_STAGE(PG8_SB(1, 0), b3, voffB); PG8_STAGE(PG8_SB(1, 1), b3 + hstepB, voffB); PG8_STAGE(PG8_SA(1, 0), a3, voffA);
;             PG8_WAIT_V(8); PG8_WAIT_L(0); PG8_BAR; PG8_MMA(1, 0, At, B0); PG8_MMA(1, 1, At, B1); PG8_BAR; PG8_SCHED;
;     ...
;         if constexpr (ALIGN_EPI) { if (wr == 0) PG8_BAR; }
	s_setprio 0
	s_add_i32 s12, s39, s21
	s_mov_b32 m0, s12
	v_lshl_add_u64 v[160:161], v[160:161], 0, s[84:85]
	global_load_lds_dwordx4 v[160:161], off
	s_add_i32 m0, s12, 0x2000
	s_add_u32 s12, s16, 0x44080
	v_lshl_add_u64 v[160:161], v[180:181], 0, s[84:85]
	s_addc_u32 s13, s17, 0
	s_add_i32 s16, s40, s21
	global_load_lds_dwordx4 v[160:161], off
	s_mov_b32 m0, s16
	v_lshl_add_u64 v[160:161], s[12:13], 0, v[134:135]
	global_load_lds_dwordx4 v[160:161], off
	s_add_i32 m0, s16, 0x2000
	v_lshl_add_u64 v[160:161], s[12:13], 0, v[130:131]
	global_load_lds_dwordx4 v[160:161], off
	s_mov_b32 m0, s27
	v_lshl_add_u64 v[160:161], v[232:233], 0, s[84:85]
	global_load_lds_dwordx4 v[160:161], off
	s_mov_b32 m0, s28
	v_lshl_add_u64 v[160:161], v[234:235], 0, s[84:85]
	global_load_lds_dwordx4 v[160:161], off
	ds_read_b128 v[200:203], v163 offset:49152
	ds_read_b128 v[204:207], v163 offset:50176
	ds_read_b128 v[208:211], v163 offset:51200
	ds_read_b128 v[212:215], v163 offset:52224
	ds_read_b128 v[216:219], v163 offset:53248
	ds_read_b128 v[220:223], v163 offset:54272
	ds_read_b128 v[224:227], v163 offset:55296
	ds_read_b128 v[228:231], v163 offset:56320
	s_setprio 1
	s_waitcnt vmcnt(8) lgkmcnt(0)
	s_barrier
	v_mfma_f32_16x16x32_bf16 v[62:65], v[164:167], v[200:203], v[62:65]
	v_mfma_f32_16x16x32_bf16 v[54:57], v[172:175], v[200:203], v[54:57]
	v_mfma_f32_16x16x32_bf16 v[46:49], v[164:167], v[208:211], v[46:49]
	v_mfma_f32_16x16x32_bf16 v[38:41], v[172:175], v[208:211], v[38:41]
	v_mfma_f32_16x16x32_bf16 v[30:33], v[164:167], v[216:219], v[30:33]
	v_mfma_f32_16x16x32_bf16 v[22:25], v[172:175], v[216:219], v[22:25]
	v_mfma_f32_16x16x32_bf16 v[14:17], v[164:167], v[224:227], v[14:17]
	v_mfma_f32_16x16x32_bf16 v[6:9], v[172:175], v[224:227], v[6:9]
	v_mfma_f32_16x16x32_bf16 v[62:65], v[168:171], v[204:207], v[62:65]
	v_mfma_f32_16x16x32_bf16 v[54:57], v[176:179], v[204:207], v[54:57]
	v_mfma_f32_16x16x32_bf16 v[46:49], v[168:171], v[212:215], v[46:49]
	v_mfma_f32_16x16x32_bf16 v[38:41], v[176:179], v[212:215], v[38:41]
	v_mfma_f32_16x16x32_bf16 v[30:33], v[168:171], v[220:223], v[30:33]
	v_mfma_f32_16x16x32_bf16 v[22:25], v[176:179], v[220:223], v[22:25]
	v_mfma_f32_16x16x32_bf16 v[14:17], v[168:171], v[228:231], v[14:17]
	v_mfma_f32_16x16x32_bf16 v[6:9], v[176:179], v[228:231], v[6:9]
	v_mfma_f32_16x16x32_bf16 v[58:61], v[184:187], v[200:203], v[58:61]
	v_mfma_f32_16x16x32_bf16 v[50:53], v[192:195], v[200:203], v[50:53]
	v_mfma_f32_16x16x32_bf16 v[42:45], v[184:187], v[208:211], v[42:45]
	v_mfma_f32_16x16x32_bf16 v[34:37], v[192:195], v[208:211], v[34:37]
	v_mfma_f32_16x16x32_bf16 v[26:29], v[184:187], v[216:219], v[26:29]
	v_mfma_f32_16x16x32_bf16 v[18:21], v[192:195], v[216:219], v[18:21]
	v_mfma_f32_16x16x32_bf16 v[10:13], v[184:187], v[224:227], v[10:13]
	v_mfma_f32_16x16x32_bf16 v[2:5], v[192:195], v[224:227], v[2:5]
	v_mfma_f32_16x16x32_bf16 v[58:61], v[188:191], v[204:207], v[58:61]
	v_mfma_f32_16x16x32_bf16 v[50:53], v[196:199], v[204:207], v[50:53]
	v_mfma_f32_16x16x32_bf16 v[42:45], v[188:191], v[212:215], v[42:45]
	v_mfma_f32_16x16x32_bf16 v[34:37], v[196:199], v[212:215], v[34:37]
	v_mfma_f32_16x16x32_bf16 v[26:29], v[188:191], v[220:223], v[26:29]
	v_mfma_f32_16x16x32_bf16 v[18:21], v[196:199], v[220:223], v[18:21]
	v_mfma_f32_16x16x32_bf16 v[10:13], v[188:191], v[228:231], v[10:13]
	v_mfma_f32_16x16x32_bf16 v[2:5], v[196:199], v[228:231], v[2:5]
	s_barrier
	s_setprio 0
	s_add_i32 s38, s38, 2
	s_add_u32 s36, s36, 0x100
	s_addc_u32 s37, s37, 0
	s_cmp_gt_u32 s38, 13
	s_mov_b64 s[12:13], s[14:15]
	s_cbranch_scc0 .LBB0_1050
	s_and_b64 vcc, exec, s[8:9]
	s_cbranch_vccz .LBB0_1053
	s_barrier

; #define LAS __attribute__((address_space(3)))
; #define PG8_STAGE(bufoff, gbase, voff) do { _Pragma("unroll") for (int _i = 0; _i < 2; ++_i) \
;         __builtin_amdgcn_global_load_lds((const unsigned*)((const char*)(gbase) + (voff)[_i]), (LAS unsigned*)(lds + (bufoff) + ldsw + _i * 8192), 16, 0, 0); } while (0)
; #define PG8_WAIT_V(n) asm volatile("s_waitcnt vmcnt(" #n ")" ::: "memory")
; template <class Epi, bool ALIGN_EPI = PG8_ALIGN, bool SP2 = PG8_SP2>
; __device__ __forceinline__ void gemm_phase(LAS uchar* lds, const Gemm g, const StaticOrder& S, const Epi& E) {
;     ...
;         const bool has_next = S.next(ui + 1, nxt);
;         const char* nA = has_next ? (const char*)g.A + (size_t)nxt.pm * tstepA : cA; const char* nB = has_next ? (const char*)g.Bt + (size_t)nxt.pn * tstepB : cB;
;         const int tblk = Epi::GROUPS ? 4 : nt;
; #pragma unroll 1
;         for (int tb = 0; tb < nt; tb += tblk) {
;         if constexpr (Epi::GROUPS) { if (tb > 0) {
;             const LAS float* rt = (const LAS float*)(lds + LDS_RT) + ((ui & 1) * 256 + wr * 64 + fr) * 8 + ((tb >> 2) - 1);
; #pragma unroll
;             for (int a = 0; a < 2; ++a)
; #pragma unroll
;                 for (int m = 0; m < 4; ++m) { const float f = rt[(a * 128 + m * 16) * 8];
; #pragma unroll
;                     for (int b = 0; b < 2; ++b)
; #pragma unroll
;                         for (int n = 0; n < 2; ++n) acc[a][b][m][n] *= f; } } }
; #pragma unroll 1
;         for (int t = tb; t < tb + tblk; t += 2) {
;             const bool last = (t == nt - 2);
;             const char* a1 = cA + (size_t)(t + 1) * kstep;
;             const char* a2 = last ? nA : cA + (size_t)(t + 2) * kstep; const char* b2 = last ? nB : cB + (size_t)(t + 2) * kstep;
;             const char* a3 = a2 + kstep; const char* b3 = b2 + kstep;
;             if constexpr (SP2) {
;             PG8_LDB(B0, 0, 0); PG8_LDB(B1, 0, 1); PG8_SCHED; PG8_LDA(At, 0, 0); PG8_STAGE(PG8_SA(1, 1), a1 + hstepA, voffA);
;             PG8_WAIT_V(8); PG8_WAIT_L(0); PG8_BAR; PG8_MMA(0, 0, At, B0); PG8_MMA(0, 1, At, B1); PG8_BAR; PG8_SCHED;
;             PG8_LDA(At, 0, 1); PG8_STAGE(PG8_SB(0, 0), b2, voffB); PG8_STAGE(PG8_SB(0, 1), b2 + hstepB, voffB); PG8_STAGE(PG8_SA(0, 0), a2, voffA);
;             PG8_WAIT_V(8); PG8_WAIT_L(0); PG8_BAR; PG8_MMA(1, 0, At, B0); PG8_MMA(1, 1, At, B1); PG8_BAR; PG8_SCHED;
.LBB0_1142:
	s_add_u32 s38, s16, 0x100
	s_addc_u32 s39, s17, 0
	s_mov_b32 s40, -2
	s_add_u32 s16, s14, 0x100
	s_addc_u32 s17, s15, 0
	s_add_i32 s41, 0, 0x10000
	s_cmp_eq_u32 s40, 40
	s_cselect_b32 s21, s5, s17
	s_cselect_b32 s20, s4, s16
	v_add_u32_e32 v144, s41, v139
	s_cselect_b32 s19, s13, s39
	s_cselect_b32 s18, s12, s38
	s_add_i32 s42, 0, 0x14000
	ds_read_b128 v[160:163], v144
	ds_read_b128 v[166:169], v144 offset:1024
	ds_read_b128 v[170:173], v144 offset:2048
	ds_read_b128 v[174:177], v144 offset:3072
	v_add_u32_e32 v144, s42, v139
	s_add_i32 m0, s25, 0xc000
	v_lshl_add_u64 v[228:229], s[14:15], 0, v[156:157]
	global_load_lds_dwordx4 v[228:229], off
	s_add_i32 m0, s25, 0xe000
	v_lshl_add_u64 v[228:229], s[14:15], 0, v[158:159]
	global_load_lds_dwordx4 v[228:229], off
	ds_read_b128 v[178:181], v144
	ds_read_b128 v[184:187], v144 offset:1024
	ds_read_b128 v[188:191], v144 offset:2048
	ds_read_b128 v[192:195], v144 offset:3072
	ds_read_b128 v[196:199], v165
	ds_read_b128 v[200:203], v165 offset:1024
	ds_read_b128 v[204:207], v165 offset:2048
	ds_read_b128 v[208:211], v165 offset:3072
	ds_read_b128 v[212:215], v165 offset:4096
	ds_read_b128 v[216:219], v165 offset:5120
	ds_read_b128 v[220:223], v165 offset:6144
	ds_read_b128 v[224:227], v165 offset:7168
	s_setprio 1
	s_waitcnt vmcnt(8) lgkmcnt(0)
	s_barrier
	v_mfma_f32_16x16x32_bf16 v[126:129], v[160:163], v[196:199], 0
	v_mfma_f32_16x16x32_bf16 v[122:125], v[170:173], v[196:199], 0
	v_mfma_f32_16x16x32_bf16 v[118:121], v[160:163], v[204:207], 0
	v_mfma_f32_16x16x32_bf16 v[110:113], v[170:173], v[204:207], 0
	v_mfma_f32_16x16x32_bf16 v[102:105], v[160:163], v[212:215], 0
	v_mfma_f32_16x16x32_bf16 v[94:97], v[170:173], v[212:215], 0
	v_mfma_f32_16x16x32_bf16 v[86:89], v[160:163], v[220:223], 0
	v_mfma_f32_16x16x32_bf16 v[78:81], v[170:173], v[220:223], 0
	v_mfma_f32_16x16x32_bf16 v[126:129], v[166:169], v[200:203], v[126:129]
	v_mfma_f32_16x16x32_bf16 v[122:125], v[174:177], v[200:203], v[122:125]
	v_mfma_f32_16x16x32_bf16 v[118:121], v[166:169], v[208:211], v[118:121]
	v_mfma_f32_16x16x32_bf16 v[110:113], v[174:177], v[208:211], v[110:113]
	v_mfma_f32_16x16x32_bf16 v[102:105], v[166:169], v[216:219], v[102:105]
	v_mfma_f32_16x16x32_bf16 v[94:97], v[174:177], v[216:219], v[94:97]
	v_mfma_f32_16x16x32_bf16 v[86:89], v[166:169], v[224:227], v[86:89]
	v_mfma_f32_16x16x32_bf16 v[78:81], v[174:177], v[224:227], v[78:81]
	v_mfma_f32_16x16x32_bf16 v[114:117], v[178:181], v[196:199], 0
	v_mfma_f32_16x16x32_bf16 v[106:109], v[188:191], v[196:199], 0
	v_mfma_f32_16x16x32_bf16 v[98:101], v[178:181], v[204:207], 0
	v_mfma_f32_16x16x32_bf16 v[90:93], v[188:191], v[204:207], 0
	v_mfma_f32_16x16x32_bf16 v[82:85], v[178:181], v[212:215], 0
	v_mfma_f32_16x16x32_bf16 v[74:77], v[188:191], v[212:215], 0
	v_mfma_f32_16x16x32_bf16 v[70:73], v[178:181], v[220:223], 0
	v_mfma_f32_16x16x32_bf16 v[66:69], v[188:191], v[220:223], 0
	v_mfma_f32_16x16x32_bf16 v[114:117], v[184:187], v[200:203], v[114:117]
	v_mfma_f32_16x16x32_bf16 v[106:109], v[192:195], v[200:203], v[106:109]
	v_mfma_f32_16x16x32_bf16 v[98:101], v[184:187], v[208:211], v[98:101]
	v_mfma_f32_16x16x32_bf16 v[90:93], v[192:195], v[208:211], v[90:93]
	v_mfma_f32_16x16x32_bf16 v[82:85], v[184:187], v[216:219], v[82:85]
	v_mfma_f32_16x16x32_bf16 v[74:77], v[192:195], v[216:219], v[74:77]
	v_mfma_f32_16x16x32_bf16 v[70:73], v[184:187], v[224:227], v[70:73]
	v_mfma_f32_16x16x32_bf16 v[66:69], v[192:195], v[224:227], v[66:69]
	s_barrier
	s_setprio 0
	s_add_i32 s14, s41, s24
	s_mov_b32 m0, s14
	v_lshl_add_u64 v[228:229], s[18:19], 0, v[132:133]
	global_load_lds_dwordx4 v[228:229], off
	s_add_i32 m0, s14, 0x2000
	s_add_u32 s14, s18, 0xb0000
	v_lshl_add_u64 v[230:231], s[18:19], 0, v[154:155]
	s_addc_u32 s15, s19, 0
	s_add_i32 s41, s42, s24
	global_load_lds_dwordx4 v[230:231], off
	s_mov_b32 m0, s41
	v_lshl_add_u64 v[232:233], s[14:15], 0, v[132:133]
	global_load_lds_dwordx4 v[232:233], off
	s_add_i32 m0, s41, 0x2000
	v_lshl_add_u64 v[232:233], s[14:15], 0, v[154:155]
	global_load_lds_dwordx4 v[232:233], off
	s_mov_b32 m0, s25
	v_lshl_add_u64 v[232:233], s[20:21], 0, v[130:131]
	global_load_lds_dwordx4 v[232:233], off
	s_mov_b32 m0, s26
	v_lshl_add_u64 v[234:235], s[20:21], 0, v[134:135]
	global_load_lds_dwordx4 v[234:235], off
	ds_read_b128 v[196:199], v165 offset:16384
	ds_read_b128 v[200:203], v165 offset:17408
	ds_read_b128 v[204:207], v165 offset:18432
	ds_read_b128 v[208:211], v165 offset:19456
	ds_read_b128 v[212:215], v165 offset:20480
	ds_read_b128 v[216:219], v165 offset:21504
	ds_read_b128 v[220:223], v165 offset:22528
	ds_read_b128 v[224:227], v165 offset:23552
	s_setprio 1
	s_waitcnt vmcnt(8) lgkmcnt(0)
	s_barrier
; #define PG8_STAGE(bufoff, gbase, voff) do { _Pragma("unroll") for (int _i = 0; _i < 2; ++_i) \
;         __builtin_amdgcn_global_load_lds((const unsigned*)((const char*)(gbase) + (voff)[_i]), (LAS unsigned*)(lds + (bufoff) + ldsw + _i * 8192), 16, 0, 0); } while (0)
; #define PG8_LDA(dst, b, h) do { _Pragma("unroll") for (int m = 0; m < 4; ++m) _Pragma("unroll") for (int k = 0; k < 2; ++k) dst[m][k] = *(const LAS bf16x8*)(lds + PG8_SA(b, h) + aoff + m * 2048 + k * 1024); } while (0)
; #define PG8_LDB(dst, b, h) do { _Pragma("unroll") for (int n = 0; n < 2; ++n) _Pragma("unroll") for (int k = 0; k < 2; ++k) dst[n][k] = *(const LAS bf16x8*)(lds + PG8_SB(b, h) + boff + n * 2048 + k * 1024); } while (0)
; #define PG8_MMA(ai, bj, At, Bt) do { __builtin_amdgcn_s_setprio(1); _Pragma("unroll") for (int m = 0; m < 4; ++m) _Pragma("unroll") for (int n = 0; n < 2; ++n) _Pragma("unroll") for (int k = 0; k < 2; ++k) \
;         acc[ai][bj][m][n] = __builtin_amdgcn_mfma_f32_16x16x32_bf16(Bt[n][k], At[m][k], acc[ai][bj][m][n], 0, 0, 0); __builtin_amdgcn_s_setprio(0); } while (0)
; #define PG8_WAIT_V(n) asm volatile("s_waitcnt vmcnt(" #n ")" ::: "memory")
; #define PG8_WAIT_L(n) asm volatile("s_waitcnt lgkmcnt(" #n ")" ::: "memory")
; #define PG8_BAR __builtin_amdgcn_s_barrier()
; #define PG8_SCHED __builtin_amdgcn_sched_barrier(0)
; template <class Epi, bool ALIGN_EPI = PG8_ALIGN, bool SP2 = PG8_SP2>
; __device__ __forceinline__ void gemm_phase(LAS uchar* lds, const Gemm g, const StaticOrder& S, const Epi& E) {
;     ...
;             PG8_WAIT_V(8); PG8_WAIT_L(0); PG8_BAR; PG8_MMA(1, 0, At, B0); PG8_MMA(1, 1, At, B1); PG8_BAR; PG8_SCHED;
;             PG8_LDB(B0, 1, 0); PG8_LDB(B1, 1, 1); PG8_SCHED; PG8_LDA(At, 1, 0); PG8_STAGE(PG8_SA(0, 1), a2 + hstepA, voffA);
;             PG8_WAIT_V(8); PG8_WAIT_L(0); PG8_BAR; PG8_MMA(0, 0, At, B0); PG8_MMA(0, 1, At, B1); PG8_BAR; PG8_SCHED;
	v_mfma_f32_16x16x32_bf16 v[62:65], v[160:163], v[196:199], 0
	v_mfma_f32_16x16x32_bf16 v[58:61], v[170:173], v[196:199], 0
	v_mfma_f32_16x16x32_bf16 v[54:57], v[160:163], v[204:207], 0
	v_mfma_f32_16x16x32_bf16 v[46:49], v[170:173], v[204:207], 0
	v_mfma_f32_16x16x32_bf16 v[38:41], v[160:163], v[212:215], 0
	v_mfma_f32_16x16x32_bf16 v[30:33], v[170:173], v[212:215], 0
	v_mfma_f32_16x16x32_bf16 v[22:25], v[160:163], v[220:223], 0
	v_mfma_f32_16x16x32_bf16 v[14:17], v[170:173], v[220:223], 0
	v_mfma_f32_16x16x32_bf16 v[62:65], v[166:169], v[200:203], v[62:65]
	v_mfma_f32_16x16x32_bf16 v[58:61], v[174:177], v[200:203], v[58:61]
	v_mfma_f32_16x16x32_bf16 v[54:57], v[166:169], v[208:211], v[54:57]
	v_mfma_f32_16x16x32_bf16 v[46:49], v[174:177], v[208:211], v[46:49]
	v_mfma_f32_16x16x32_bf16 v[38:41], v[166:169], v[216:219], v[38:41]
	v_mfma_f32_16x16x32_bf16 v[30:33], v[174:177], v[216:219], v[30:33]
	v_mfma_f32_16x16x32_bf16 v[22:25], v[166:169], v[224:227], v[22:25]
	v_mfma_f32_16x16x32_bf16 v[14:17], v[174:177], v[224:227], v[14:17]
	v_mfma_f32_16x16x32_bf16 v[50:53], v[178:181], v[196:199], 0
	v_mfma_f32_16x16x32_bf16 v[42:45], v[188:191], v[196:199], 0
	v_mfma_f32_16x16x32_bf16 v[34:37], v[178:181], v[204:207], 0
	v_mfma_f32_16x16x32_bf16 v[26:29], v[188:191], v[204:207], 0
	v_mfma_f32_16x16x32_bf16 v[18:21], v[178:181], v[212:215], 0
	v_mfma_f32_16x16x32_bf16 v[10:13], v[188:191], v[212:215], 0
	v_mfma_f32_16x16x32_bf16 v[6:9], v[178:181], v[220:223], 0
	v_mfma_f32_16x16x32_bf16 v[2:5], v[188:191], v[220:223], 0
	v_mfma_f32_16x16x32_bf16 v[50:53], v[184:187], v[200:203], v[50:53]
	v_mfma_f32_16x16x32_bf16 v[42:45], v[192:195], v[200:203], v[42:45]
	v_mfma_f32_16x16x32_bf16 v[34:37], v[184:187], v[208:211], v[34:37]
	v_mfma_f32_16x16x32_bf16 v[26:29], v[192:195], v[208:211], v[26:29]
	v_mfma_f32_16x16x32_bf16 v[18:21], v[184:187], v[216:219], v[18:21]
	v_mfma_f32_16x16x32_bf16 v[10:13], v[192:195], v[216:219], v[10:13]
	v_mfma_f32_16x16x32_bf16 v[6:9], v[184:187], v[224:227], v[6:9]
	v_mfma_f32_16x16x32_bf16 v[2:5], v[192:195], v[224:227], v[2:5]
	s_barrier
	s_setprio 0
	s_add_i32 s41, 0, 0x18000
	v_add_u32_e32 v144, s41, v139
	s_add_i32 s42, 0, 0x1c000
	ds_read_b128 v[160:163], v144
	ds_read_b128 v[166:169], v144 offset:1024
	ds_read_b128 v[170:173], v144 offset:2048
	ds_read_b128 v[174:177], v144 offset:3072
	v_add_u32_e32 v144, s42, v139
	s_add_u32 s14, s20, 0xb0000
	s_addc_u32 s15, s21, 0
	s_mov_b32 m0, s27
	v_lshl_add_u64 v[236:237], s[14:15], 0, v[130:131]
	global_load_lds_dwordx4 v[236:237], off
	s_mov_b32 m0, s28
	v_lshl_add_u64 v[236:237], s[14:15], 0, v[134:135]
	global_load_lds_dwordx4 v[236:237], off
	ds_read_b128 v[178:181], v144
	ds_read_b128 v[184:187], v144 offset:1024
	ds_read_b128 v[188:191], v144 offset:2048
	ds_read_b128 v[192:195], v144 offset:3072
	ds_read_b128 v[196:199], v165 offset:32768
	ds_read_b128 v[200:203], v165 offset:33792
	ds_read_b128 v[204:207], v165 offset:34816
	ds_read_b128 v[208:211], v165 offset:35840
	ds_read_b128 v[212:215], v165 offset:36864
	ds_read_b128 v[216:219], v165 offset:37888
	ds_read_b128 v[220:223], v165 offset:38912
	ds_read_b128 v[224:227], v165 offset:39936
	s_setprio 1
	s_waitcnt vmcnt(8) lgkmcnt(0)
	s_barrier
	v_mfma_f32_16x16x32_bf16 v[126:129], v[160:163], v[196:199], v[126:129]
	v_mfma_f32_16x16x32_bf16 v[122:125], v[170:173], v[196:199], v[122:125]
	v_mfma_f32_16x16x32_bf16 v[118:121], v[160:163], v[204:207], v[118:121]
	v_mfma_f32_16x16x32_bf16 v[110:113], v[170:173], v[204:207], v[110:113]
	v_mfma_f32_16x16x32_bf16 v[102:105], v[160:163], v[212:215], v[102:105]
	v_mfma_f32_16x16x32_bf16 v[94:97], v[170:173], v[212:215], v[94:97]
	v_mfma_f32_16x16x32_bf16 v[86:89], v[160:163], v[220:223], v[86:89]
	v_mfma_f32_16x16x32_bf16 v[78:81], v[170:173], v[220:223], v[78:81]
	v_mfma_f32_16x16x32_bf16 v[126:129], v[166:169], v[200:203], v[126:129]
	v_mfma_f32_16x16x32_bf16 v[122:125], v[174:177], v[200:203], v[122:125]
	v_mfma_f32_16x16x32_bf16 v[118:121], v[166:169], v[208:211], v[118:121]
	v_mfma_f32_16x16x32_bf16 v[110:113], v[174:177], v[208:211], v[110:113]
	v_mfma_f32_16x16x32_bf16 v[102:105], v[166:169], v[216:219], v[102:105]
	v_mfma_f32_16x16x32_bf16 v[94:97], v[174:177], v[216:219], v[94:97]
	v_mfma_f32_16x16x32_bf16 v[86:89], v[166:169], v[224:227], v[86:89]
	v_mfma_f32_16x16x32_bf16 v[78:81], v[174:177], v[224:227], v[78:81]
	v_mfma_f32_16x16x32_bf16 v[114:117], v[178:181], v[196:199], v[114:117]
	v_mfma_f32_16x16x32_bf16 v[106:109], v[188:191], v[196:199], v[106:109]
	v_mfma_f32_16x16x32_bf16 v[98:101], v[178:181], v[204:207], v[98:101]
	v_mfma_f32_16x16x32_bf16 v[90:93], v[188:191], v[204:207], v[90:93]
	v_mfma_f32_16x16x32_bf16 v[82:85], v[178:181], v[212:215], v[82:85]
	v_mfma_f32_16x16x32_bf16 v[74:77], v[188:191], v[212:215], v[74:77]
	v_mfma_f32_16x16x32_bf16 v[70:73], v[178:181], v[220:223], v[70:73]
	v_mfma_f32_16x16x32_bf16 v[66:69], v[188:191], v[220:223], v[66:69]
	v_mfma_f32_16x16x32_bf16 v[114:117], v[184:187], v[200:203], v[114:117]
	v_mfma_f32_16x16x32_bf16 v[106:109], v[192:195], v[200:203], v[106:109]
	v_mfma_f32_16x16x32_bf16 v[98:101], v[184:187], v[208:211], v[98:101]
	v_mfma_f32_16x16x32_bf16 v[90:93], v[192:195], v[208:211], v[90:93]
	v_mfma_f32_16x16x32_bf16 v[82:85], v[184:187], v[216:219], v[82:85]
	v_mfma_f32_16x16x32_bf16 v[74:77], v[192:195], v[216:219], v[74:77]
	v_mfma_f32_16x16x32_bf16 v[70:73], v[184:187], v[224:227], v[70:73]
	v_mfma_f32_16x16x32_bf16 v[66:69], v[192:195], v[224:227], v[66:69]
	s_barrier
; #define PG8_STAGE(bufoff, gbase, voff) do { _Pragma("unroll") for (int _i = 0; _i < 2; ++_i) \
;         __builtin_amdgcn_global_load_lds((const unsigned*)((const char*)(gbase) + (voff)[_i]), (LAS unsigned*)(lds + (bufoff) + ldsw + _i * 8192), 16, 0, 0); } while (0)
; #define PG8_LDA(dst, b, h) do { _Pragma("unroll") for (int m = 0; m < 4; ++m) _Pragma("unroll") for (int k = 0; k < 2; ++k) dst[m][k] = *(const LAS bf16x8*)(lds + PG8_SA(b, h) + aoff + m * 2048 + k * 1024); } while (0)
; #define PG8_LDB(dst, b, h) do { _Pragma("unroll") for (int n = 0; n < 2; ++n) _Pragma("unroll") for (int k = 0; k < 2; ++k) dst[n][k] = *(const LAS bf16x8*)(lds + PG8_SB(b, h) + boff + n * 2048 + k * 1024); } while (0)
; #define PG8_BAR __builtin_amdgcn_s_barrier()
; template <class Epi, bool ALIGN_EPI = PG8_ALIGN, bool SP2 = PG8_SP2>
; __device__ __forceinline__ void gemm_phase(LAS uchar* lds, const Gemm g, const StaticOrder& S, const Epi& E) {
;     ...
;         for (int t = tb; t < tb + tblk; t += 2) {
;             const bool last = (t == nt - 2);
;             const char* a1 = cA + (size_t)(t + 1) * kstep;
;             const char* a2 = last ? nA : cA + (size_t)(t + 2) * kstep; const char* b2 = last ? nB : cB + (size_t)(t + 2) * kstep;
;             const char* a3 = a2 + kstep; const char* b3 = b2 + kstep;
;             if constexpr (SP2) {
;             PG8_LDB(B0, 0, 0); PG8_LDB(B1, 0, 1); PG8_SCHED; PG8_LDA(At, 0, 0); PG8_STAGE(PG8_SA(1, 1), a1 + hstepA, voffA);
;             PG8_WAIT_V(8); PG8_WAIT_L(0); PG8_BAR; PG8_MMA(0, 0, At, B0); PG8_MMA(0, 1, At, B1); PG8_BAR; PG8_SCHED;
;             PG8_LDA(At, 0, 1); PG8_STAGE(PG8_SB(0, 0), b2, voffB); PG8_STAGE(PG8_SB(0, 1), b2 + hstepB, voffB); PG8_STAGE(PG8_SA(0, 0), a2, voffA);
;             PG8_WAIT_V(8); PG8_WAIT_L(0); PG8_BAR; PG8_MMA(1, 0, At, B0); PG8_MMA(1, 1, At, B1); PG8_BAR; PG8_SCHED;
;             PG8_LDB(B0, 1, 0); PG8_LDB(B1, 1, 1); PG8_SCHED; PG8_LDA(At, 1, 0); PG8_STAGE(PG8_SA(0, 1), a2 + hstepA, voffA);
;             PG8_WAIT_V(8); PG8_WAIT_L(0); PG8_BAR; PG8_MMA(0, 0, At, B0); PG8_MMA(0, 1, At, B1); PG8_BAR; PG8_SCHED;
;             PG8_LDA(At, 1, 1); PG8_STAGE(PG8_SB(1, 0), b3, voffB); PG8_STAGE(PG8_SB(1, 1), b3 + hstepB, voffB); PG8_STAGE(PG8_SA(1, 0), a3, voffA);
;             PG8_WAIT_V(8); PG8_WAIT_L(0); PG8_BAR; PG8_MMA(1, 0, At, B0); PG8_MMA(1, 1, At, B1); PG8_BAR; PG8_SCHED;
	s_setprio 0
	s_add_i32 s14, s41, s24
	s_mov_b32 m0, s14
	v_lshl_add_u64 v[228:229], v[228:229], 0, s[84:85]
	global_load_lds_dwordx4 v[228:229], off
	s_add_i32 m0, s14, 0x2000
	s_add_u32 s14, s18, 0xb0080
	v_lshl_add_u64 v[228:229], v[230:231], 0, s[84:85]
	s_addc_u32 s15, s19, 0
	s_add_i32 s18, s42, s24
	global_load_lds_dwordx4 v[228:229], off
	s_mov_b32 m0, s18
	v_lshl_add_u64 v[228:229], s[14:15], 0, v[132:133]
	global_load_lds_dwordx4 v[228:229], off
	s_add_i32 m0, s18, 0x2000
	v_lshl_add_u64 v[228:229], s[14:15], 0, v[154:155]
	global_load_lds_dwordx4 v[228:229], off
	s_mov_b32 m0, s29
	v_lshl_add_u64 v[228:229], v[232:233], 0, s[84:85]
	global_load_lds_dwordx4 v[228:229], off
	s_mov_b32 m0, s30
	v_lshl_add_u64 v[228:229], v[234:235], 0, s[84:85]
	global_load_lds_dwordx4 v[228:229], off
	ds_read_b128 v[196:199], v165 offset:49152
	ds_read_b128 v[200:203], v165 offset:50176
	ds_read_b128 v[204:207], v165 offset:51200
	ds_read_b128 v[208:211], v165 offset:52224
	ds_read_b128 v[212:215], v165 offset:53248
	ds_read_b128 v[216:219], v165 offset:54272
	ds_read_b128 v[220:223], v165 offset:55296
	ds_read_b128 v[224:227], v165 offset:56320
	s_setprio 1
	s_waitcnt vmcnt(8) lgkmcnt(0)
	s_barrier
	v_mfma_f32_16x16x32_bf16 v[62:65], v[160:163], v[196:199], v[62:65]
	v_mfma_f32_16x16x32_bf16 v[58:61], v[170:173], v[196:199], v[58:61]
	v_mfma_f32_16x16x32_bf16 v[54:57], v[160:163], v[204:207], v[54:57]
	v_mfma_f32_16x16x32_bf16 v[46:49], v[170:173], v[204:207], v[46:49]
	v_mfma_f32_16x16x32_bf16 v[38:41], v[160:163], v[212:215], v[38:41]
	v_mfma_f32_16x16x32_bf16 v[30:33], v[170:173], v[212:215], v[30:33]
	v_mfma_f32_16x16x32_bf16 v[22:25], v[160:163], v[220:223], v[22:25]
	v_mfma_f32_16x16x32_bf16 v[14:17], v[170:173], v[220:223], v[14:17]
	v_mfma_f32_16x16x32_bf16 v[62:65], v[166:169], v[200:203], v[62:65]
	v_mfma_f32_16x16x32_bf16 v[58:61], v[174:177], v[200:203], v[58:61]
	v_mfma_f32_16x16x32_bf16 v[54:57], v[166:169], v[208:211], v[54:57]
	v_mfma_f32_16x16x32_bf16 v[46:49], v[174:177], v[208:211], v[46:49]
	v_mfma_f32_16x16x32_bf16 v[38:41], v[166:169], v[216:219], v[38:41]
	v_mfma_f32_16x16x32_bf16 v[30:33], v[174:177], v[216:219], v[30:33]
	v_mfma_f32_16x16x32_bf16 v[22:25], v[166:169], v[224:227], v[22:25]
	v_mfma_f32_16x16x32_bf16 v[14:17], v[174:177], v[224:227], v[14:17]
	v_mfma_f32_16x16x32_bf16 v[50:53], v[178:181], v[196:199], v[50:53]
	v_mfma_f32_16x16x32_bf16 v[42:45], v[188:191], v[196:199], v[42:45]
	v_mfma_f32_16x16x32_bf16 v[34:37], v[178:181], v[204:207], v[34:37]
	v_mfma_f32_16x16x32_bf16 v[26:29], v[188:191], v[204:207], v[26:29]
	v_mfma_f32_16x16x32_bf16 v[18:21], v[178:181], v[212:215], v[18:21]
	v_mfma_f32_16x16x32_bf16 v[10:13], v[188:191], v[212:215], v[10:13]
	v_mfma_f32_16x16x32_bf16 v[6:9], v[178:181], v[220:223], v[6:9]
	v_mfma_f32_16x16x32_bf16 v[2:5], v[188:191], v[220:223], v[2:5]
	v_mfma_f32_16x16x32_bf16 v[50:53], v[184:187], v[200:203], v[50:53]
	v_mfma_f32_16x16x32_bf16 v[42:45], v[192:195], v[200:203], v[42:45]
	v_mfma_f32_16x16x32_bf16 v[34:37], v[184:187], v[208:211], v[34:37]
	v_mfma_f32_16x16x32_bf16 v[26:29], v[192:195], v[208:211], v[26:29]
	v_mfma_f32_16x16x32_bf16 v[18:21], v[184:187], v[216:219], v[18:21]
	v_mfma_f32_16x16x32_bf16 v[10:13], v[192:195], v[216:219], v[10:13]
	v_mfma_f32_16x16x32_bf16 v[6:9], v[184:187], v[224:227], v[6:9]
	v_mfma_f32_16x16x32_bf16 v[2:5], v[192:195], v[224:227], v[2:5]
	s_barrier
	s_setprio 0
	s_add_i32 s40, s40, 2
	s_add_u32 s38, s38, 0x100
	s_addc_u32 s39, s39, 0
	s_cmp_gt_u32 s40, 41
	s_mov_b64 s[14:15], s[16:17]
.LBB0_1143:
	s_add_u32 s16, s14, 0x100
	s_addc_u32 s17, s15, 0
	s_add_i32 s41, 0, 0x10000
	s_cmp_eq_u32 s40, 40
	s_cselect_b32 s21, s5, s17
	s_cselect_b32 s20, s4, s16
	v_add_u32_e32 v144, s41, v139
	s_cselect_b32 s19, s13, s39
	s_cselect_b32 s18, s12, s38
	s_add_i32 s42, 0, 0x14000
	ds_read_b128 v[160:163], v144
	ds_read_b128 v[166:169], v144 offset:1024
	ds_read_b128 v[170:173], v144 offset:2048
	ds_read_b128 v[174:177], v144 offset:3072
	v_add_u32_e32 v144, s42, v139
	s_add_i32 m0, s25, 0xc000
	v_lshl_add_u64 v[228:229], s[14:15], 0, v[156:157]
	global_load_lds_dwordx4 v[228:229], off
	s_add_i32 m0, s25, 0xe000
	v_lshl_add_u64 v[228:229], s[14:15], 0, v[158:159]
	global_load_lds_dwordx4 v[228:229], off
	ds_read_b128 v[178:181], v144
	ds_read_b128 v[184:187], v144 offset:1024
	ds_read_b128 v[188:191], v144 offset:2048
	ds_read_b128 v[192:195], v144 offset:3072
	ds_read_b128 v[196:199], v165
	ds_read_b128 v[200:203], v165 offset:1024
	ds_read_b128 v[204:207], v165 offset:2048
	ds_read_b128 v[208:211], v165 offset:3072
	ds_read_b128 v[212:215], v165 offset:4096
	ds_read_b128 v[216:219], v165 offset:5120
	ds_read_b128 v[220:223], v165 offset:6144
	ds_read_b128 v[224:227], v165 offset:7168
	s_setprio 1
	s_waitcnt vmcnt(8) lgkmcnt(0)
	s_barrier
; #define PG8_STAGE(bufoff, gbase, voff) do { _Pragma("unroll") for (int _i = 0; _i < 2; ++_i) \
;         __builtin_amdgcn_global_load_lds((const unsigned*)((const char*)(gbase) + (voff)[_i]), (LAS unsigned*)(lds + (bufoff) + ldsw + _i * 8192), 16, 0, 0); } while (0)
; #define PG8_LDA(dst, b, h) do { _Pragma("unroll") for (int m = 0; m < 4; ++m) _Pragma("unroll") for (int k = 0; k < 2; ++k) dst[m][k] = *(const LAS bf16x8*)(lds + PG8_SA(b, h) + aoff + m * 2048 + k * 1024); } while (0)
; #define PG8_LDB(dst, b, h) do { _Pragma("unroll") for (int n = 0; n < 2; ++n) _Pragma("unroll") for (int k = 0; k < 2; ++k) dst[n][k] = *(const LAS bf16x8*)(lds + PG8_SB(b, h) + boff + n * 2048 + k * 1024); } while (0)
; #define PG8_MMA(ai, bj, At, Bt) do { __builtin_amdgcn_s_setprio(1); _Pragma("unroll") for (int m = 0; m < 4; ++m) _Pragma("unroll") for (int n = 0; n < 2; ++n) _Pragma("unroll") for (int k = 0; k < 2; ++k) \
;         acc[ai][bj][m][n] = __builtin_amdgcn_mfma_f32_16x16x32_bf16(Bt[n][k], At[m][k], acc[ai][bj][m][n], 0, 0, 0); __builtin_amdgcn_s_setprio(0); } while (0)
; #define PG8_WAIT_V(n) asm volatile("s_waitcnt vmcnt(" #n ")" ::: "memory")
; #define PG8_WAIT_L(n) asm volatile("s_waitcnt lgkmcnt(" #n ")" ::: "memory")
; #define PG8_BAR __builtin_amdgcn_s_barrier()
; #define PG8_SCHED __builtin_amdgcn_sched_barrier(0)
; template <class Epi, bool ALIGN_EPI = PG8_ALIGN, bool SP2 = PG8_SP2>
; __device__ __forceinline__ void gemm_phase(LAS uchar* lds, const Gemm g, const StaticOrder& S, const Epi& E) {
;     ...
;             PG8_LDB(B0, 0, 0); PG8_LDB(B1, 0, 1); PG8_SCHED; PG8_LDA(At, 0, 0); PG8_STAGE(PG8_SA(1, 1), a1 + hstepA, voffA);
;             PG8_WAIT_V(8); PG8_WAIT_L(0); PG8_BAR; PG8_MMA(0, 0, At, B0); PG8_MMA(0, 1, At, B1); PG8_BAR; PG8_SCHED;
;             PG8_LDA(At, 0, 1); PG8_STAGE(PG8_SB(0, 0), b2, voffB); PG8_STAGE(PG8_SB(0, 1), b2 + hstepB, voffB); PG8_STAGE(PG8_SA(0, 0), a2, voffA);
;             PG8_WAIT_V(8); PG8_WAIT_L(0); PG8_BAR; PG8_MMA(1, 0, At, B0); PG8_MMA(1, 1, At, B1); PG8_BAR; PG8_SCHED;
	v_mfma_f32_16x16x32_bf16 v[126:129], v[160:163], v[196:199], v[126:129]
	v_mfma_f32_16x16x32_bf16 v[122:125], v[170:173], v[196:199], v[122:125]
	v_mfma_f32_16x16x32_bf16 v[118:121], v[160:163], v[204:207], v[118:121]
	v_mfma_f32_16x16x32_bf16 v[110:113], v[170:173], v[204:207], v[110:113]
	v_mfma_f32_16x16x32_bf16 v[102:105], v[160:163], v[212:215], v[102:105]
	v_mfma_f32_16x16x32_bf16 v[94:97], v[170:173], v[212:215], v[94:97]
	v_mfma_f32_16x16x32_bf16 v[86:89], v[160:163], v[220:223], v[86:89]
	v_mfma_f32_16x16x32_bf16 v[78:81], v[170:173], v[220:223], v[78:81]
	v_mfma_f32_16x16x32_bf16 v[126:129], v[166:169], v[200:203], v[126:129]
	v_mfma_f32_16x16x32_bf16 v[122:125], v[174:177], v[200:203], v[122:125]
	v_mfma_f32_16x16x32_bf16 v[118:121], v[166:169], v[208:211], v[118:121]
	v_mfma_f32_16x16x32_bf16 v[110:113], v[174:177], v[208:211], v[110:113]
	v_mfma_f32_16x16x32_bf16 v[102:105], v[166:169], v[216:219], v[102:105]
	v_mfma_f32_16x16x32_bf16 v[94:97], v[174:177], v[216:219], v[94:97]
	v_mfma_f32_16x16x32_bf16 v[86:89], v[166:169], v[224:227], v[86:89]
	v_mfma_f32_16x16x32_bf16 v[78:81], v[174:177], v[224:227], v[78:81]
	v_mfma_f32_16x16x32_bf16 v[114:117], v[178:181], v[196:199], v[114:117]
	v_mfma_f32_16x16x32_bf16 v[106:109], v[188:191], v[196:199], v[106:109]
	v_mfma_f32_16x16x32_bf16 v[98:101], v[178:181], v[204:207], v[98:101]
	v_mfma_f32_16x16x32_bf16 v[90:93], v[188:191], v[204:207], v[90:93]
	v_mfma_f32_16x16x32_bf16 v[82:85], v[178:181], v[212:215], v[82:85]
	v_mfma_f32_16x16x32_bf16 v[74:77], v[188:191], v[212:215], v[74:77]
	v_mfma_f32_16x16x32_bf16 v[70:73], v[178:181], v[220:223], v[70:73]
	v_mfma_f32_16x16x32_bf16 v[66:69], v[188:191], v[220:223], v[66:69]
	v_mfma_f32_16x16x32_bf16 v[114:117], v[184:187], v[200:203], v[114:117]
	v_mfma_f32_16x16x32_bf16 v[106:109], v[192:195], v[200:203], v[106:109]
	v_mfma_f32_16x16x32_bf16 v[98:101], v[184:187], v[208:211], v[98:101]
	v_mfma_f32_16x16x32_bf16 v[90:93], v[192:195], v[208:211], v[90:93]
	v_mfma_f32_16x16x32_bf16 v[82:85], v[184:187], v[216:219], v[82:85]
	v_mfma_f32_16x16x32_bf16 v[74:77], v[192:195], v[216:219], v[74:77]
	v_mfma_f32_16x16x32_bf16 v[70:73], v[184:187], v[224:227], v[70:73]
	v_mfma_f32_16x16x32_bf16 v[66:69], v[192:195], v[224:227], v[66:69]
	s_barrier
	s_setprio 0
	s_add_i32 s14, s41, s24
	s_mov_b32 m0, s14
	v_lshl_add_u64 v[228:229], s[18:19], 0, v[132:133]
	global_load_lds_dwordx4 v[228:229], off
	s_add_i32 m0, s14, 0x2000
	s_add_u32 s14, s18, 0xb0000
	v_lshl_add_u64 v[230:231], s[18:19], 0, v[154:155]
	s_addc_u32 s15, s19, 0
	s_add_i32 s41, s42, s24
	global_load_lds_dwordx4 v[230:231], off
	s_mov_b32 m0, s41
	v_lshl_add_u64 v[232:233], s[14:15], 0, v[132:133]
	global_load_lds_dwordx4 v[232:233], off
	s_add_i32 m0, s41, 0x2000
	v_lshl_add_u64 v[232:233], s[14:15], 0, v[154:155]
	global_load_lds_dwordx4 v[232:233], off
	s_mov_b32 m0, s25
	v_lshl_add_u64 v[232:233], s[20:21], 0, v[130:131]
	global_load_lds_dwordx4 v[232:233], off
	s_mov_b32 m0, s26
	v_lshl_add_u64 v[234:235], s[20:21], 0, v[134:135]
	global_load_lds_dwordx4 v[234:235], off
	ds_read_b128 v[196:199], v165 offset:16384
	ds_read_b128 v[200:203], v165 offset:17408
	ds_read_b128 v[204:207], v165 offset:18432
	ds_read_b128 v[208:211], v165 offset:19456
	ds_read_b128 v[212:215], v165 offset:20480
	ds_read_b128 v[216:219], v165 offset:21504
	ds_read_b128 v[220:223], v165 offset:22528
	ds_read_b128 v[224:227], v165 offset:23552
	s_setprio 1
	s_waitcnt vmcnt(8) lgkmcnt(0)
	s_barrier
	v_mfma_f32_16x16x32_bf16 v[62:65], v[160:163], v[196:199], v[62:65]
	v_mfma_f32_16x16x32_bf16 v[58:61], v[170:173], v[196:199], v[58:61]
	v_mfma_f32_16x16x32_bf16 v[54:57], v[160:163], v[204:207], v[54:57]
	v_mfma_f32_16x16x32_bf16 v[46:49], v[170:173], v[204:207], v[46:49]
	v_mfma_f32_16x16x32_bf16 v[38:41], v[160:163], v[212:215], v[38:41]
	v_mfma_f32_16x16x32_bf16 v[30:33], v[170:173], v[212:215], v[30:33]
	v_mfma_f32_16x16x32_bf16 v[22:25], v[160:163], v[220:223], v[22:25]
	v_mfma_f32_16x16x32_bf16 v[14:17], v[170:173], v[220:223], v[14:17]
	v_mfma_f32_16x16x32_bf16 v[62:65], v[166:169], v[200:203], v[62:65]
	v_mfma_f32_16x16x32_bf16 v[58:61], v[174:177], v[200:203], v[58:61]
	v_mfma_f32_16x16x32_bf16 v[54:57], v[166:169], v[208:211], v[54:57]
	v_mfma_f32_16x16x32_bf16 v[46:49], v[174:177], v[208:211], v[46:49]
	v_mfma_f32_16x16x32_bf16 v[38:41], v[166:169], v[216:219], v[38:41]
	v_mfma_f32_16x16x32_bf16 v[30:33], v[174:177], v[216:219], v[30:33]
	v_mfma_f32_16x16x32_bf16 v[22:25], v[166:169], v[224:227], v[22:25]
	v_mfma_f32_16x16x32_bf16 v[14:17], v[174:177], v[224:227], v[14:17]
	v_mfma_f32_16x16x32_bf16 v[50:53], v[178:181], v[196:199], v[50:53]
	v_mfma_f32_16x16x32_bf16 v[42:45], v[188:191], v[196:199], v[42:45]
	v_mfma_f32_16x16x32_bf16 v[34:37], v[178:181], v[204:207], v[34:37]
	v_mfma_f32_16x16x32_bf16 v[26:29], v[188:191], v[204:207], v[26:29]
	v_mfma_f32_16x16x32_bf16 v[18:21], v[178:181], v[212:215], v[18:21]
	v_mfma_f32_16x16x32_bf16 v[10:13], v[188:191], v[212:215], v[10:13]
	v_mfma_f32_16x16x32_bf16 v[6:9], v[178:181], v[220:223], v[6:9]
	v_mfma_f32_16x16x32_bf16 v[2:5], v[188:191], v[220:223], v[2:5]
	v_mfma_f32_16x16x32_bf16 v[50:53], v[184:187], v[200:203], v[50:53]
	v_mfma_f32_16x16x32_bf16 v[42:45], v[192:195], v[200:203], v[42:45]
	v_mfma_f32_16x16x32_bf16 v[34:37], v[184:187], v[208:211], v[34:37]
	v_mfma_f32_16x16x32_bf16 v[26:29], v[192:195], v[208:211], v[26:29]
	v_mfma_f32_16x16x32_bf16 v[18:21], v[184:187], v[216:219], v[18:21]
	v_mfma_f32_16x16x32_bf16 v[10:13], v[192:195], v[216:219], v[10:13]
	v_mfma_f32_16x16x32_bf16 v[6:9], v[184:187], v[224:227], v[6:9]
	v_mfma_f32_16x16x32_bf16 v[2:5], v[192:195], v[224:227], v[2:5]
	s_barrier
; #define PG8_STAGE(bufoff, gbase, voff) do { _Pragma("unroll") for (int _i = 0; _i < 2; ++_i) \
;         __builtin_amdgcn_global_load_lds((const unsigned*)((const char*)(gbase) + (voff)[_i]), (LAS unsigned*)(lds + (bufoff) + ldsw + _i * 8192), 16, 0, 0); } while (0)
; #define PG8_LDA(dst, b, h) do { _Pragma("unroll") for (int m = 0; m < 4; ++m) _Pragma("unroll") for (int k = 0; k < 2; ++k) dst[m][k] = *(const LAS bf16x8*)(lds + PG8_SA(b, h) + aoff + m * 2048 + k * 1024); } while (0)
; #define PG8_LDB(dst, b, h) do { _Pragma("unroll") for (int n = 0; n < 2; ++n) _Pragma("unroll") for (int k = 0; k < 2; ++k) dst[n][k] = *(const LAS bf16x8*)(lds + PG8_SB(b, h) + boff + n * 2048 + k * 1024); } while (0)
; #define PG8_MMA(ai, bj, At, Bt) do { __builtin_amdgcn_s_setprio(1); _Pragma("unroll") for (int m = 0; m < 4; ++m) _Pragma("unroll") for (int n = 0; n < 2; ++n) _Pragma("unroll") for (int k = 0; k < 2; ++k) \
;         acc[ai][bj][m][n] = __builtin_amdgcn_mfma_f32_16x16x32_bf16(Bt[n][k], At[m][k], acc[ai][bj][m][n], 0, 0, 0); __builtin_amdgcn_s_setprio(0); } while (0)
; #define PG8_WAIT_V(n) asm volatile("s_waitcnt vmcnt(" #n ")" ::: "memory")
; #define PG8_WAIT_L(n) asm volatile("s_waitcnt lgkmcnt(" #n ")" ::: "memory")
; #define PG8_BAR __builtin_amdgcn_s_barrier()
; #define PG8_SCHED __builtin_amdgcn_sched_barrier(0)
; template <class Epi, bool ALIGN_EPI = PG8_ALIGN, bool SP2 = PG8_SP2>
; __device__ __forceinline__ void gemm_phase(LAS uchar* lds, const Gemm g, const StaticOrder& S, const Epi& E) {
;     ...
;             PG8_LDB(B0, 1, 0); PG8_LDB(B1, 1, 1); PG8_SCHED; PG8_LDA(At, 1, 0); PG8_STAGE(PG8_SA(0, 1), a2 + hstepA, voffA);
;             PG8_WAIT_V(8); PG8_WAIT_L(0); PG8_BAR; PG8_MMA(0, 0, At, B0); PG8_MMA(0, 1, At, B1); PG8_BAR; PG8_SCHED;
	s_setprio 0
	s_add_i32 s41, 0, 0x18000
	v_add_u32_e32 v144, s41, v139
	s_add_i32 s42, 0, 0x1c000
	ds_read_b128 v[160:163], v144
	ds_read_b128 v[166:169], v144 offset:1024
	ds_read_b128 v[170:173], v144 offset:2048
	ds_read_b128 v[174:177], v144 offset:3072
	v_add_u32_e32 v144, s42, v139
	s_add_u32 s14, s20, 0xb0000
	s_addc_u32 s15, s21, 0
	s_mov_b32 m0, s27
	v_lshl_add_u64 v[236:237], s[14:15], 0, v[130:131]
	global_load_lds_dwordx4 v[236:237], off
	s_mov_b32 m0, s28
	v_lshl_add_u64 v[236:237], s[14:15], 0, v[134:135]
	global_load_lds_dwordx4 v[236:237], off
	ds_read_b128 v[178:181], v144
	ds_read_b128 v[184:187], v144 offset:1024
	ds_read_b128 v[188:191], v144 offset:2048
	ds_read_b128 v[192:195], v144 offset:3072
	ds_read_b128 v[196:199], v165 offset:32768
	ds_read_b128 v[200:203], v165 offset:33792
	ds_read_b128 v[204:207], v165 offset:34816
	ds_read_b128 v[208:211], v165 offset:35840
	ds_read_b128 v[212:215], v165 offset:36864
	ds_read_b128 v[216:219], v165 offset:37888
	ds_read_b128 v[220:223], v165 offset:38912
	ds_read_b128 v[224:227], v165 offset:39936
	s_setprio 1
	s_waitcnt vmcnt(8) lgkmcnt(0)
	s_barrier
	v_mfma_f32_16x16x32_bf16 v[126:129], v[160:163], v[196:199], v[126:129]
	v_mfma_f32_16x16x32_bf16 v[122:125], v[170:173], v[196:199], v[122:125]
	v_mfma_f32_16x16x32_bf16 v[118:121], v[160:163], v[204:207], v[118:121]
	v_mfma_f32_16x16x32_bf16 v[110:113], v[170:173], v[204:207], v[110:113]
	v_mfma_f32_16x16x32_bf16 v[102:105], v[160:163], v[212:215], v[102:105]
	v_mfma_f32_16x16x32_bf16 v[94:97], v[170:173], v[212:215], v[94:97]
	v_mfma_f32_16x16x32_bf16 v[86:89], v[160:163], v[220:223], v[86:89]
	v_mfma_f32_16x16x32_bf16 v[78:81], v[170:173], v[220:223], v[78:81]
	v_mfma_f32_16x16x32_bf16 v[126:129], v[166:169], v[200:203], v[126:129]
	v_mfma_f32_16x16x32_bf16 v[122:125], v[174:177], v[200:203], v[122:125]
	v_mfma_f32_16x16x32_bf16 v[118:121], v[166:169], v[208:211], v[118:121]
	v_mfma_f32_16x16x32_bf16 v[110:113], v[174:177], v[208:211], v[110:113]
	v_mfma_f32_16x16x32_bf16 v[102:105], v[166:169], v[216:219], v[102:105]
	v_mfma_f32_16x16x32_bf16 v[94:97], v[174:177], v[216:219], v[94:97]
	v_mfma_f32_16x16x32_bf16 v[86:89], v[166:169], v[224:227], v[86:89]
	v_mfma_f32_16x16x32_bf16 v[78:81], v[174:177], v[224:227], v[78:81]
	v_mfma_f32_16x16x32_bf16 v[114:117], v[178:181], v[196:199], v[114:117]
	v_mfma_f32_16x16x32_bf16 v[106:109], v[188:191], v[196:199], v[106:109]
	v_mfma_f32_16x16x32_bf16 v[98:101], v[178:181], v[204:207], v[98:101]
	v_mfma_f32_16x16x32_bf16 v[90:93], v[188:191], v[204:207], v[90:93]
	v_mfma_f32_16x16x32_bf16 v[82:85], v[178:181], v[212:215], v[82:85]
	v_mfma_f32_16x16x32_bf16 v[74:77], v[188:191], v[212:215], v[74:77]
	v_mfma_f32_16x16x32_bf16 v[70:73], v[178:181], v[220:223], v[70:73]
	v_mfma_f32_16x16x32_bf16 v[66:69], v[188:191], v[220:223], v[66:69]
	v_mfma_f32_16x16x32_bf16 v[114:117], v[184:187], v[200:203], v[114:117]
	v_mfma_f32_16x16x32_bf16 v[106:109], v[192:195], v[200:203], v[106:109]
	v_mfma_f32_16x16x32_bf16 v[98:101], v[184:187], v[208:211], v[98:101]
	v_mfma_f32_16x16x32_bf16 v[90:93], v[192:195], v[208:211], v[90:93]
	v_mfma_f32_16x16x32_bf16 v[82:85], v[184:187], v[216:219], v[82:85]
	v_mfma_f32_16x16x32_bf16 v[74:77], v[192:195], v[216:219], v[74:77]
	v_mfma_f32_16x16x32_bf16 v[70:73], v[184:187], v[224:227], v[70:73]
	v_mfma_f32_16x16x32_bf16 v[66:69], v[192:195], v[224:227], v[66:69]
	s_barrier
; #define PG8_STAGE(bufoff, gbase, voff) do { _Pragma("unroll") for (int _i = 0; _i < 2; ++_i) \
;         __builtin_amdgcn_global_load_lds((const unsigned*)((const char*)(gbase) + (voff)[_i]), (LAS unsigned*)(lds + (bufoff) + ldsw + _i * 8192), 16, 0, 0); } while (0)
; #define PG8_LDA(dst, b, h) do { _Pragma("unroll") for (int m = 0; m < 4; ++m) _Pragma("unroll") for (int k = 0; k < 2; ++k) dst[m][k] = *(const LAS bf16x8*)(lds + PG8_SA(b, h) + aoff + m * 2048 + k * 1024); } while (0)
; #define PG8_MMA(ai, bj, At, Bt) do { __builtin_amdgcn_s_setprio(1); _Pragma("unroll") for (int m = 0; m < 4; ++m) _Pragma("unroll") for (int n = 0; n < 2; ++n) _Pragma("unroll") for (int k = 0; k < 2; ++k) \
;         acc[ai][bj][m][n] = __builtin_amdgcn_mfma_f32_16x16x32_bf16(Bt[n][k], At[m][k], acc[ai][bj][m][n], 0, 0, 0); __builtin_amdgcn_s_setprio(0); } while (0)
; #define PG8_WAIT_V(n) asm volatile("s_waitcnt vmcnt(" #n ")" ::: "memory")
; #define PG8_WAIT_L(n) asm volatile("s_waitcnt lgkmcnt(" #n ")" ::: "memory")
; #define PG8_BAR __builtin_amdgcn_s_barrier()
; #define PG8_SCHED __builtin_amdgcn_sched_barrier(0)
; template <class Epi, bool ALIGN_EPI = PG8_ALIGN, bool SP2 = PG8_SP2>
; __device__ __forceinline__ void gemm_phase(LAS uchar* lds, const Gemm g, const StaticOrder& S, const Epi& E) {
;     ...
;             PG8_LDA(At, 1, 1); PG8_STAGE(PG8_SB(1, 0), b3, voffB); PG8_STAGE(PG8_SB(1, 1), b3 + hstepB, voffB); PG8_STAGE(PG8_SA(1, 0), a3, voffA);
;             PG8_WAIT_V(8); PG8_WAIT_L(0); PG8_BAR; PG8_MMA(1, 0, At, B0); PG8_MMA(1, 1, At, B1); PG8_BAR; PG8_SCHED;
;     ...
;         if constexpr (ALIGN_EPI) { if (wr == 0) PG8_BAR; }
	s_setprio 0
	s_add_i32 s14, s41, s24
	s_mov_b32 m0, s14
	v_lshl_add_u64 v[228:229], v[228:229], 0, s[84:85]
	global_load_lds_dwordx4 v[228:229], off
	s_add_i32 m0, s14, 0x2000
	s_add_u32 s14, s18, 0xb0080
	v_lshl_add_u64 v[228:229], v[230:231], 0, s[84:85]
	s_addc_u32 s15, s19, 0
	s_add_i32 s18, s42, s24
	global_load_lds_dwordx4 v[228:229], off
	s_mov_b32 m0, s18
	v_lshl_add_u64 v[228:229], s[14:15], 0, v[132:133]
	global_load_lds_dwordx4 v[228:229], off
	s_add_i32 m0, s18, 0x2000
	v_lshl_add_u64 v[228:229], s[14:15], 0, v[154:155]
	global_load_lds_dwordx4 v[228:229], off
	s_mov_b32 m0, s29
	v_lshl_add_u64 v[228:229], v[232:233], 0, s[84:85]
	global_load_lds_dwordx4 v[228:229], off
	s_mov_b32 m0, s30
	v_lshl_add_u64 v[228:229], v[234:235], 0, s[84:85]
	global_load_lds_dwordx4 v[228:229], off
	ds_read_b128 v[196:199], v165 offset:49152
	ds_read_b128 v[200:203], v165 offset:50176
	ds_read_b128 v[204:207], v165 offset:51200
	ds_read_b128 v[208:211], v165 offset:52224
	ds_read_b128 v[212:215], v165 offset:53248
	ds_read_b128 v[216:219], v165 offset:54272
	ds_read_b128 v[220:223], v165 offset:55296
	ds_read_b128 v[224:227], v165 offset:56320
	s_setprio 1
	s_waitcnt vmcnt(8) lgkmcnt(0)
	s_barrier
	v_mfma_f32_16x16x32_bf16 v[62:65], v[160:163], v[196:199], v[62:65]
	v_mfma_f32_16x16x32_bf16 v[58:61], v[170:173], v[196:199], v[58:61]
	v_mfma_f32_16x16x32_bf16 v[54:57], v[160:163], v[204:207], v[54:57]
	v_mfma_f32_16x16x32_bf16 v[46:49], v[170:173], v[204:207], v[46:49]
	v_mfma_f32_16x16x32_bf16 v[38:41], v[160:163], v[212:215], v[38:41]
	v_mfma_f32_16x16x32_bf16 v[30:33], v[170:173], v[212:215], v[30:33]
	v_mfma_f32_16x16x32_bf16 v[22:25], v[160:163], v[220:223], v[22:25]
	v_mfma_f32_16x16x32_bf16 v[14:17], v[170:173], v[220:223], v[14:17]
	v_mfma_f32_16x16x32_bf16 v[62:65], v[166:169], v[200:203], v[62:65]
	v_mfma_f32_16x16x32_bf16 v[58:61], v[174:177], v[200:203], v[58:61]
	v_mfma_f32_16x16x32_bf16 v[54:57], v[166:169], v[208:211], v[54:57]
	v_mfma_f32_16x16x32_bf16 v[46:49], v[174:177], v[208:211], v[46:49]
	v_mfma_f32_16x16x32_bf16 v[38:41], v[166:169], v[216:219], v[38:41]
	v_mfma_f32_16x16x32_bf16 v[30:33], v[174:177], v[216:219], v[30:33]
	v_mfma_f32_16x16x32_bf16 v[22:25], v[166:169], v[224:227], v[22:25]
	v_mfma_f32_16x16x32_bf16 v[14:17], v[174:177], v[224:227], v[14:17]
	v_mfma_f32_16x16x32_bf16 v[50:53], v[178:181], v[196:199], v[50:53]
	v_mfma_f32_16x16x32_bf16 v[42:45], v[188:191], v[196:199], v[42:45]
	v_mfma_f32_16x16x32_bf16 v[34:37], v[178:181], v[204:207], v[34:37]
	v_mfma_f32_16x16x32_bf16 v[26:29], v[188:191], v[204:207], v[26:29]
	v_mfma_f32_16x16x32_bf16 v[18:21], v[178:181], v[212:215], v[18:21]
	v_mfma_f32_16x16x32_bf16 v[10:13], v[188:191], v[212:215], v[10:13]
	v_mfma_f32_16x16x32_bf16 v[6:9], v[178:181], v[220:223], v[6:9]
	v_mfma_f32_16x16x32_bf16 v[2:5], v[188:191], v[220:223], v[2:5]
	v_mfma_f32_16x16x32_bf16 v[50:53], v[184:187], v[200:203], v[50:53]
	v_mfma_f32_16x16x32_bf16 v[42:45], v[192:195], v[200:203], v[42:45]
	v_mfma_f32_16x16x32_bf16 v[34:37], v[184:187], v[208:211], v[34:37]
	v_mfma_f32_16x16x32_bf16 v[26:29], v[192:195], v[208:211], v[26:29]
	v_mfma_f32_16x16x32_bf16 v[18:21], v[184:187], v[216:219], v[18:21]
	v_mfma_f32_16x16x32_bf16 v[10:13], v[192:195], v[216:219], v[10:13]
	v_mfma_f32_16x16x32_bf16 v[6:9], v[184:187], v[224:227], v[6:9]
	v_mfma_f32_16x16x32_bf16 v[2:5], v[192:195], v[224:227], v[2:5]
	s_barrier
	s_setprio 0
	s_add_i32 s40, s40, 2
	s_add_u32 s38, s38, 0x100
	s_addc_u32 s39, s39, 0
	s_cmp_gt_u32 s40, 41
	s_mov_b64 s[14:15], s[16:17]
	s_cbranch_scc0 .LBB0_1143
	s_and_b64 vcc, exec, s[10:11]
	s_cbranch_vccz .LBB0_1146
	s_barrier
